# strategy 4: one static s_setprio 1 for waves 4-7 before each GEMM phase's unit loop, per-burst flips deleted, reset at phase exit
# speedup vs baseline: 1.0077x; 1.0077x over previous
.LBB0_120:
	s_mov_b32 s100, -1
	v_readlane_b32 s30, v254, 52
	v_readlane_b32 s40, v252, 4
	s_mul_i32 s25, s30, 0x8400
	v_readlane_b32 s44, v252, 8
	s_mul_hi_i32 s1, s30, 0x8400
	v_readlane_b32 s45, v252, 9
	s_add_u32 s68, s44, s25
	v_readlane_b32 s46, v252, 10
	s_addc_u32 s69, s45, s1
	s_mul_i32 s25, s30, 0x2c00
	v_readlane_b32 s47, v252, 11
	s_mul_hi_i32 s1, s30, 0x2c00
	s_add_u32 s70, s46, s25
	s_addc_u32 s71, s47, s1
	s_mul_i32 s25, s38, 0x1c00000
	v_readlane_b32 s20, v252, 32
	s_mul_hi_i32 s1, s38, 0x1c00000
	s_add_u32 s27, s20, s25
	v_readlane_b32 s20, v252, 33
	v_readlane_b32 s31, v254, 53
	s_addc_u32 s30, s20, s1
	s_mul_i32 s33, s38, 0xfea00000
	s_mul_hi_i32 s31, s38, 0xfea00000
	s_add_u32 s94, s27, s33
	s_addc_u32 s95, s30, s31
	s_add_u32 s25, s54, s25
	s_addc_u32 s1, s55, s1
	s_mul_i32 s30, s38, 0xffea0000
	s_mul_hi_i32 s27, s38, 0xffea0000
	s_add_u32 s25, s25, s30
	s_addc_u32 s1, s1, s27
	s_add_u32 s52, s25, 0x5600000
	s_addc_u32 s53, s1, 0
	s_add_u32 s50, s25, 0x5780000
	s_addc_u32 s51, s1, 0
	v_lshrrev_b32_e32 v15, 1, v14
	s_add_u32 s92, s25, 0x5900000
	v_and_b32_e32 v15, 24, v15
	s_addc_u32 s93, s1, 0
	v_and_b32_e32 v216, 15, v14
	s_lshl_b32 s1, s10, 6
	v_lshlrev_b32_e32 v16, 1, v15
	v_lshlrev_b32_e32 v14, 2, v14
	v_writelane_b32 v254, s1, 61
	v_lshl_or_b32 v16, v216, 6, v16
	s_lshl_b32 s1, s10, 13
	v_and_b32_e32 v14, 32, v14
	v_bitop3_b32 v17, v16, s1, v14 bitop3:0xde
	s_lshl_b32 s1, s11, 5
	s_and_b32 s1, s1, 0x60
	s_add_i32 m0, s75, 0x18000
	v_lshl_add_u64 v[6:7], v[6:7], 0, s[18:19]
	s_lshl_b32 s10, s1, 7
	s_waitcnt vmcnt(4)
	s_barrier
	global_load_lds_dwordx4 v[6:7], off
	v_lshl_add_u64 v[4:5], v[4:5], 0, s[18:19]
	s_add_i32 m0, s75, 0x1a000
	s_add_i32 s31, s75, 0x8000
	s_add_i32 s34, s75, 0xa000
	v_bitop3_b32 v217, v16, s10, v14 bitop3:0xde
	global_load_lds_dwordx4 v[4:5], off
	v_lshl_add_u64 v[2:3], v[2:3], 0, s[18:19]
	s_mov_b32 m0, s31
	s_add_u32 s10, s82, 0x40080
	global_load_lds_dwordx4 v[2:3], off
	v_lshl_add_u64 v[0:1], v[0:1], 0, s[18:19]
	s_mov_b32 m0, s34
	s_addc_u32 s11, s83, 0
	global_load_lds_dwordx4 v[0:1], off
	s_add_i32 m0, s75, 0x1c000
	v_lshl_add_u64 v[0:1], s[10:11], 0, v[144:145]
	global_load_lds_dwordx4 v[0:1], off
	v_lshl_add_u64 v[0:1], s[10:11], 0, v[162:163]
	s_add_i32 m0, s75, 0x1e000
	s_ashr_i32 s30, s8, 31
	global_load_lds_dwordx4 v[0:1], off
	v_lshlrev_b32_e32 v0, 14, v8
	v_and_b32_e32 v0, 0xffff8000, v0
	v_lshl_add_u32 v0, v9, 11, v0
	v_and_b32_e32 v1, 1, v8
	v_lshl_or_b32 v0, v1, 6, v0
	v_lshl_add_u32 v164, v10, 1, v0
	v_lshlrev_b32_e32 v0, 14, v11
	s_add_u32 s60, s68, 0x2c00
	v_and_b32_e32 v0, 0xffff8000, v0
	s_waitcnt vmcnt(6)
	s_addc_u32 s61, s69, 0
	v_lshl_add_u32 v0, v12, 11, v0
	v_and_b32_e32 v1, 1, v11
	v_readlane_b32 s41, v252, 5
	v_readlane_b32 s42, v252, 6
	v_readlane_b32 s43, v252, 7
	s_add_u32 s64, s68, 0x5800
	v_lshl_or_b32 v0, v1, 6, v0
	v_readlane_b32 s48, v252, 38
	s_mov_b32 s35, 0
	v_cmp_eq_u32_e64 s[38:39], 0, v216
	v_cmp_lt_u32_e64 s[40:41], 1, v216
	v_cmp_gt_u32_e64 s[42:43], 2, v216
	v_cmp_lt_u32_e64 s[44:45], 13, v216
	v_add_u32_e32 v218, -14, v216
	s_addc_u32 s65, s69, 0
	v_or_b32_e32 v219, s1, v15
	v_mov_b32_e32 v165, v145
	v_lshl_add_u32 v166, v13, 1, v0
	v_mov_b32_e32 v167, v145
	v_add_u32_e32 v220, 0, v17
	v_readlane_b32 s49, v252, 39
	s_barrier
	v_readfirstlane_b32 s101, v208
	s_nop 3
	s_lshr_b32 s101, s101, 8
	s_cmp_eq_u32 s101, 0
	s_cbranch_scc1 .Lprio_d_done
	s_setprio 1
.Lprio_d_done:
	s_branch .LBB0_122
.LBB0_122:
	s_add_i32 s35, s35, 1
	v_readlane_b32 s1, v252, 40
	s_mul_i32 s1, s35, s1
	s_mul_hi_u32 s10, s35, s4
	s_add_i32 s10, s10, s1
	s_mul_i32 s1, s35, s4
	s_add_u32 s72, s1, s8
	s_addc_u32 s73, s10, s30
	v_mov_b64_e32 v[0:1], 0xaff
	v_cmp_gt_i64_e64 s[46:47], s[72:73], v[0:1]
	s_and_b64 vcc, exec, s[46:47]
	s_cbranch_vccnz .LBB0_124
	s_ashr_i32 s1, s72, 31
	s_lshr_b32 s1, s1, 29
	s_add_i32 s1, s72, s1
	s_ashr_i32 s10, s1, 3
	s_and_b32 s1, s1, -8
	s_sub_i32 s1, s72, s1
	s_cmp_lt_i32 s1, 0
	s_movk_i32 s11, 0x161
	s_cselect_b32 s11, s11, 0x160
	s_mul_i32 s1, s11, s1
	s_add_i32 s1, s1, s10
	s_mul_hi_i32 s10, s1, 0x2e8ba2e9
	s_lshr_b32 s11, s10, 31
	s_ashr_i32 s10, s10, 5
	s_add_i32 s10, s10, s11
	s_lshl_b32 s11, s10, 3
	s_mulk_i32 s10, 0xb0
	s_sub_i32 s1, s1, s10
	s_lshr_b32 s76, s1, 3
	s_and_b32 s1, s1, 7
	s_add_i32 s78, s1, s11
.LBB0_124:
	s_ashr_i32 s79, s78, 31
	s_lshl_b64 s[10:11], s[78:79], 19
	s_add_u32 s80, s54, s10
	v_cmp_lt_i64_e32 vcc, s[72:73], v[178:179]
	s_addc_u32 s81, s55, s11
	s_and_b64 s[10:11], vcc, exec
	s_cselect_b32 s1, s81, s87
	s_cselect_b32 s10, s80, s86
	s_ashr_i32 s77, s76, 31
	s_lshl_b64 s[36:37], s[76:77], 19
	s_add_u32 s72, s66, s36
	s_addc_u32 s73, s59, s37
	s_and_b64 s[36:37], vcc, exec
	s_cselect_b32 s11, s73, s83
	s_cselect_b32 s25, s72, s82
	s_add_u32 s86, s86, 0x40080
	s_addc_u32 s87, s87, 0
	s_add_u32 s33, s82, 0x100
	s_addc_u32 s36, s83, 0
	s_mov_b32 s37, -2
	s_add_u32 s27, s86, 0xfffc0080
	s_addc_u32 s56, s87, -1
	s_add_i32 s57, 0, 0x10000
	v_add_u32_e32 v76, s57, v217
	ds_read_b128 v[64:67], v76
	ds_read_b128 v[68:71], v76 offset:1024
	ds_read_b128 v[72:75], v76 offset:2048
	ds_read_b128 v[76:79], v76 offset:3072
	s_cmp_eq_u32 s37, 12
	s_cselect_b32 vcc_hi, s1, s56
	s_cselect_b32 vcc_lo, s10, s27
	s_cselect_b32 s83, s11, s36
	s_cselect_b32 s82, s25, s33
	v_lshl_add_u64 v[168:169], s[86:87], 0, v[164:165]
	s_add_i32 m0, s75, 0xc000
	ds_read_b128 v[80:83], v220
	ds_read_b128 v[84:87], v220 offset:1024
	ds_read_b128 v[88:91], v220 offset:2048
	ds_read_b128 v[92:95], v220 offset:3072
	ds_read_b128 v[188:191], v220 offset:4096
	ds_read_b128 v[192:195], v220 offset:5120
	ds_read_b128 v[196:199], v220 offset:6144
	ds_read_b128 v[200:203], v220 offset:7168
	global_load_lds_dwordx4 v[168:169], off
	v_lshl_add_u64 v[168:169], s[86:87], 0, v[166:167]
	s_add_i32 m0, s75, 0xe000
	s_nop 0
	global_load_lds_dwordx4 v[168:169], off
	s_waitcnt lgkmcnt(8)
	s_barrier
	s_waitcnt lgkmcnt(0)
	v_mfma_f32_16x16x32_bf16 v[146:149], v[64:67], v[80:83], 0
	v_mfma_f32_16x16x32_bf16 v[116:119], v[72:75], v[80:83], 0
	v_mfma_f32_16x16x32_bf16 v[158:161], v[64:67], v[88:91], 0
	v_mfma_f32_16x16x32_bf16 v[124:127], v[72:75], v[88:91], 0
	v_mfma_f32_16x16x32_bf16 v[154:157], v[64:67], v[188:191], 0
	v_mfma_f32_16x16x32_bf16 v[112:115], v[72:75], v[188:191], 0
	v_mfma_f32_16x16x32_bf16 v[150:153], v[64:67], v[196:199], 0
	v_mfma_f32_16x16x32_bf16 v[120:123], v[72:75], v[196:199], 0
	v_mfma_f32_16x16x32_bf16 v[146:149], v[68:71], v[84:87], v[146:149]
	v_mfma_f32_16x16x32_bf16 v[116:119], v[76:79], v[84:87], v[116:119]
	v_mfma_f32_16x16x32_bf16 v[158:161], v[68:71], v[92:95], v[158:161]
	v_mfma_f32_16x16x32_bf16 v[124:127], v[76:79], v[92:95], v[124:127]
	v_mfma_f32_16x16x32_bf16 v[154:157], v[68:71], v[192:195], v[154:157]
	v_mfma_f32_16x16x32_bf16 v[112:115], v[76:79], v[192:195], v[112:115]
	v_mfma_f32_16x16x32_bf16 v[150:153], v[68:71], v[200:203], v[150:153]
	v_mfma_f32_16x16x32_bf16 v[120:123], v[76:79], v[200:203], v[120:123]
	s_barrier
	s_add_i32 s27, 0, 0x14000
	v_add_u32_e32 v168, s27, v217
	s_add_i32 s56, s57, s74
	ds_read_b128 v[204:207], v168
	ds_read_b128 v[222:225], v168 offset:1024
	ds_read_b128 v[228:231], v168 offset:2048
	ds_read_b128 v[232:235], v168 offset:3072
	v_lshl_add_u64 v[168:169], s[82:83], 0, v[144:145]
	s_mov_b32 m0, s56
	v_lshl_add_u64 v[176:177], s[82:83], 0, v[162:163]
	global_load_lds_dwordx4 v[168:169], off
	s_add_i32 m0, s56, 0x2000
	s_nop 0
	global_load_lds_dwordx4 v[176:177], off
	s_barrier
	s_waitcnt lgkmcnt(0)
	v_mfma_f32_16x16x32_bf16 v[140:143], v[204:207], v[80:83], 0
	v_mfma_f32_16x16x32_bf16 v[80:83], v[228:231], v[80:83], 0
	v_mfma_f32_16x16x32_bf16 v[140:143], v[222:225], v[84:87], v[140:143]
	v_mfma_f32_16x16x32_bf16 v[80:83], v[232:235], v[84:87], v[80:83]
	v_mfma_f32_16x16x32_bf16 v[84:87], v[204:207], v[88:91], 0
	v_mfma_f32_16x16x32_bf16 v[88:91], v[228:231], v[88:91], 0
	v_mfma_f32_16x16x32_bf16 v[100:103], v[228:231], v[188:191], 0
	v_mfma_f32_16x16x32_bf16 v[104:107], v[204:207], v[196:199], 0
	v_mfma_f32_16x16x32_bf16 v[96:99], v[228:231], v[196:199], 0
	v_mfma_f32_16x16x32_bf16 v[84:87], v[222:225], v[92:95], v[84:87]
	v_mfma_f32_16x16x32_bf16 v[88:91], v[232:235], v[92:95], v[88:91]
	v_mfma_f32_16x16x32_bf16 v[92:95], v[204:207], v[188:191], 0
	v_mfma_f32_16x16x32_bf16 v[100:103], v[232:235], v[192:195], v[100:103]
	v_mfma_f32_16x16x32_bf16 v[128:131], v[222:225], v[200:203], v[104:107]
	v_mfma_f32_16x16x32_bf16 v[96:99], v[232:235], v[200:203], v[96:99]
	v_mfma_f32_16x16x32_bf16 v[92:95], v[222:225], v[192:195], v[92:95]
	s_barrier
	s_mov_b32 m0, s75
	v_lshl_add_u64 v[240:241], vcc, 0, v[144:145]
	ds_read_b128 v[104:107], v220 offset:16384
	ds_read_b128 v[108:111], v220 offset:17408
	ds_read_b128 v[132:135], v220 offset:18432
	ds_read_b128 v[136:139], v220 offset:19456
	ds_read_b128 v[188:191], v220 offset:20480
	ds_read_b128 v[192:195], v220 offset:21504
	ds_read_b128 v[196:199], v220 offset:22528
	ds_read_b128 v[200:203], v220 offset:23552
	global_load_lds_dwordx4 v[240:241], off
	v_lshl_add_u64 v[242:243], vcc, 0, v[162:163]
	s_mov_b32 m0, s85
	s_nop 0
	global_load_lds_dwordx4 v[242:243], off
	s_barrier
	s_waitcnt lgkmcnt(0)
	v_mfma_f32_16x16x32_bf16 v[48:51], v[64:67], v[104:107], 0
	v_mfma_f32_16x16x32_bf16 v[20:23], v[72:75], v[104:107], 0
	v_mfma_f32_16x16x32_bf16 v[60:63], v[64:67], v[132:135], 0
	v_mfma_f32_16x16x32_bf16 v[28:31], v[72:75], v[132:135], 0
	v_mfma_f32_16x16x32_bf16 v[56:59], v[64:67], v[188:191], 0
	v_mfma_f32_16x16x32_bf16 v[16:19], v[72:75], v[188:191], 0
	v_mfma_f32_16x16x32_bf16 v[52:55], v[64:67], v[196:199], 0
	v_mfma_f32_16x16x32_bf16 v[24:27], v[72:75], v[196:199], 0
	v_mfma_f32_16x16x32_bf16 v[48:51], v[68:71], v[108:111], v[48:51]
	v_mfma_f32_16x16x32_bf16 v[20:23], v[76:79], v[108:111], v[20:23]
	v_mfma_f32_16x16x32_bf16 v[60:63], v[68:71], v[136:139], v[60:63]
	v_mfma_f32_16x16x32_bf16 v[28:31], v[76:79], v[136:139], v[28:31]
	v_mfma_f32_16x16x32_bf16 v[56:59], v[68:71], v[192:195], v[56:59]
	v_mfma_f32_16x16x32_bf16 v[16:19], v[76:79], v[192:195], v[16:19]
	v_mfma_f32_16x16x32_bf16 v[52:55], v[68:71], v[200:203], v[52:55]
	v_mfma_f32_16x16x32_bf16 v[24:27], v[76:79], v[200:203], v[24:27]
	s_barrier
	s_add_u32 s56, s82, 0x40000
	s_addc_u32 s57, s83, 0
	s_add_i32 s27, s27, s74
	v_lshl_add_u64 v[64:65], s[56:57], 0, v[144:145]
	s_mov_b32 m0, s27
	s_nop 0
	global_load_lds_dwordx4 v[64:65], off
	v_lshl_add_u64 v[64:65], s[56:57], 0, v[162:163]
	s_add_i32 m0, s27, 0x2000
	s_nop 0
	global_load_lds_dwordx4 v[64:65], off
	s_waitcnt vmcnt(6)
	s_barrier
	v_mfma_f32_16x16x32_bf16 v[44:47], v[204:207], v[104:107], 0
	v_mfma_f32_16x16x32_bf16 v[12:15], v[228:231], v[104:107], 0
	v_mfma_f32_16x16x32_bf16 v[40:43], v[204:207], v[132:135], 0
	v_mfma_f32_16x16x32_bf16 v[8:11], v[228:231], v[132:135], 0
	v_mfma_f32_16x16x32_bf16 v[36:39], v[204:207], v[188:191], 0
	v_mfma_f32_16x16x32_bf16 v[4:7], v[228:231], v[188:191], 0
	v_mfma_f32_16x16x32_bf16 v[32:35], v[204:207], v[196:199], 0
	v_mfma_f32_16x16x32_bf16 v[0:3], v[228:231], v[196:199], 0
	v_mfma_f32_16x16x32_bf16 v[44:47], v[222:225], v[108:111], v[44:47]
	v_mfma_f32_16x16x32_bf16 v[12:15], v[232:235], v[108:111], v[12:15]
	v_mfma_f32_16x16x32_bf16 v[40:43], v[222:225], v[136:139], v[40:43]
	v_mfma_f32_16x16x32_bf16 v[8:11], v[232:235], v[136:139], v[8:11]
	v_mfma_f32_16x16x32_bf16 v[36:39], v[222:225], v[192:195], v[36:39]
	v_mfma_f32_16x16x32_bf16 v[4:7], v[232:235], v[192:195], v[4:7]
	v_mfma_f32_16x16x32_bf16 v[32:35], v[222:225], v[200:203], v[32:35]
	v_mfma_f32_16x16x32_bf16 v[0:3], v[232:235], v[200:203], v[0:3]
	s_barrier
	s_add_i32 s27, 0, 0x18000
	v_add_u32_e32 v76, s27, v217
	ds_read_b128 v[64:67], v76
	ds_read_b128 v[68:71], v76 offset:1024
	ds_read_b128 v[72:75], v76 offset:2048
	ds_read_b128 v[76:79], v76 offset:3072
	s_add_u32 s56, vcc_lo, 0x40000
	s_addc_u32 s57, vcc_hi, 0
	s_mov_b32 m0, s98
	v_lshl_add_u64 v[136:137], s[56:57], 0, v[144:145]
	ds_read_b128 v[104:107], v220 offset:32768
	ds_read_b128 v[108:111], v220 offset:33792
	ds_read_b128 v[132:135], v220 offset:34816
	ds_read_b128 v[188:191], v220 offset:35840
	ds_read_b128 v[192:195], v220 offset:36864
	ds_read_b128 v[196:199], v220 offset:37888
	ds_read_b128 v[200:203], v220 offset:38912
	ds_read_b128 v[204:207], v220 offset:39936
	global_load_lds_dwordx4 v[136:137], off
	v_lshl_add_u64 v[136:137], s[56:57], 0, v[162:163]
	s_mov_b32 m0, s29
	s_nop 0
	global_load_lds_dwordx4 v[136:137], off
	s_waitcnt lgkmcnt(8)
	s_barrier
	s_waitcnt lgkmcnt(0)
	v_mfma_f32_16x16x32_bf16 v[136:139], v[64:67], v[104:107], v[146:149]
	v_mfma_f32_16x16x32_bf16 v[146:149], v[68:71], v[108:111], v[136:139]
	v_mfma_f32_16x16x32_bf16 v[136:139], v[64:67], v[132:135], v[158:161]
	v_mfma_f32_16x16x32_bf16 v[158:161], v[68:71], v[188:191], v[136:139]
	v_mfma_f32_16x16x32_bf16 v[136:139], v[64:67], v[192:195], v[154:157]
	v_mfma_f32_16x16x32_bf16 v[116:119], v[72:75], v[104:107], v[116:119]
	v_mfma_f32_16x16x32_bf16 v[124:127], v[72:75], v[132:135], v[124:127]
	v_mfma_f32_16x16x32_bf16 v[154:157], v[68:71], v[196:199], v[136:139]
	v_mfma_f32_16x16x32_bf16 v[112:115], v[72:75], v[192:195], v[112:115]
	v_mfma_f32_16x16x32_bf16 v[136:139], v[64:67], v[200:203], v[150:153]
	v_mfma_f32_16x16x32_bf16 v[120:123], v[72:75], v[200:203], v[120:123]
	v_mfma_f32_16x16x32_bf16 v[116:119], v[76:79], v[108:111], v[116:119]
	v_mfma_f32_16x16x32_bf16 v[124:127], v[76:79], v[188:191], v[124:127]
	v_mfma_f32_16x16x32_bf16 v[112:115], v[76:79], v[196:199], v[112:115]
	v_mfma_f32_16x16x32_bf16 v[150:153], v[68:71], v[204:207], v[136:139]
	v_mfma_f32_16x16x32_bf16 v[120:123], v[76:79], v[204:207], v[120:123]
	s_barrier
	s_add_i32 s58, 0, 0x1c000
	v_add_u32_e32 v136, s58, v217
	s_add_i32 s27, s27, s74
	ds_read_b128 v[222:225], v136
	ds_read_b128 v[228:231], v136 offset:1024
	ds_read_b128 v[232:235], v136 offset:2048
	ds_read_b128 v[236:239], v136 offset:3072
	v_lshl_add_u64 v[136:137], v[168:169], 0, s[18:19]
	s_mov_b32 m0, s27
	s_nop 0
	global_load_lds_dwordx4 v[136:137], off
	v_lshl_add_u64 v[136:137], v[176:177], 0, s[18:19]
	s_add_i32 m0, s27, 0x2000
	s_nop 0
	global_load_lds_dwordx4 v[136:137], off
	s_barrier
	s_waitcnt lgkmcnt(0)
	v_mfma_f32_16x16x32_bf16 v[136:139], v[222:225], v[104:107], v[140:143]
	v_mfma_f32_16x16x32_bf16 v[80:83], v[232:235], v[104:107], v[80:83]
	v_mfma_f32_16x16x32_bf16 v[140:143], v[228:231], v[108:111], v[136:139]
	v_mfma_f32_16x16x32_bf16 v[108:111], v[236:239], v[108:111], v[80:83]
	v_mfma_f32_16x16x32_bf16 v[80:83], v[222:225], v[132:135], v[84:87]
	v_mfma_f32_16x16x32_bf16 v[136:139], v[228:231], v[188:191], v[80:83]
	v_mfma_f32_16x16x32_bf16 v[80:83], v[232:235], v[132:135], v[88:91]
	v_mfma_f32_16x16x32_bf16 v[104:107], v[236:239], v[188:191], v[80:83]
	v_mfma_f32_16x16x32_bf16 v[80:83], v[222:225], v[192:195], v[92:95]
	v_mfma_f32_16x16x32_bf16 v[132:135], v[228:231], v[196:199], v[80:83]
	v_mfma_f32_16x16x32_bf16 v[80:83], v[232:235], v[192:195], v[100:103]
	v_mfma_f32_16x16x32_bf16 v[100:103], v[236:239], v[196:199], v[80:83]
	v_mfma_f32_16x16x32_bf16 v[80:83], v[222:225], v[200:203], v[128:131]
	v_mfma_f32_16x16x32_bf16 v[128:131], v[228:231], v[204:207], v[80:83]
	v_mfma_f32_16x16x32_bf16 v[80:83], v[232:235], v[200:203], v[96:99]
	v_mfma_f32_16x16x32_bf16 v[96:99], v[236:239], v[204:207], v[80:83]
	s_barrier
	s_mov_b32 m0, s31
	v_lshl_add_u64 v[168:169], v[240:241], 0, s[18:19]
	s_nop 2
	ds_read_b128 v[80:83], v220 offset:49152
	ds_read_b128 v[84:87], v220 offset:50176
	ds_read_b128 v[88:91], v220 offset:51200
	ds_read_b128 v[92:95], v220 offset:52224
	ds_read_b128 v[188:191], v220 offset:53248
	ds_read_b128 v[192:195], v220 offset:54272
	ds_read_b128 v[196:199], v220 offset:55296
	ds_read_b128 v[200:203], v220 offset:56320
	global_load_lds_dwordx4 v[168:169], off
	v_lshl_add_u64 v[168:169], v[242:243], 0, s[18:19]
	s_mov_b32 m0, s34
	s_nop 0
	global_load_lds_dwordx4 v[168:169], off
	s_barrier
	s_waitcnt lgkmcnt(0)
	v_mfma_f32_16x16x32_bf16 v[48:51], v[64:67], v[80:83], v[48:51]
	v_mfma_f32_16x16x32_bf16 v[20:23], v[72:75], v[80:83], v[20:23]
	v_mfma_f32_16x16x32_bf16 v[60:63], v[64:67], v[88:91], v[60:63]
	v_mfma_f32_16x16x32_bf16 v[28:31], v[72:75], v[88:91], v[28:31]
	v_mfma_f32_16x16x32_bf16 v[56:59], v[64:67], v[188:191], v[56:59]
	v_mfma_f32_16x16x32_bf16 v[16:19], v[72:75], v[188:191], v[16:19]
	v_mfma_f32_16x16x32_bf16 v[52:55], v[64:67], v[196:199], v[52:55]
	v_mfma_f32_16x16x32_bf16 v[24:27], v[72:75], v[196:199], v[24:27]
	v_mfma_f32_16x16x32_bf16 v[48:51], v[68:71], v[84:87], v[48:51]
	v_mfma_f32_16x16x32_bf16 v[20:23], v[76:79], v[84:87], v[20:23]
	v_mfma_f32_16x16x32_bf16 v[60:63], v[68:71], v[92:95], v[60:63]
	v_mfma_f32_16x16x32_bf16 v[28:31], v[76:79], v[92:95], v[28:31]
	v_mfma_f32_16x16x32_bf16 v[56:59], v[68:71], v[192:195], v[56:59]
	v_mfma_f32_16x16x32_bf16 v[16:19], v[76:79], v[192:195], v[16:19]
	v_mfma_f32_16x16x32_bf16 v[52:55], v[68:71], v[200:203], v[52:55]
	v_mfma_f32_16x16x32_bf16 v[24:27], v[76:79], v[200:203], v[24:27]
	s_barrier
	s_add_u32 s56, s82, 0x40080
	s_addc_u32 s57, s83, 0
	s_add_i32 s27, s58, s74
	v_lshl_add_u64 v[64:65], s[56:57], 0, v[144:145]
	s_mov_b32 m0, s27
	s_nop 0
	global_load_lds_dwordx4 v[64:65], off
	v_lshl_add_u64 v[64:65], s[56:57], 0, v[162:163]
	s_add_i32 m0, s27, 0x2000
	s_nop 0
	global_load_lds_dwordx4 v[64:65], off
	s_waitcnt vmcnt(6)
	s_barrier
	v_mfma_f32_16x16x32_bf16 v[44:47], v[222:225], v[80:83], v[44:47]
	v_mfma_f32_16x16x32_bf16 v[12:15], v[232:235], v[80:83], v[12:15]
	v_mfma_f32_16x16x32_bf16 v[40:43], v[222:225], v[88:91], v[40:43]
	v_mfma_f32_16x16x32_bf16 v[8:11], v[232:235], v[88:91], v[8:11]
	v_mfma_f32_16x16x32_bf16 v[36:39], v[222:225], v[188:191], v[36:39]
	v_mfma_f32_16x16x32_bf16 v[4:7], v[232:235], v[188:191], v[4:7]
	v_mfma_f32_16x16x32_bf16 v[32:35], v[222:225], v[196:199], v[32:35]
	v_mfma_f32_16x16x32_bf16 v[0:3], v[232:235], v[196:199], v[0:3]
	v_mfma_f32_16x16x32_bf16 v[44:47], v[228:231], v[84:87], v[44:47]
	v_mfma_f32_16x16x32_bf16 v[12:15], v[236:239], v[84:87], v[12:15]
	v_mfma_f32_16x16x32_bf16 v[40:43], v[228:231], v[92:95], v[40:43]
	v_mfma_f32_16x16x32_bf16 v[8:11], v[236:239], v[92:95], v[8:11]
	v_mfma_f32_16x16x32_bf16 v[36:39], v[228:231], v[192:195], v[36:39]
	v_mfma_f32_16x16x32_bf16 v[4:7], v[236:239], v[192:195], v[4:7]
	v_mfma_f32_16x16x32_bf16 v[32:35], v[228:231], v[200:203], v[32:35]
	v_mfma_f32_16x16x32_bf16 v[0:3], v[236:239], v[200:203], v[0:3]
	s_barrier
	s_add_i32 s37, s37, 2
	s_add_u32 s86, s86, 0x100
	s_addc_u32 s87, s87, 0
	s_add_u32 s33, s33, 0x100
	s_addc_u32 s36, s36, 0
	s_cmp_gt_u32 s37, 13
.LBB0_125:
	s_add_u32 s27, s86, 0xfffc0080
	s_addc_u32 s56, s87, -1
	s_add_i32 s57, 0, 0x10000
	v_add_u32_e32 v76, s57, v217
	ds_read_b128 v[64:67], v76
	ds_read_b128 v[68:71], v76 offset:1024
	ds_read_b128 v[72:75], v76 offset:2048
	ds_read_b128 v[76:79], v76 offset:3072
	s_cmp_eq_u32 s37, 12
	s_cselect_b32 vcc_hi, s1, s56
	s_cselect_b32 vcc_lo, s10, s27
	s_cselect_b32 s83, s11, s36
	s_cselect_b32 s82, s25, s33
	v_lshl_add_u64 v[168:169], s[86:87], 0, v[164:165]
	s_add_i32 m0, s75, 0xc000
	ds_read_b128 v[80:83], v220
	ds_read_b128 v[84:87], v220 offset:1024
	ds_read_b128 v[88:91], v220 offset:2048
	ds_read_b128 v[92:95], v220 offset:3072
	ds_read_b128 v[188:191], v220 offset:4096
	ds_read_b128 v[192:195], v220 offset:5120
	ds_read_b128 v[196:199], v220 offset:6144
	ds_read_b128 v[200:203], v220 offset:7168
	global_load_lds_dwordx4 v[168:169], off
	v_lshl_add_u64 v[168:169], s[86:87], 0, v[166:167]
	s_add_i32 m0, s75, 0xe000
	s_nop 0
	global_load_lds_dwordx4 v[168:169], off
	s_waitcnt lgkmcnt(8)
	s_barrier
	s_waitcnt lgkmcnt(0)
	v_mfma_f32_16x16x32_bf16 v[146:149], v[64:67], v[80:83], v[146:149]
	v_mfma_f32_16x16x32_bf16 v[116:119], v[72:75], v[80:83], v[116:119]
	v_mfma_f32_16x16x32_bf16 v[158:161], v[64:67], v[88:91], v[158:161]
	v_mfma_f32_16x16x32_bf16 v[124:127], v[72:75], v[88:91], v[124:127]
	v_mfma_f32_16x16x32_bf16 v[154:157], v[64:67], v[188:191], v[154:157]
	v_mfma_f32_16x16x32_bf16 v[112:115], v[72:75], v[188:191], v[112:115]
	v_mfma_f32_16x16x32_bf16 v[150:153], v[64:67], v[196:199], v[150:153]
	v_mfma_f32_16x16x32_bf16 v[120:123], v[72:75], v[196:199], v[120:123]
	v_mfma_f32_16x16x32_bf16 v[146:149], v[68:71], v[84:87], v[146:149]
	v_mfma_f32_16x16x32_bf16 v[116:119], v[76:79], v[84:87], v[116:119]
	v_mfma_f32_16x16x32_bf16 v[158:161], v[68:71], v[92:95], v[158:161]
	v_mfma_f32_16x16x32_bf16 v[124:127], v[76:79], v[92:95], v[124:127]
	v_mfma_f32_16x16x32_bf16 v[154:157], v[68:71], v[192:195], v[154:157]
	v_mfma_f32_16x16x32_bf16 v[112:115], v[76:79], v[192:195], v[112:115]
	v_mfma_f32_16x16x32_bf16 v[150:153], v[68:71], v[200:203], v[150:153]
	v_mfma_f32_16x16x32_bf16 v[120:123], v[76:79], v[200:203], v[120:123]
	s_barrier
	s_add_i32 s27, 0, 0x14000
	v_add_u32_e32 v168, s27, v217
	s_add_i32 s56, s57, s74
	ds_read_b128 v[204:207], v168
	ds_read_b128 v[222:225], v168 offset:1024
	ds_read_b128 v[228:231], v168 offset:2048
	ds_read_b128 v[232:235], v168 offset:3072
	v_lshl_add_u64 v[168:169], s[82:83], 0, v[144:145]
	s_mov_b32 m0, s56
	v_lshl_add_u64 v[176:177], s[82:83], 0, v[162:163]
	global_load_lds_dwordx4 v[168:169], off
	s_add_i32 m0, s56, 0x2000
	s_nop 0
	global_load_lds_dwordx4 v[176:177], off
	s_barrier
	s_waitcnt lgkmcnt(0)
	v_mfma_f32_16x16x32_bf16 v[140:143], v[204:207], v[80:83], v[140:143]
	v_mfma_f32_16x16x32_bf16 v[80:83], v[228:231], v[80:83], v[108:111]
	v_mfma_f32_16x16x32_bf16 v[140:143], v[222:225], v[84:87], v[140:143]
	v_mfma_f32_16x16x32_bf16 v[80:83], v[232:235], v[84:87], v[80:83]
	v_mfma_f32_16x16x32_bf16 v[84:87], v[204:207], v[88:91], v[136:139]
	v_mfma_f32_16x16x32_bf16 v[88:91], v[228:231], v[88:91], v[104:107]
	v_mfma_f32_16x16x32_bf16 v[100:103], v[228:231], v[188:191], v[100:103]
	v_mfma_f32_16x16x32_bf16 v[104:107], v[204:207], v[196:199], v[128:131]
	v_mfma_f32_16x16x32_bf16 v[96:99], v[228:231], v[196:199], v[96:99]
	v_mfma_f32_16x16x32_bf16 v[84:87], v[222:225], v[92:95], v[84:87]
	v_mfma_f32_16x16x32_bf16 v[88:91], v[232:235], v[92:95], v[88:91]
	v_mfma_f32_16x16x32_bf16 v[92:95], v[204:207], v[188:191], v[132:135]
	v_mfma_f32_16x16x32_bf16 v[100:103], v[232:235], v[192:195], v[100:103]
	v_mfma_f32_16x16x32_bf16 v[128:131], v[222:225], v[200:203], v[104:107]
	v_mfma_f32_16x16x32_bf16 v[96:99], v[232:235], v[200:203], v[96:99]
	v_mfma_f32_16x16x32_bf16 v[92:95], v[222:225], v[192:195], v[92:95]
	s_barrier
	s_mov_b32 m0, s75
	v_lshl_add_u64 v[240:241], vcc, 0, v[144:145]
	ds_read_b128 v[104:107], v220 offset:16384
	ds_read_b128 v[108:111], v220 offset:17408
	ds_read_b128 v[132:135], v220 offset:18432
	ds_read_b128 v[136:139], v220 offset:19456
	ds_read_b128 v[188:191], v220 offset:20480
	ds_read_b128 v[192:195], v220 offset:21504
	ds_read_b128 v[196:199], v220 offset:22528
	ds_read_b128 v[200:203], v220 offset:23552
	global_load_lds_dwordx4 v[240:241], off
	v_lshl_add_u64 v[242:243], vcc, 0, v[162:163]
	s_mov_b32 m0, s85
	s_nop 0
	global_load_lds_dwordx4 v[242:243], off
	s_barrier
	s_waitcnt lgkmcnt(0)
	v_mfma_f32_16x16x32_bf16 v[48:51], v[64:67], v[104:107], v[48:51]
	v_mfma_f32_16x16x32_bf16 v[20:23], v[72:75], v[104:107], v[20:23]
	v_mfma_f32_16x16x32_bf16 v[60:63], v[64:67], v[132:135], v[60:63]
	v_mfma_f32_16x16x32_bf16 v[28:31], v[72:75], v[132:135], v[28:31]
	v_mfma_f32_16x16x32_bf16 v[56:59], v[64:67], v[188:191], v[56:59]
	v_mfma_f32_16x16x32_bf16 v[16:19], v[72:75], v[188:191], v[16:19]
	v_mfma_f32_16x16x32_bf16 v[52:55], v[64:67], v[196:199], v[52:55]
	v_mfma_f32_16x16x32_bf16 v[24:27], v[72:75], v[196:199], v[24:27]
	v_mfma_f32_16x16x32_bf16 v[48:51], v[68:71], v[108:111], v[48:51]
	v_mfma_f32_16x16x32_bf16 v[20:23], v[76:79], v[108:111], v[20:23]
	v_mfma_f32_16x16x32_bf16 v[60:63], v[68:71], v[136:139], v[60:63]
	v_mfma_f32_16x16x32_bf16 v[28:31], v[76:79], v[136:139], v[28:31]
	v_mfma_f32_16x16x32_bf16 v[56:59], v[68:71], v[192:195], v[56:59]
	v_mfma_f32_16x16x32_bf16 v[16:19], v[76:79], v[192:195], v[16:19]
	v_mfma_f32_16x16x32_bf16 v[52:55], v[68:71], v[200:203], v[52:55]
	v_mfma_f32_16x16x32_bf16 v[24:27], v[76:79], v[200:203], v[24:27]
	s_barrier
	s_add_u32 s56, s82, 0x40000
	s_addc_u32 s57, s83, 0
	s_add_i32 s27, s27, s74
	v_lshl_add_u64 v[64:65], s[56:57], 0, v[144:145]
	s_mov_b32 m0, s27
	s_nop 0
	global_load_lds_dwordx4 v[64:65], off
	v_lshl_add_u64 v[64:65], s[56:57], 0, v[162:163]
	s_add_i32 m0, s27, 0x2000
	s_nop 0
	global_load_lds_dwordx4 v[64:65], off
	s_waitcnt vmcnt(6)
	s_barrier
	v_mfma_f32_16x16x32_bf16 v[44:47], v[204:207], v[104:107], v[44:47]
	v_mfma_f32_16x16x32_bf16 v[12:15], v[228:231], v[104:107], v[12:15]
	v_mfma_f32_16x16x32_bf16 v[40:43], v[204:207], v[132:135], v[40:43]
	v_mfma_f32_16x16x32_bf16 v[8:11], v[228:231], v[132:135], v[8:11]
	v_mfma_f32_16x16x32_bf16 v[36:39], v[204:207], v[188:191], v[36:39]
	v_mfma_f32_16x16x32_bf16 v[4:7], v[228:231], v[188:191], v[4:7]
	v_mfma_f32_16x16x32_bf16 v[32:35], v[204:207], v[196:199], v[32:35]
	v_mfma_f32_16x16x32_bf16 v[0:3], v[228:231], v[196:199], v[0:3]
	v_mfma_f32_16x16x32_bf16 v[44:47], v[222:225], v[108:111], v[44:47]
	v_mfma_f32_16x16x32_bf16 v[12:15], v[232:235], v[108:111], v[12:15]
	v_mfma_f32_16x16x32_bf16 v[40:43], v[222:225], v[136:139], v[40:43]
	v_mfma_f32_16x16x32_bf16 v[8:11], v[232:235], v[136:139], v[8:11]
	v_mfma_f32_16x16x32_bf16 v[36:39], v[222:225], v[192:195], v[36:39]
	v_mfma_f32_16x16x32_bf16 v[4:7], v[232:235], v[192:195], v[4:7]
	v_mfma_f32_16x16x32_bf16 v[32:35], v[222:225], v[200:203], v[32:35]
	v_mfma_f32_16x16x32_bf16 v[0:3], v[232:235], v[200:203], v[0:3]
	s_barrier
	s_add_i32 s27, 0, 0x18000
	v_add_u32_e32 v76, s27, v217
	ds_read_b128 v[64:67], v76
	ds_read_b128 v[68:71], v76 offset:1024
	ds_read_b128 v[72:75], v76 offset:2048
	ds_read_b128 v[76:79], v76 offset:3072
	s_add_u32 s56, vcc_lo, 0x40000
	s_addc_u32 s57, vcc_hi, 0
	s_mov_b32 m0, s98
	v_lshl_add_u64 v[136:137], s[56:57], 0, v[144:145]
	ds_read_b128 v[104:107], v220 offset:32768
	ds_read_b128 v[108:111], v220 offset:33792
	ds_read_b128 v[132:135], v220 offset:34816
	ds_read_b128 v[188:191], v220 offset:35840
	ds_read_b128 v[192:195], v220 offset:36864
	ds_read_b128 v[196:199], v220 offset:37888
	ds_read_b128 v[200:203], v220 offset:38912
	ds_read_b128 v[204:207], v220 offset:39936
	global_load_lds_dwordx4 v[136:137], off
	v_lshl_add_u64 v[136:137], s[56:57], 0, v[162:163]
	s_mov_b32 m0, s29
	s_nop 0
	global_load_lds_dwordx4 v[136:137], off
	s_waitcnt lgkmcnt(8)
	s_barrier
	s_waitcnt lgkmcnt(0)
	v_mfma_f32_16x16x32_bf16 v[136:139], v[64:67], v[104:107], v[146:149]
	v_mfma_f32_16x16x32_bf16 v[146:149], v[68:71], v[108:111], v[136:139]
	v_mfma_f32_16x16x32_bf16 v[136:139], v[64:67], v[132:135], v[158:161]
	v_mfma_f32_16x16x32_bf16 v[158:161], v[68:71], v[188:191], v[136:139]
	v_mfma_f32_16x16x32_bf16 v[136:139], v[64:67], v[192:195], v[154:157]
	v_mfma_f32_16x16x32_bf16 v[116:119], v[72:75], v[104:107], v[116:119]
	v_mfma_f32_16x16x32_bf16 v[124:127], v[72:75], v[132:135], v[124:127]
	v_mfma_f32_16x16x32_bf16 v[154:157], v[68:71], v[196:199], v[136:139]
	v_mfma_f32_16x16x32_bf16 v[112:115], v[72:75], v[192:195], v[112:115]
	v_mfma_f32_16x16x32_bf16 v[136:139], v[64:67], v[200:203], v[150:153]
	v_mfma_f32_16x16x32_bf16 v[120:123], v[72:75], v[200:203], v[120:123]
	v_mfma_f32_16x16x32_bf16 v[116:119], v[76:79], v[108:111], v[116:119]
	v_mfma_f32_16x16x32_bf16 v[124:127], v[76:79], v[188:191], v[124:127]
	v_mfma_f32_16x16x32_bf16 v[112:115], v[76:79], v[196:199], v[112:115]
	v_mfma_f32_16x16x32_bf16 v[150:153], v[68:71], v[204:207], v[136:139]
	v_mfma_f32_16x16x32_bf16 v[120:123], v[76:79], v[204:207], v[120:123]
	s_barrier
	s_add_i32 s58, 0, 0x1c000
	v_add_u32_e32 v136, s58, v217
	s_add_i32 s27, s27, s74
	ds_read_b128 v[222:225], v136
	ds_read_b128 v[228:231], v136 offset:1024
	ds_read_b128 v[232:235], v136 offset:2048
	ds_read_b128 v[236:239], v136 offset:3072
	v_lshl_add_u64 v[136:137], v[168:169], 0, s[18:19]
	s_mov_b32 m0, s27
	s_nop 0
	global_load_lds_dwordx4 v[136:137], off
	v_lshl_add_u64 v[136:137], v[176:177], 0, s[18:19]
	s_add_i32 m0, s27, 0x2000
	s_nop 0
	global_load_lds_dwordx4 v[136:137], off
	s_barrier
	s_waitcnt lgkmcnt(0)
	v_mfma_f32_16x16x32_bf16 v[136:139], v[222:225], v[104:107], v[140:143]
	v_mfma_f32_16x16x32_bf16 v[80:83], v[232:235], v[104:107], v[80:83]
	v_mfma_f32_16x16x32_bf16 v[140:143], v[228:231], v[108:111], v[136:139]
	v_mfma_f32_16x16x32_bf16 v[108:111], v[236:239], v[108:111], v[80:83]
	v_mfma_f32_16x16x32_bf16 v[80:83], v[222:225], v[132:135], v[84:87]
	v_mfma_f32_16x16x32_bf16 v[136:139], v[228:231], v[188:191], v[80:83]
	v_mfma_f32_16x16x32_bf16 v[80:83], v[232:235], v[132:135], v[88:91]
	v_mfma_f32_16x16x32_bf16 v[104:107], v[236:239], v[188:191], v[80:83]
	v_mfma_f32_16x16x32_bf16 v[80:83], v[222:225], v[192:195], v[92:95]
	v_mfma_f32_16x16x32_bf16 v[132:135], v[228:231], v[196:199], v[80:83]
	v_mfma_f32_16x16x32_bf16 v[80:83], v[232:235], v[192:195], v[100:103]
	v_mfma_f32_16x16x32_bf16 v[100:103], v[236:239], v[196:199], v[80:83]
	v_mfma_f32_16x16x32_bf16 v[80:83], v[222:225], v[200:203], v[128:131]
	v_mfma_f32_16x16x32_bf16 v[128:131], v[228:231], v[204:207], v[80:83]
	v_mfma_f32_16x16x32_bf16 v[80:83], v[232:235], v[200:203], v[96:99]
	v_mfma_f32_16x16x32_bf16 v[96:99], v[236:239], v[204:207], v[80:83]
	s_barrier
	s_mov_b32 m0, s31
	v_lshl_add_u64 v[168:169], v[240:241], 0, s[18:19]
	s_nop 2
	ds_read_b128 v[80:83], v220 offset:49152
	ds_read_b128 v[84:87], v220 offset:50176
	ds_read_b128 v[88:91], v220 offset:51200
	ds_read_b128 v[92:95], v220 offset:52224
	ds_read_b128 v[188:191], v220 offset:53248
	ds_read_b128 v[192:195], v220 offset:54272
	ds_read_b128 v[196:199], v220 offset:55296
	ds_read_b128 v[200:203], v220 offset:56320
	global_load_lds_dwordx4 v[168:169], off
	v_lshl_add_u64 v[168:169], v[242:243], 0, s[18:19]
	s_mov_b32 m0, s34
	s_nop 0
	global_load_lds_dwordx4 v[168:169], off
	s_barrier
	s_waitcnt lgkmcnt(0)
	v_mfma_f32_16x16x32_bf16 v[48:51], v[64:67], v[80:83], v[48:51]
	v_mfma_f32_16x16x32_bf16 v[20:23], v[72:75], v[80:83], v[20:23]
	v_mfma_f32_16x16x32_bf16 v[60:63], v[64:67], v[88:91], v[60:63]
	v_mfma_f32_16x16x32_bf16 v[28:31], v[72:75], v[88:91], v[28:31]
	v_mfma_f32_16x16x32_bf16 v[56:59], v[64:67], v[188:191], v[56:59]
	v_mfma_f32_16x16x32_bf16 v[16:19], v[72:75], v[188:191], v[16:19]
	v_mfma_f32_16x16x32_bf16 v[52:55], v[64:67], v[196:199], v[52:55]
	v_mfma_f32_16x16x32_bf16 v[24:27], v[72:75], v[196:199], v[24:27]
	v_mfma_f32_16x16x32_bf16 v[48:51], v[68:71], v[84:87], v[48:51]
	v_mfma_f32_16x16x32_bf16 v[20:23], v[76:79], v[84:87], v[20:23]
	v_mfma_f32_16x16x32_bf16 v[60:63], v[68:71], v[92:95], v[60:63]
	v_mfma_f32_16x16x32_bf16 v[28:31], v[76:79], v[92:95], v[28:31]
	v_mfma_f32_16x16x32_bf16 v[56:59], v[68:71], v[192:195], v[56:59]
	v_mfma_f32_16x16x32_bf16 v[16:19], v[76:79], v[192:195], v[16:19]
	v_mfma_f32_16x16x32_bf16 v[52:55], v[68:71], v[200:203], v[52:55]
	v_mfma_f32_16x16x32_bf16 v[24:27], v[76:79], v[200:203], v[24:27]
	s_barrier
	s_add_u32 s56, s82, 0x40080
	s_addc_u32 s57, s83, 0
	s_add_i32 s27, s58, s74
	v_lshl_add_u64 v[64:65], s[56:57], 0, v[144:145]
	s_mov_b32 m0, s27
	s_nop 0
	global_load_lds_dwordx4 v[64:65], off
	v_lshl_add_u64 v[64:65], s[56:57], 0, v[162:163]
	s_add_i32 m0, s27, 0x2000
	s_nop 0
	global_load_lds_dwordx4 v[64:65], off
	s_waitcnt vmcnt(6)
	s_barrier
	v_mfma_f32_16x16x32_bf16 v[44:47], v[222:225], v[80:83], v[44:47]
	v_mfma_f32_16x16x32_bf16 v[12:15], v[232:235], v[80:83], v[12:15]
	v_mfma_f32_16x16x32_bf16 v[40:43], v[222:225], v[88:91], v[40:43]
	v_mfma_f32_16x16x32_bf16 v[8:11], v[232:235], v[88:91], v[8:11]
	v_mfma_f32_16x16x32_bf16 v[36:39], v[222:225], v[188:191], v[36:39]
	v_mfma_f32_16x16x32_bf16 v[4:7], v[232:235], v[188:191], v[4:7]
	v_mfma_f32_16x16x32_bf16 v[32:35], v[222:225], v[196:199], v[32:35]
	v_mfma_f32_16x16x32_bf16 v[0:3], v[232:235], v[196:199], v[0:3]
	v_mfma_f32_16x16x32_bf16 v[44:47], v[228:231], v[84:87], v[44:47]
	v_mfma_f32_16x16x32_bf16 v[12:15], v[236:239], v[84:87], v[12:15]
	v_mfma_f32_16x16x32_bf16 v[40:43], v[228:231], v[92:95], v[40:43]
	v_mfma_f32_16x16x32_bf16 v[8:11], v[236:239], v[92:95], v[8:11]
	v_mfma_f32_16x16x32_bf16 v[36:39], v[228:231], v[192:195], v[36:39]
	v_mfma_f32_16x16x32_bf16 v[4:7], v[236:239], v[192:195], v[4:7]
	v_mfma_f32_16x16x32_bf16 v[32:35], v[228:231], v[200:203], v[32:35]
	v_mfma_f32_16x16x32_bf16 v[0:3], v[236:239], v[200:203], v[0:3]
	s_barrier
	s_add_i32 s37, s37, 2
	s_add_u32 s86, s86, 0x100
	s_addc_u32 s87, s87, 0
	s_add_u32 s33, s33, 0x100
	s_addc_u32 s36, s36, 0
	s_cmp_gt_u32 s37, 13
	s_cbranch_scc0 .LBB0_125
	s_lshl_b32 s1, s84, 8
	v_readlane_b32 s10, v254, 61
	s_add_i32 s1, s1, s10
	v_or_b32_e32 v198, s1, v216
	s_add_i32 s10, s1, 0x80
	v_or_b32_e32 v168, s10, v216
	v_lshl_or_b32 v188, s0, 7, v219
	v_lshlrev_b32_e32 v190, 2, v188
	v_lshlrev_b32_e32 v189, 1, v188
	s_ashr_i32 s11, s1, 5
	s_movk_i32 s10, 0xb00
	s_movk_i32 s20, 0x1600
	s_mov_b32 s101, 0xbfb8aa3b
	s_cmp_eq_u32 s84, s100
	s_cbranch_scc1 .Ldepi_w
	v_ashrrev_i32_e32 v199, 31, v198
	v_ashrrev_i32_e32 v169, 31, v168
	v_lshl_add_u64 v[170:171], v[198:199], 3, s[48:49]
	v_lshl_add_u64 v[172:173], v[168:169], 3, s[48:49]
	global_load_dwordx2 v[176:177], v[170:171], off
	global_load_dwordx2 v[202:203], v[170:171], off offset:128
	global_load_dwordx2 v[206:207], v[170:171], off offset:256
	global_load_dwordx2 v[222:223], v[170:171], off offset:384
	global_load_dwordx2 v[200:201], v[172:173], off
	global_load_dwordx2 v[196:197], v[172:173], off offset:128
	global_load_dwordx2 v[194:195], v[172:173], off offset:256
	global_load_dwordx2 v[192:193], v[172:173], off offset:384

.LBB0_146:
	s_setprio 0
	s_waitcnt vmcnt(0)
	v_readlane_b32 s48, v254, 55
	v_readlane_b32 s92, v254, 39
	v_readlane_b32 s94, v254, 41
	s_cmpk_gt_u32 s28, 0xff
	v_readlane_b32 s49, v254, 56
	v_readlane_b32 s93, v254, 40
	v_readlane_b32 s95, v254, 42
	s_mov_b64 s[36:37], 0x20000
	s_cbranch_scc1 .LBB0_148
	s_barrier

.LBB0_181:
	v_readlane_b32 s20, v254, 47
	s_add_i32 s31, s20, 4
	s_cmp_lt_u32 s31, 11
	s_cselect_b64 s[34:35], -1, 0
	s_and_b64 s[34:35], s[34:35], s[0:1]
	v_readlane_b32 s56, v254, 23
	s_and_b64 s[34:35], s[34:35], exec
	v_readlane_b32 s57, v254, 24
	s_cselect_b32 s51, s57, 0
	s_cselect_b32 s50, s56, 0
	s_sub_i32 s31, s20, 25
	s_cmp_lt_u32 s31, -6
	s_cselect_b64 s[34:35], -1, 0
	s_or_b64 s[0:1], s[34:35], s[0:1]
	v_readlane_b32 s40, v252, 0
	s_and_b64 s[0:1], s[0:1], exec
	v_readlane_b32 s42, v252, 2
	v_readlane_b32 s43, v252, 3
	v_bfe_u32 v19, v18, 4, 2
	s_cselect_b32 s95, 0, s43
	s_cselect_b32 s94, 0, s42
	s_add_u32 s52, s54, s38
	v_and_b32_e32 v20, 15, v18
	v_lshlrev_b32_e32 v21, 4, v19
	v_lshlrev_b32_e32 v18, 2, v18
	s_addc_u32 s53, s55, s39
	v_lshl_or_b32 v206, s27, 6, v20
	v_lshl_or_b32 v20, v20, 6, v21
	s_lshl_b32 s0, s27, 13
	v_and_b32_e32 v18, 32, v18
	s_add_i32 m0, s85, 0x18000
	v_lshl_add_u64 v[0:1], v[0:1], 0, s[18:19]
	v_bitop3_b32 v21, v20, s0, v18 bitop3:0xde
	s_lshl_b32 s0, s30, 5
	s_waitcnt vmcnt(4)
	s_barrier
	global_load_lds_dwordx4 v[0:1], off
	v_lshl_add_u64 v[0:1], v[2:3], 0, s[18:19]
	s_add_i32 m0, s85, 0x1a000
	s_add_i32 s30, s85, 0x8000
	global_load_lds_dwordx4 v[0:1], off
	v_lshl_add_u64 v[0:1], v[4:5], 0, s[18:19]
	s_mov_b32 m0, s30
	s_add_i32 s31, s85, 0xa000
	global_load_lds_dwordx4 v[0:1], off
	v_lshl_add_u64 v[0:1], v[6:7], 0, s[18:19]
	s_mov_b32 m0, s31
	s_lshr_b32 s34, s25, 6
	global_load_lds_dwordx4 v[0:1], off
	s_add_i32 m0, s85, 0x1c000
	v_lshl_add_u64 v[0:1], v[8:9], 0, s[18:19]
	global_load_lds_dwordx4 v[0:1], off
	v_lshl_add_u64 v[0:1], v[10:11], 0, s[18:19]
	s_add_i32 m0, s85, 0x1e000
	s_and_b32 s0, s0, 0x60
	global_load_lds_dwordx4 v[0:1], off
	s_lshl_b32 s1, s0, 7
	s_add_i32 s82, s34, -2
	s_ashr_i32 s35, s29, 31
	v_add_u32_e32 v0, v14, v12
	s_cmp_lg_u64 s[50:51], 0
	v_add_lshl_u32 v0, v0, v13, 1
	v_mov_b32_e32 v1, v145
	s_waitcnt vmcnt(6)
	s_cselect_b64 s[92:93], -1, 0
	s_cmp_eq_u64 s[94:95], 0
	v_lshl_add_u64 v[190:191], s[98:99], 0, v[0:1]
	v_add_u32_e32 v0, v17, v15
	s_cselect_b64 s[72:73], -1, 0
	s_cmp_lg_u64 s[94:95], 0
	v_add_lshl_u32 v0, v0, v16, 1
	s_mov_b32 s81, 0
	v_bitop3_b32 v207, v20, s1, v18 bitop3:0xde
	v_cmp_eq_u32_e64 s[38:39], 0, v19
	s_cselect_b64 s[74:75], -1, 0
	v_lshl_or_b32 v216, v19, 3, s0
	v_lshl_add_u64 v[192:193], s[98:99], 0, v[0:1]
	v_add_u32_e32 v217, 0, v21
	v_readlane_b32 s58, v254, 25
	v_readlane_b32 s59, v254, 26
	v_readlane_b32 s60, v254, 27
	v_readlane_b32 s61, v254, 28
	v_readlane_b32 s62, v254, 29
	v_readlane_b32 s63, v254, 30
	v_readlane_b32 s64, v254, 31
	v_readlane_b32 s65, v254, 32
	v_readlane_b32 s66, v254, 33
	v_readlane_b32 s67, v254, 34
	v_readlane_b32 s68, v254, 35
	v_readlane_b32 s69, v254, 36
	v_readlane_b32 s70, v254, 37
	v_readlane_b32 s71, v254, 38
	v_readlane_b32 s41, v252, 1
	s_barrier
	v_readfirstlane_b32 s101, v208
	s_nop 3
	s_lshr_b32 s101, s101, 8
	s_cmp_eq_u32 s101, 0
	s_cbranch_scc1 .Lprio_ce_done
	s_setprio 1
.Lprio_ce_done:
	s_branch .LBB0_185
.LBB0_182:
	s_or_b64 exec, exec, s[42:43]

.LBB0_195:
	s_add_u32 s42, s78, 0x80
	s_addc_u32 s43, s79, 0
	s_add_u32 s33, s44, 0x100
	s_addc_u32 s37, s45, 0
	s_mov_b32 s27, 0
	s_waitcnt lgkmcnt(0)
	s_add_i32 s56, s27, 2
	s_add_u32 s44, s42, 0x80
	s_addc_u32 s45, s43, 0
	s_add_i32 s57, 0, 0x10000
	v_add_u32_e32 v140, s57, v207
	ds_read_b128 v[128:131], v140
	ds_read_b128 v[132:135], v140 offset:1024
	ds_read_b128 v[136:139], v140 offset:2048
	ds_read_b128 v[140:143], v140 offset:3072
	s_cmp_eq_u32 s82, s27
	s_cselect_b32 s45, s77, s45
	s_cselect_b32 s44, s76, s44
	s_cselect_b32 s79, s1, s37
	s_cselect_b32 s78, s0, s33
	v_lshl_add_u64 v[176:177], s[42:43], 0, v[190:191]
	s_add_i32 m0, s85, 0xc000
	ds_read_b128 v[146:149], v217
	ds_read_b128 v[150:153], v217 offset:1024
	ds_read_b128 v[154:157], v217 offset:2048
	ds_read_b128 v[158:161], v217 offset:3072
	ds_read_b128 v[162:165], v217 offset:4096
	ds_read_b128 v[166:169], v217 offset:5120
	ds_read_b128 v[194:197], v217 offset:6144
	ds_read_b128 v[198:201], v217 offset:7168
	global_load_lds_dwordx4 v[176:177], off
	v_lshl_add_u64 v[176:177], s[42:43], 0, v[192:193]
	s_add_i32 m0, s85, 0xe000
	s_nop 0
	global_load_lds_dwordx4 v[176:177], off
	s_waitcnt lgkmcnt(8)
	s_barrier
	s_waitcnt lgkmcnt(0)
	v_mfma_f32_16x16x32_bf16 v[124:127], v[128:131], v[146:149], 0
	v_mfma_f32_16x16x32_bf16 v[120:123], v[136:139], v[146:149], 0
	v_mfma_f32_16x16x32_bf16 v[108:111], v[128:131], v[154:157], 0
	v_mfma_f32_16x16x32_bf16 v[104:107], v[136:139], v[154:157], 0
	v_mfma_f32_16x16x32_bf16 v[92:95], v[128:131], v[162:165], 0
	v_mfma_f32_16x16x32_bf16 v[88:91], v[136:139], v[162:165], 0
	v_mfma_f32_16x16x32_bf16 v[76:79], v[128:131], v[194:197], 0
	v_mfma_f32_16x16x32_bf16 v[72:75], v[136:139], v[194:197], 0
	v_mfma_f32_16x16x32_bf16 v[124:127], v[132:135], v[150:153], v[124:127]
	v_mfma_f32_16x16x32_bf16 v[120:123], v[140:143], v[150:153], v[120:123]
	v_mfma_f32_16x16x32_bf16 v[108:111], v[132:135], v[158:161], v[108:111]
	v_mfma_f32_16x16x32_bf16 v[104:107], v[140:143], v[158:161], v[104:107]
	v_mfma_f32_16x16x32_bf16 v[92:95], v[132:135], v[166:169], v[92:95]
	v_mfma_f32_16x16x32_bf16 v[88:91], v[140:143], v[166:169], v[88:91]
	v_mfma_f32_16x16x32_bf16 v[76:79], v[132:135], v[198:201], v[76:79]
	v_mfma_f32_16x16x32_bf16 v[72:75], v[140:143], v[198:201], v[72:75]
	s_barrier
	s_add_i32 s27, 0, 0x14000
	v_add_u32_e32 v176, s27, v207
	s_add_i32 s57, s57, s84
	ds_read_b128 v[202:205], v176
	ds_read_b128 v[218:221], v176 offset:1024
	ds_read_b128 v[222:225], v176 offset:2048
	ds_read_b128 v[228:231], v176 offset:3072
	v_lshl_add_u64 v[176:177], s[78:79], 0, v[144:145]
	s_mov_b32 m0, s57
	v_lshl_add_u64 v[232:233], s[78:79], 0, v[188:189]
	global_load_lds_dwordx4 v[176:177], off
	s_add_i32 m0, s57, 0x2000
	s_nop 0
	global_load_lds_dwordx4 v[232:233], off
	s_barrier
	s_waitcnt lgkmcnt(0)
	v_mfma_f32_16x16x32_bf16 v[116:119], v[202:205], v[146:149], 0
	v_mfma_f32_16x16x32_bf16 v[112:115], v[222:225], v[146:149], 0
	v_mfma_f32_16x16x32_bf16 v[100:103], v[202:205], v[154:157], 0
	v_mfma_f32_16x16x32_bf16 v[96:99], v[222:225], v[154:157], 0
	v_mfma_f32_16x16x32_bf16 v[84:87], v[202:205], v[162:165], 0
	v_mfma_f32_16x16x32_bf16 v[80:83], v[222:225], v[162:165], 0
	v_mfma_f32_16x16x32_bf16 v[68:71], v[202:205], v[194:197], 0
	v_mfma_f32_16x16x32_bf16 v[64:67], v[222:225], v[194:197], 0
	v_mfma_f32_16x16x32_bf16 v[116:119], v[218:221], v[150:153], v[116:119]
	v_mfma_f32_16x16x32_bf16 v[112:115], v[228:231], v[150:153], v[112:115]
	v_mfma_f32_16x16x32_bf16 v[100:103], v[218:221], v[158:161], v[100:103]
	v_mfma_f32_16x16x32_bf16 v[96:99], v[228:231], v[158:161], v[96:99]
	v_mfma_f32_16x16x32_bf16 v[84:87], v[218:221], v[166:169], v[84:87]
	v_mfma_f32_16x16x32_bf16 v[80:83], v[228:231], v[166:169], v[80:83]
	v_mfma_f32_16x16x32_bf16 v[68:71], v[218:221], v[198:201], v[68:71]
	v_mfma_f32_16x16x32_bf16 v[64:67], v[228:231], v[198:201], v[64:67]
	s_barrier
	s_mov_b32 m0, s85
	v_lshl_add_u64 v[234:235], s[44:45], 0, v[144:145]
	ds_read_b128 v[146:149], v217 offset:16384
	ds_read_b128 v[150:153], v217 offset:17408
	ds_read_b128 v[154:157], v217 offset:18432
	ds_read_b128 v[158:161], v217 offset:19456
	ds_read_b128 v[162:165], v217 offset:20480
	ds_read_b128 v[166:169], v217 offset:21504
	ds_read_b128 v[194:197], v217 offset:22528
	ds_read_b128 v[198:201], v217 offset:23552
	global_load_lds_dwordx4 v[234:235], off
	v_lshl_add_u64 v[236:237], s[44:45], 0, v[188:189]
	s_mov_b32 m0, s86
	s_nop 0
	global_load_lds_dwordx4 v[236:237], off
	s_barrier
	s_waitcnt lgkmcnt(0)
	v_mfma_f32_16x16x32_bf16 v[60:63], v[128:131], v[146:149], 0
	v_mfma_f32_16x16x32_bf16 v[56:59], v[136:139], v[146:149], 0
	v_mfma_f32_16x16x32_bf16 v[44:47], v[128:131], v[154:157], 0
	v_mfma_f32_16x16x32_bf16 v[40:43], v[136:139], v[154:157], 0
	v_mfma_f32_16x16x32_bf16 v[28:31], v[128:131], v[162:165], 0
	v_mfma_f32_16x16x32_bf16 v[24:27], v[136:139], v[162:165], 0
	v_mfma_f32_16x16x32_bf16 v[12:15], v[128:131], v[194:197], 0
	v_mfma_f32_16x16x32_bf16 v[8:11], v[136:139], v[194:197], 0
	v_mfma_f32_16x16x32_bf16 v[60:63], v[132:135], v[150:153], v[60:63]
	v_mfma_f32_16x16x32_bf16 v[56:59], v[140:143], v[150:153], v[56:59]
	v_mfma_f32_16x16x32_bf16 v[44:47], v[132:135], v[158:161], v[44:47]
	v_mfma_f32_16x16x32_bf16 v[40:43], v[140:143], v[158:161], v[40:43]
	v_mfma_f32_16x16x32_bf16 v[28:31], v[132:135], v[166:169], v[28:31]
	v_mfma_f32_16x16x32_bf16 v[24:27], v[140:143], v[166:169], v[24:27]
	v_mfma_f32_16x16x32_bf16 v[12:15], v[132:135], v[198:201], v[12:15]
	v_mfma_f32_16x16x32_bf16 v[8:11], v[140:143], v[198:201], v[8:11]
	s_barrier
	s_add_u32 s58, s78, s98
	s_addc_u32 s59, s79, 0
	s_add_i32 s27, s27, s84
	v_lshl_add_u64 v[238:239], s[58:59], 0, v[144:145]
	s_mov_b32 m0, s27
	v_lshl_add_u64 v[240:241], s[58:59], 0, v[188:189]
	global_load_lds_dwordx4 v[238:239], off
	s_add_i32 m0, s27, 0x2000
	s_nop 0
	global_load_lds_dwordx4 v[240:241], off
	s_waitcnt vmcnt(6)
	s_barrier
	v_mfma_f32_16x16x32_bf16 v[52:55], v[202:205], v[146:149], 0
	v_mfma_f32_16x16x32_bf16 v[48:51], v[222:225], v[146:149], 0
	v_mfma_f32_16x16x32_bf16 v[36:39], v[202:205], v[154:157], 0
	v_mfma_f32_16x16x32_bf16 v[32:35], v[222:225], v[154:157], 0
	v_mfma_f32_16x16x32_bf16 v[20:23], v[202:205], v[162:165], 0
	v_mfma_f32_16x16x32_bf16 v[16:19], v[222:225], v[162:165], 0
	v_mfma_f32_16x16x32_bf16 v[4:7], v[202:205], v[194:197], 0
	v_mfma_f32_16x16x32_bf16 v[0:3], v[222:225], v[194:197], 0
	v_mfma_f32_16x16x32_bf16 v[52:55], v[218:221], v[150:153], v[52:55]
	v_mfma_f32_16x16x32_bf16 v[48:51], v[228:231], v[150:153], v[48:51]
	v_mfma_f32_16x16x32_bf16 v[36:39], v[218:221], v[158:161], v[36:39]
	v_mfma_f32_16x16x32_bf16 v[32:35], v[228:231], v[158:161], v[32:35]
	v_mfma_f32_16x16x32_bf16 v[20:23], v[218:221], v[166:169], v[20:23]
	v_mfma_f32_16x16x32_bf16 v[16:19], v[228:231], v[166:169], v[16:19]
	v_mfma_f32_16x16x32_bf16 v[4:7], v[218:221], v[198:201], v[4:7]
	v_mfma_f32_16x16x32_bf16 v[0:3], v[228:231], v[198:201], v[0:3]
	s_barrier
	s_add_i32 s27, 0, 0x18000
	v_add_u32_e32 v140, s27, v207
	ds_read_b128 v[128:131], v140
	ds_read_b128 v[132:135], v140 offset:1024
	ds_read_b128 v[136:139], v140 offset:2048
	ds_read_b128 v[140:143], v140 offset:3072
	s_add_u32 s44, s44, s98
	s_addc_u32 s45, s45, 0
	s_mov_b32 m0, s87
	v_lshl_add_u64 v[202:203], s[44:45], 0, v[144:145]
	ds_read_b128 v[146:149], v217 offset:32768
	ds_read_b128 v[150:153], v217 offset:33792
	ds_read_b128 v[154:157], v217 offset:34816
	ds_read_b128 v[158:161], v217 offset:35840
	ds_read_b128 v[162:165], v217 offset:36864
	ds_read_b128 v[166:169], v217 offset:37888
	ds_read_b128 v[194:197], v217 offset:38912
	ds_read_b128 v[198:201], v217 offset:39936
	global_load_lds_dwordx4 v[202:203], off
	v_lshl_add_u64 v[202:203], s[44:45], 0, v[188:189]
	s_mov_b32 m0, s80
	s_nop 0
	global_load_lds_dwordx4 v[202:203], off
	s_waitcnt lgkmcnt(8)
	s_barrier
	s_waitcnt lgkmcnt(0)
	v_mfma_f32_16x16x32_bf16 v[124:127], v[128:131], v[146:149], v[124:127]
	v_mfma_f32_16x16x32_bf16 v[120:123], v[136:139], v[146:149], v[120:123]
	v_mfma_f32_16x16x32_bf16 v[108:111], v[128:131], v[154:157], v[108:111]
	v_mfma_f32_16x16x32_bf16 v[104:107], v[136:139], v[154:157], v[104:107]
	v_mfma_f32_16x16x32_bf16 v[92:95], v[128:131], v[162:165], v[92:95]
	v_mfma_f32_16x16x32_bf16 v[88:91], v[136:139], v[162:165], v[88:91]
	v_mfma_f32_16x16x32_bf16 v[76:79], v[128:131], v[194:197], v[76:79]
	v_mfma_f32_16x16x32_bf16 v[72:75], v[136:139], v[194:197], v[72:75]
	v_mfma_f32_16x16x32_bf16 v[124:127], v[132:135], v[150:153], v[124:127]
	v_mfma_f32_16x16x32_bf16 v[120:123], v[140:143], v[150:153], v[120:123]
	v_mfma_f32_16x16x32_bf16 v[108:111], v[132:135], v[158:161], v[108:111]
	v_mfma_f32_16x16x32_bf16 v[104:107], v[140:143], v[158:161], v[104:107]
	v_mfma_f32_16x16x32_bf16 v[92:95], v[132:135], v[166:169], v[92:95]
	v_mfma_f32_16x16x32_bf16 v[88:91], v[140:143], v[166:169], v[88:91]
	v_mfma_f32_16x16x32_bf16 v[76:79], v[132:135], v[198:201], v[76:79]
	v_mfma_f32_16x16x32_bf16 v[72:75], v[140:143], v[198:201], v[72:75]
	s_barrier
	s_add_i32 s44, 0, 0x1c000
	s_add_i32 s27, s27, s84
	v_add_u32_e32 v228, s44, v207
	v_lshl_add_u64 v[176:177], v[176:177], 0, s[18:19]
	s_mov_b32 m0, s27
	ds_read_b128 v[202:205], v228
	ds_read_b128 v[218:221], v228 offset:1024
	ds_read_b128 v[222:225], v228 offset:2048
	ds_read_b128 v[228:231], v228 offset:3072
	global_load_lds_dwordx4 v[176:177], off
	v_lshl_add_u64 v[176:177], v[232:233], 0, s[18:19]
	s_add_i32 m0, s27, 0x2000
	s_nop 0
	global_load_lds_dwordx4 v[176:177], off
	s_barrier
	s_waitcnt lgkmcnt(0)
	v_mfma_f32_16x16x32_bf16 v[116:119], v[202:205], v[146:149], v[116:119]
	v_mfma_f32_16x16x32_bf16 v[112:115], v[222:225], v[146:149], v[112:115]
	v_mfma_f32_16x16x32_bf16 v[100:103], v[202:205], v[154:157], v[100:103]
	v_mfma_f32_16x16x32_bf16 v[96:99], v[222:225], v[154:157], v[96:99]
	v_mfma_f32_16x16x32_bf16 v[84:87], v[202:205], v[162:165], v[84:87]
	v_mfma_f32_16x16x32_bf16 v[80:83], v[222:225], v[162:165], v[80:83]
	v_mfma_f32_16x16x32_bf16 v[68:71], v[202:205], v[194:197], v[68:71]
	v_mfma_f32_16x16x32_bf16 v[64:67], v[222:225], v[194:197], v[64:67]
	v_mfma_f32_16x16x32_bf16 v[116:119], v[218:221], v[150:153], v[116:119]
	v_mfma_f32_16x16x32_bf16 v[112:115], v[228:231], v[150:153], v[112:115]
	v_mfma_f32_16x16x32_bf16 v[100:103], v[218:221], v[158:161], v[100:103]
	v_mfma_f32_16x16x32_bf16 v[96:99], v[228:231], v[158:161], v[96:99]
	v_mfma_f32_16x16x32_bf16 v[84:87], v[218:221], v[166:169], v[84:87]
	v_mfma_f32_16x16x32_bf16 v[80:83], v[228:231], v[166:169], v[80:83]
	v_mfma_f32_16x16x32_bf16 v[68:71], v[218:221], v[198:201], v[68:71]
	v_mfma_f32_16x16x32_bf16 v[64:67], v[228:231], v[198:201], v[64:67]
	s_barrier
	s_mov_b32 m0, s30
	v_lshl_add_u64 v[176:177], v[234:235], 0, s[18:19]
	ds_read_b128 v[146:149], v217 offset:49152
	ds_read_b128 v[150:153], v217 offset:50176
	ds_read_b128 v[154:157], v217 offset:51200
	ds_read_b128 v[158:161], v217 offset:52224
	ds_read_b128 v[162:165], v217 offset:53248
	ds_read_b128 v[166:169], v217 offset:54272
	ds_read_b128 v[194:197], v217 offset:55296
	ds_read_b128 v[198:201], v217 offset:56320
	global_load_lds_dwordx4 v[176:177], off
	v_lshl_add_u64 v[176:177], v[236:237], 0, s[18:19]
	s_mov_b32 m0, s31
	s_nop 0
	global_load_lds_dwordx4 v[176:177], off
	s_barrier
	s_waitcnt lgkmcnt(0)
	v_mfma_f32_16x16x32_bf16 v[60:63], v[128:131], v[146:149], v[60:63]
	v_mfma_f32_16x16x32_bf16 v[56:59], v[136:139], v[146:149], v[56:59]
	v_mfma_f32_16x16x32_bf16 v[44:47], v[128:131], v[154:157], v[44:47]
	v_mfma_f32_16x16x32_bf16 v[40:43], v[136:139], v[154:157], v[40:43]
	v_mfma_f32_16x16x32_bf16 v[28:31], v[128:131], v[162:165], v[28:31]
	v_mfma_f32_16x16x32_bf16 v[24:27], v[136:139], v[162:165], v[24:27]
	v_mfma_f32_16x16x32_bf16 v[12:15], v[128:131], v[194:197], v[12:15]
	v_mfma_f32_16x16x32_bf16 v[8:11], v[136:139], v[194:197], v[8:11]
	v_mfma_f32_16x16x32_bf16 v[60:63], v[132:135], v[150:153], v[60:63]
	v_mfma_f32_16x16x32_bf16 v[56:59], v[140:143], v[150:153], v[56:59]
	v_mfma_f32_16x16x32_bf16 v[44:47], v[132:135], v[158:161], v[44:47]
	v_mfma_f32_16x16x32_bf16 v[40:43], v[140:143], v[158:161], v[40:43]
	v_mfma_f32_16x16x32_bf16 v[28:31], v[132:135], v[166:169], v[28:31]
	v_mfma_f32_16x16x32_bf16 v[24:27], v[140:143], v[166:169], v[24:27]
	v_mfma_f32_16x16x32_bf16 v[12:15], v[132:135], v[198:201], v[12:15]
	v_mfma_f32_16x16x32_bf16 v[8:11], v[140:143], v[198:201], v[8:11]
	s_barrier
	s_add_i32 s27, s44, s84
	v_lshl_add_u64 v[128:129], v[238:239], 0, s[18:19]
	s_mov_b32 m0, s27
	s_nop 0
	global_load_lds_dwordx4 v[128:129], off
	v_lshl_add_u64 v[128:129], v[240:241], 0, s[18:19]
	s_add_i32 m0, s27, 0x2000
	s_nop 0
	global_load_lds_dwordx4 v[128:129], off
	s_waitcnt vmcnt(6)
	s_barrier
	v_mfma_f32_16x16x32_bf16 v[52:55], v[202:205], v[146:149], v[52:55]
	v_mfma_f32_16x16x32_bf16 v[48:51], v[222:225], v[146:149], v[48:51]
	v_mfma_f32_16x16x32_bf16 v[36:39], v[202:205], v[154:157], v[36:39]
	v_mfma_f32_16x16x32_bf16 v[32:35], v[222:225], v[154:157], v[32:35]
	v_mfma_f32_16x16x32_bf16 v[20:23], v[202:205], v[162:165], v[20:23]
	v_mfma_f32_16x16x32_bf16 v[16:19], v[222:225], v[162:165], v[16:19]
	v_mfma_f32_16x16x32_bf16 v[4:7], v[202:205], v[194:197], v[4:7]
	v_mfma_f32_16x16x32_bf16 v[0:3], v[222:225], v[194:197], v[0:3]
	v_mfma_f32_16x16x32_bf16 v[52:55], v[218:221], v[150:153], v[52:55]
	v_mfma_f32_16x16x32_bf16 v[48:51], v[228:231], v[150:153], v[48:51]
	v_mfma_f32_16x16x32_bf16 v[36:39], v[218:221], v[158:161], v[36:39]
	v_mfma_f32_16x16x32_bf16 v[32:35], v[228:231], v[158:161], v[32:35]
	v_mfma_f32_16x16x32_bf16 v[20:23], v[218:221], v[166:169], v[20:23]
	v_mfma_f32_16x16x32_bf16 v[16:19], v[228:231], v[166:169], v[16:19]
	v_mfma_f32_16x16x32_bf16 v[4:7], v[218:221], v[198:201], v[4:7]
	v_mfma_f32_16x16x32_bf16 v[0:3], v[228:231], v[198:201], v[0:3]
	s_barrier
	s_add_u32 s42, s42, 0x100
	s_addc_u32 s43, s43, 0
	s_add_u32 s33, s33, 0x100
	s_addc_u32 s37, s37, 0
	s_cmp_ge_u32 s56, s34
	s_mov_b32 s27, s56
.LBB0_196:
	s_add_i32 s56, s27, 2
	s_add_u32 s44, s42, 0x80
	s_addc_u32 s45, s43, 0
	s_add_i32 s57, 0, 0x10000
	v_add_u32_e32 v140, s57, v207
	ds_read_b128 v[128:131], v140
	ds_read_b128 v[132:135], v140 offset:1024
	ds_read_b128 v[136:139], v140 offset:2048
	ds_read_b128 v[140:143], v140 offset:3072
	s_cmp_eq_u32 s82, s27
	s_cselect_b32 s45, s77, s45
	s_cselect_b32 s44, s76, s44
	s_cselect_b32 s79, s1, s37
	s_cselect_b32 s78, s0, s33
	v_lshl_add_u64 v[176:177], s[42:43], 0, v[190:191]
	s_add_i32 m0, s85, 0xc000
	ds_read_b128 v[146:149], v217
	ds_read_b128 v[150:153], v217 offset:1024
	ds_read_b128 v[154:157], v217 offset:2048
	ds_read_b128 v[158:161], v217 offset:3072
	ds_read_b128 v[162:165], v217 offset:4096
	ds_read_b128 v[166:169], v217 offset:5120
	ds_read_b128 v[194:197], v217 offset:6144
	ds_read_b128 v[198:201], v217 offset:7168
	global_load_lds_dwordx4 v[176:177], off
	v_lshl_add_u64 v[176:177], s[42:43], 0, v[192:193]
	s_add_i32 m0, s85, 0xe000
	s_nop 0
	global_load_lds_dwordx4 v[176:177], off
	s_waitcnt lgkmcnt(8)
	s_barrier
	s_waitcnt lgkmcnt(0)
	v_mfma_f32_16x16x32_bf16 v[124:127], v[128:131], v[146:149], v[124:127]
	v_mfma_f32_16x16x32_bf16 v[120:123], v[136:139], v[146:149], v[120:123]
	v_mfma_f32_16x16x32_bf16 v[108:111], v[128:131], v[154:157], v[108:111]
	v_mfma_f32_16x16x32_bf16 v[104:107], v[136:139], v[154:157], v[104:107]
	v_mfma_f32_16x16x32_bf16 v[92:95], v[128:131], v[162:165], v[92:95]
	v_mfma_f32_16x16x32_bf16 v[88:91], v[136:139], v[162:165], v[88:91]
	v_mfma_f32_16x16x32_bf16 v[76:79], v[128:131], v[194:197], v[76:79]
	v_mfma_f32_16x16x32_bf16 v[72:75], v[136:139], v[194:197], v[72:75]
	v_mfma_f32_16x16x32_bf16 v[124:127], v[132:135], v[150:153], v[124:127]
	v_mfma_f32_16x16x32_bf16 v[120:123], v[140:143], v[150:153], v[120:123]
	v_mfma_f32_16x16x32_bf16 v[108:111], v[132:135], v[158:161], v[108:111]
	v_mfma_f32_16x16x32_bf16 v[104:107], v[140:143], v[158:161], v[104:107]
	v_mfma_f32_16x16x32_bf16 v[92:95], v[132:135], v[166:169], v[92:95]
	v_mfma_f32_16x16x32_bf16 v[88:91], v[140:143], v[166:169], v[88:91]
	v_mfma_f32_16x16x32_bf16 v[76:79], v[132:135], v[198:201], v[76:79]
	v_mfma_f32_16x16x32_bf16 v[72:75], v[140:143], v[198:201], v[72:75]
	s_barrier
	s_add_i32 s27, 0, 0x14000
	v_add_u32_e32 v176, s27, v207
	s_add_i32 s57, s57, s84
	ds_read_b128 v[202:205], v176
	ds_read_b128 v[218:221], v176 offset:1024
	ds_read_b128 v[222:225], v176 offset:2048
	ds_read_b128 v[228:231], v176 offset:3072
	v_lshl_add_u64 v[176:177], s[78:79], 0, v[144:145]
	s_mov_b32 m0, s57
	v_lshl_add_u64 v[232:233], s[78:79], 0, v[188:189]
	global_load_lds_dwordx4 v[176:177], off
	s_add_i32 m0, s57, 0x2000
	s_nop 0
	global_load_lds_dwordx4 v[232:233], off
	s_barrier
	s_waitcnt lgkmcnt(0)
	v_mfma_f32_16x16x32_bf16 v[116:119], v[202:205], v[146:149], v[116:119]
	v_mfma_f32_16x16x32_bf16 v[112:115], v[222:225], v[146:149], v[112:115]
	v_mfma_f32_16x16x32_bf16 v[100:103], v[202:205], v[154:157], v[100:103]
	v_mfma_f32_16x16x32_bf16 v[96:99], v[222:225], v[154:157], v[96:99]
	v_mfma_f32_16x16x32_bf16 v[84:87], v[202:205], v[162:165], v[84:87]
	v_mfma_f32_16x16x32_bf16 v[80:83], v[222:225], v[162:165], v[80:83]
	v_mfma_f32_16x16x32_bf16 v[68:71], v[202:205], v[194:197], v[68:71]
	v_mfma_f32_16x16x32_bf16 v[64:67], v[222:225], v[194:197], v[64:67]
	v_mfma_f32_16x16x32_bf16 v[116:119], v[218:221], v[150:153], v[116:119]
	v_mfma_f32_16x16x32_bf16 v[112:115], v[228:231], v[150:153], v[112:115]
	v_mfma_f32_16x16x32_bf16 v[100:103], v[218:221], v[158:161], v[100:103]
	v_mfma_f32_16x16x32_bf16 v[96:99], v[228:231], v[158:161], v[96:99]
	v_mfma_f32_16x16x32_bf16 v[84:87], v[218:221], v[166:169], v[84:87]
	v_mfma_f32_16x16x32_bf16 v[80:83], v[228:231], v[166:169], v[80:83]
	v_mfma_f32_16x16x32_bf16 v[68:71], v[218:221], v[198:201], v[68:71]
	v_mfma_f32_16x16x32_bf16 v[64:67], v[228:231], v[198:201], v[64:67]
	s_barrier
	s_mov_b32 m0, s85
	v_lshl_add_u64 v[234:235], s[44:45], 0, v[144:145]
	ds_read_b128 v[146:149], v217 offset:16384
	ds_read_b128 v[150:153], v217 offset:17408
	ds_read_b128 v[154:157], v217 offset:18432
	ds_read_b128 v[158:161], v217 offset:19456
	ds_read_b128 v[162:165], v217 offset:20480
	ds_read_b128 v[166:169], v217 offset:21504
	ds_read_b128 v[194:197], v217 offset:22528
	ds_read_b128 v[198:201], v217 offset:23552
	global_load_lds_dwordx4 v[234:235], off
	v_lshl_add_u64 v[236:237], s[44:45], 0, v[188:189]
	s_mov_b32 m0, s86
	s_nop 0
	global_load_lds_dwordx4 v[236:237], off
	s_barrier
	s_waitcnt lgkmcnt(0)
	v_mfma_f32_16x16x32_bf16 v[60:63], v[128:131], v[146:149], v[60:63]
	v_mfma_f32_16x16x32_bf16 v[56:59], v[136:139], v[146:149], v[56:59]
	v_mfma_f32_16x16x32_bf16 v[44:47], v[128:131], v[154:157], v[44:47]
	v_mfma_f32_16x16x32_bf16 v[40:43], v[136:139], v[154:157], v[40:43]
	v_mfma_f32_16x16x32_bf16 v[28:31], v[128:131], v[162:165], v[28:31]
	v_mfma_f32_16x16x32_bf16 v[24:27], v[136:139], v[162:165], v[24:27]
	v_mfma_f32_16x16x32_bf16 v[12:15], v[128:131], v[194:197], v[12:15]
	v_mfma_f32_16x16x32_bf16 v[8:11], v[136:139], v[194:197], v[8:11]
	v_mfma_f32_16x16x32_bf16 v[60:63], v[132:135], v[150:153], v[60:63]
	v_mfma_f32_16x16x32_bf16 v[56:59], v[140:143], v[150:153], v[56:59]
	v_mfma_f32_16x16x32_bf16 v[44:47], v[132:135], v[158:161], v[44:47]
	v_mfma_f32_16x16x32_bf16 v[40:43], v[140:143], v[158:161], v[40:43]
	v_mfma_f32_16x16x32_bf16 v[28:31], v[132:135], v[166:169], v[28:31]
	v_mfma_f32_16x16x32_bf16 v[24:27], v[140:143], v[166:169], v[24:27]
	v_mfma_f32_16x16x32_bf16 v[12:15], v[132:135], v[198:201], v[12:15]
	v_mfma_f32_16x16x32_bf16 v[8:11], v[140:143], v[198:201], v[8:11]
	s_barrier
	s_add_u32 s58, s78, s98
	s_addc_u32 s59, s79, 0
	s_add_i32 s27, s27, s84
	v_lshl_add_u64 v[238:239], s[58:59], 0, v[144:145]
	s_mov_b32 m0, s27
	v_lshl_add_u64 v[240:241], s[58:59], 0, v[188:189]
	global_load_lds_dwordx4 v[238:239], off
	s_add_i32 m0, s27, 0x2000
	s_nop 0
	global_load_lds_dwordx4 v[240:241], off
	s_waitcnt vmcnt(6)
	s_barrier
	v_mfma_f32_16x16x32_bf16 v[52:55], v[202:205], v[146:149], v[52:55]
	v_mfma_f32_16x16x32_bf16 v[48:51], v[222:225], v[146:149], v[48:51]
	v_mfma_f32_16x16x32_bf16 v[36:39], v[202:205], v[154:157], v[36:39]
	v_mfma_f32_16x16x32_bf16 v[32:35], v[222:225], v[154:157], v[32:35]
	v_mfma_f32_16x16x32_bf16 v[20:23], v[202:205], v[162:165], v[20:23]
	v_mfma_f32_16x16x32_bf16 v[16:19], v[222:225], v[162:165], v[16:19]
	v_mfma_f32_16x16x32_bf16 v[4:7], v[202:205], v[194:197], v[4:7]
	v_mfma_f32_16x16x32_bf16 v[0:3], v[222:225], v[194:197], v[0:3]
	v_mfma_f32_16x16x32_bf16 v[52:55], v[218:221], v[150:153], v[52:55]
	v_mfma_f32_16x16x32_bf16 v[48:51], v[228:231], v[150:153], v[48:51]
	v_mfma_f32_16x16x32_bf16 v[36:39], v[218:221], v[158:161], v[36:39]
	v_mfma_f32_16x16x32_bf16 v[32:35], v[228:231], v[158:161], v[32:35]
	v_mfma_f32_16x16x32_bf16 v[20:23], v[218:221], v[166:169], v[20:23]
	v_mfma_f32_16x16x32_bf16 v[16:19], v[228:231], v[166:169], v[16:19]
	v_mfma_f32_16x16x32_bf16 v[4:7], v[218:221], v[198:201], v[4:7]
	v_mfma_f32_16x16x32_bf16 v[0:3], v[228:231], v[198:201], v[0:3]
	s_barrier
	s_add_i32 s27, 0, 0x18000
	v_add_u32_e32 v140, s27, v207
	ds_read_b128 v[128:131], v140
	ds_read_b128 v[132:135], v140 offset:1024
	ds_read_b128 v[136:139], v140 offset:2048
	ds_read_b128 v[140:143], v140 offset:3072
	s_add_u32 s44, s44, s98
	s_addc_u32 s45, s45, 0
	s_mov_b32 m0, s87
	v_lshl_add_u64 v[202:203], s[44:45], 0, v[144:145]
	ds_read_b128 v[146:149], v217 offset:32768
	ds_read_b128 v[150:153], v217 offset:33792
	ds_read_b128 v[154:157], v217 offset:34816
	ds_read_b128 v[158:161], v217 offset:35840
	ds_read_b128 v[162:165], v217 offset:36864
	ds_read_b128 v[166:169], v217 offset:37888
	ds_read_b128 v[194:197], v217 offset:38912
	ds_read_b128 v[198:201], v217 offset:39936
	global_load_lds_dwordx4 v[202:203], off
	v_lshl_add_u64 v[202:203], s[44:45], 0, v[188:189]
	s_mov_b32 m0, s80
	s_nop 0
	global_load_lds_dwordx4 v[202:203], off
	s_waitcnt lgkmcnt(8)
	s_barrier
	s_waitcnt lgkmcnt(0)
	v_mfma_f32_16x16x32_bf16 v[124:127], v[128:131], v[146:149], v[124:127]
	v_mfma_f32_16x16x32_bf16 v[120:123], v[136:139], v[146:149], v[120:123]
	v_mfma_f32_16x16x32_bf16 v[108:111], v[128:131], v[154:157], v[108:111]
	v_mfma_f32_16x16x32_bf16 v[104:107], v[136:139], v[154:157], v[104:107]
	v_mfma_f32_16x16x32_bf16 v[92:95], v[128:131], v[162:165], v[92:95]
	v_mfma_f32_16x16x32_bf16 v[88:91], v[136:139], v[162:165], v[88:91]
	v_mfma_f32_16x16x32_bf16 v[76:79], v[128:131], v[194:197], v[76:79]
	v_mfma_f32_16x16x32_bf16 v[72:75], v[136:139], v[194:197], v[72:75]
	v_mfma_f32_16x16x32_bf16 v[124:127], v[132:135], v[150:153], v[124:127]
	v_mfma_f32_16x16x32_bf16 v[120:123], v[140:143], v[150:153], v[120:123]
	v_mfma_f32_16x16x32_bf16 v[108:111], v[132:135], v[158:161], v[108:111]
	v_mfma_f32_16x16x32_bf16 v[104:107], v[140:143], v[158:161], v[104:107]
	v_mfma_f32_16x16x32_bf16 v[92:95], v[132:135], v[166:169], v[92:95]
	v_mfma_f32_16x16x32_bf16 v[88:91], v[140:143], v[166:169], v[88:91]
	v_mfma_f32_16x16x32_bf16 v[76:79], v[132:135], v[198:201], v[76:79]
	v_mfma_f32_16x16x32_bf16 v[72:75], v[140:143], v[198:201], v[72:75]
	s_barrier
	s_add_i32 s44, 0, 0x1c000
	s_add_i32 s27, s27, s84
	v_add_u32_e32 v228, s44, v207
	v_lshl_add_u64 v[176:177], v[176:177], 0, s[18:19]
	s_mov_b32 m0, s27
	ds_read_b128 v[202:205], v228
	ds_read_b128 v[218:221], v228 offset:1024
	ds_read_b128 v[222:225], v228 offset:2048
	ds_read_b128 v[228:231], v228 offset:3072
	global_load_lds_dwordx4 v[176:177], off
	v_lshl_add_u64 v[176:177], v[232:233], 0, s[18:19]
	s_add_i32 m0, s27, 0x2000
	s_nop 0
	global_load_lds_dwordx4 v[176:177], off
	s_barrier
	s_waitcnt lgkmcnt(0)
	v_mfma_f32_16x16x32_bf16 v[116:119], v[202:205], v[146:149], v[116:119]
	v_mfma_f32_16x16x32_bf16 v[112:115], v[222:225], v[146:149], v[112:115]
	v_mfma_f32_16x16x32_bf16 v[100:103], v[202:205], v[154:157], v[100:103]
	v_mfma_f32_16x16x32_bf16 v[96:99], v[222:225], v[154:157], v[96:99]
	v_mfma_f32_16x16x32_bf16 v[84:87], v[202:205], v[162:165], v[84:87]
	v_mfma_f32_16x16x32_bf16 v[80:83], v[222:225], v[162:165], v[80:83]
	v_mfma_f32_16x16x32_bf16 v[68:71], v[202:205], v[194:197], v[68:71]
	v_mfma_f32_16x16x32_bf16 v[64:67], v[222:225], v[194:197], v[64:67]
	v_mfma_f32_16x16x32_bf16 v[116:119], v[218:221], v[150:153], v[116:119]
	v_mfma_f32_16x16x32_bf16 v[112:115], v[228:231], v[150:153], v[112:115]
	v_mfma_f32_16x16x32_bf16 v[100:103], v[218:221], v[158:161], v[100:103]
	v_mfma_f32_16x16x32_bf16 v[96:99], v[228:231], v[158:161], v[96:99]
	v_mfma_f32_16x16x32_bf16 v[84:87], v[218:221], v[166:169], v[84:87]
	v_mfma_f32_16x16x32_bf16 v[80:83], v[228:231], v[166:169], v[80:83]
	v_mfma_f32_16x16x32_bf16 v[68:71], v[218:221], v[198:201], v[68:71]
	v_mfma_f32_16x16x32_bf16 v[64:67], v[228:231], v[198:201], v[64:67]
	s_barrier
	s_mov_b32 m0, s30
	v_lshl_add_u64 v[176:177], v[234:235], 0, s[18:19]
	ds_read_b128 v[146:149], v217 offset:49152
	ds_read_b128 v[150:153], v217 offset:50176
	ds_read_b128 v[154:157], v217 offset:51200
	ds_read_b128 v[158:161], v217 offset:52224
	ds_read_b128 v[162:165], v217 offset:53248
	ds_read_b128 v[166:169], v217 offset:54272
	ds_read_b128 v[194:197], v217 offset:55296
	ds_read_b128 v[198:201], v217 offset:56320
	global_load_lds_dwordx4 v[176:177], off
	v_lshl_add_u64 v[176:177], v[236:237], 0, s[18:19]
	s_mov_b32 m0, s31
	s_nop 0
	global_load_lds_dwordx4 v[176:177], off
	s_barrier
	s_waitcnt lgkmcnt(0)
	v_mfma_f32_16x16x32_bf16 v[60:63], v[128:131], v[146:149], v[60:63]
	v_mfma_f32_16x16x32_bf16 v[56:59], v[136:139], v[146:149], v[56:59]
	v_mfma_f32_16x16x32_bf16 v[44:47], v[128:131], v[154:157], v[44:47]
	v_mfma_f32_16x16x32_bf16 v[40:43], v[136:139], v[154:157], v[40:43]
	v_mfma_f32_16x16x32_bf16 v[28:31], v[128:131], v[162:165], v[28:31]
	v_mfma_f32_16x16x32_bf16 v[24:27], v[136:139], v[162:165], v[24:27]
	v_mfma_f32_16x16x32_bf16 v[12:15], v[128:131], v[194:197], v[12:15]
	v_mfma_f32_16x16x32_bf16 v[8:11], v[136:139], v[194:197], v[8:11]
	v_mfma_f32_16x16x32_bf16 v[60:63], v[132:135], v[150:153], v[60:63]
	v_mfma_f32_16x16x32_bf16 v[56:59], v[140:143], v[150:153], v[56:59]
	v_mfma_f32_16x16x32_bf16 v[44:47], v[132:135], v[158:161], v[44:47]
	v_mfma_f32_16x16x32_bf16 v[40:43], v[140:143], v[158:161], v[40:43]
	v_mfma_f32_16x16x32_bf16 v[28:31], v[132:135], v[166:169], v[28:31]
	v_mfma_f32_16x16x32_bf16 v[24:27], v[140:143], v[166:169], v[24:27]
	v_mfma_f32_16x16x32_bf16 v[12:15], v[132:135], v[198:201], v[12:15]
	v_mfma_f32_16x16x32_bf16 v[8:11], v[140:143], v[198:201], v[8:11]
	s_barrier
	s_add_i32 s27, s44, s84
	v_lshl_add_u64 v[128:129], v[238:239], 0, s[18:19]
	s_mov_b32 m0, s27
	s_nop 0
	global_load_lds_dwordx4 v[128:129], off
	v_lshl_add_u64 v[128:129], v[240:241], 0, s[18:19]
	s_add_i32 m0, s27, 0x2000
	s_nop 0
	global_load_lds_dwordx4 v[128:129], off
	s_waitcnt vmcnt(6)
	s_barrier
	v_mfma_f32_16x16x32_bf16 v[52:55], v[202:205], v[146:149], v[52:55]
	v_mfma_f32_16x16x32_bf16 v[48:51], v[222:225], v[146:149], v[48:51]
	v_mfma_f32_16x16x32_bf16 v[36:39], v[202:205], v[154:157], v[36:39]
	v_mfma_f32_16x16x32_bf16 v[32:35], v[222:225], v[154:157], v[32:35]
	v_mfma_f32_16x16x32_bf16 v[20:23], v[202:205], v[162:165], v[20:23]
	v_mfma_f32_16x16x32_bf16 v[16:19], v[222:225], v[162:165], v[16:19]
	v_mfma_f32_16x16x32_bf16 v[4:7], v[202:205], v[194:197], v[4:7]
	v_mfma_f32_16x16x32_bf16 v[0:3], v[222:225], v[194:197], v[0:3]
	v_mfma_f32_16x16x32_bf16 v[52:55], v[218:221], v[150:153], v[52:55]
	v_mfma_f32_16x16x32_bf16 v[48:51], v[228:231], v[150:153], v[48:51]
	v_mfma_f32_16x16x32_bf16 v[36:39], v[218:221], v[158:161], v[36:39]
	v_mfma_f32_16x16x32_bf16 v[32:35], v[228:231], v[158:161], v[32:35]
	v_mfma_f32_16x16x32_bf16 v[20:23], v[218:221], v[166:169], v[20:23]
	v_mfma_f32_16x16x32_bf16 v[16:19], v[228:231], v[166:169], v[16:19]
	v_mfma_f32_16x16x32_bf16 v[4:7], v[218:221], v[198:201], v[4:7]
	v_mfma_f32_16x16x32_bf16 v[0:3], v[228:231], v[198:201], v[0:3]
	s_barrier
	s_add_u32 s42, s42, 0x100
	s_addc_u32 s43, s43, 0
	s_add_u32 s33, s33, 0x100
	s_addc_u32 s37, s37, 0
	s_cmp_ge_u32 s56, s34
	s_mov_b32 s27, s56
	s_cbranch_scc0 .LBB0_196
	v_lshl_add_u32 v194, s11, 8, v206
	v_ashrrev_i32_e32 v195, 31, v194
	v_lshl_or_b32 v196, s10, 8, v216
	v_lshlrev_b64 v[128:129], 11, v[194:195]
	v_ashrrev_i32_e32 v197, 31, v196
	s_and_b64 vcc, exec, s[92:93]
	v_or_b32_e32 v198, 16, v194
	v_lshl_add_u64 v[200:201], s[54:55], 0, v[128:129]
	s_cbranch_vccz .LBB0_215
	v_lshlrev_b64 v[128:129], 12, v[194:195]
	v_lshl_add_u64 v[128:129], s[50:51], 0, v[128:129]
	v_lshlrev_b64 v[130:131], 2, v[196:197]
	v_lshl_add_u64 v[128:129], v[128:129], 0, v[130:131]
	global_load_dwordx4 v[146:149], v[128:129], off offset:16
	global_load_dwordx4 v[150:153], v[128:129], off
	global_load_dwordx4 v[154:157], v[128:129], off offset:528
	global_load_dwordx4 v[158:161], v[128:129], off offset:512
	v_ashrrev_i32_e32 v199, 31, v198
	v_lshlrev_b64 v[128:129], 12, v[198:199]
	v_lshl_add_u64 v[128:129], s[50:51], 0, v[128:129]
	v_lshl_add_u64 v[132:133], v[128:129], 0, v[130:131]
	global_load_dwordx4 v[136:139], v[132:133], off offset:16
	global_load_dwordx4 v[140:143], v[132:133], off
	global_load_dwordx4 v[128:131], v[132:133], off offset:528
	s_nop 0
	global_load_dwordx4 v[132:135], v[132:133], off offset:512
	v_lshl_add_u64 v[166:167], v[196:197], 1, v[200:201]
	s_waitcnt vmcnt(0)
	v_pk_add_f32 v[164:165], v[120:121], v[146:147]
	v_pk_add_f32 v[152:153], v[126:127], v[152:153]
	v_pk_add_f32 v[150:151], v[124:125], v[150:151]
	v_pk_add_f32 v[162:163], v[122:123], v[148:149]
	v_cvt_pk_bf16_f32 v146, v150, v151
	v_cvt_pk_bf16_f32 v147, v152, v153
	v_cvt_pk_bf16_f32 v148, v164, v165
	v_pk_add_f32 v[156:157], v[114:115], v[156:157]
	v_cvt_pk_bf16_f32 v149, v162, v163
	global_store_dwordx4 v[166:167], v[146:149], off
	v_pk_add_f32 v[154:155], v[112:113], v[154:155]
	s_nop 0
	v_mul_f32_e32 v146, v151, v151
	v_mul_f32_e32 v147, v153, v153
	v_fmac_f32_e32 v146, v150, v150
	v_fmac_f32_e32 v147, v152, v152
	v_add_f32_e32 v146, v146, v147
	v_mul_f32_e32 v147, v165, v165
	v_mul_f32_e32 v148, v163, v163
	v_fmac_f32_e32 v147, v164, v164
	v_fmac_f32_e32 v148, v162, v162
	v_add_f32_e32 v147, v147, v148
	v_add_f32_e32 v162, v146, v147
	v_pk_add_f32 v[150:151], v[118:119], v[160:161]
	v_pk_add_f32 v[152:153], v[116:117], v[158:159]
	s_nop 0
	v_cvt_pk_bf16_f32 v146, v152, v153
	v_cvt_pk_bf16_f32 v147, v150, v151
	v_cvt_pk_bf16_f32 v148, v154, v155
	v_cvt_pk_bf16_f32 v149, v156, v157
	global_store_dwordx4 v[166:167], v[146:149], off offset:256
	s_nop 1
	v_mul_f32_e32 v146, v153, v153
	v_mul_f32_e32 v147, v151, v151
	v_fmac_f32_e32 v146, v152, v152
	v_fmac_f32_e32 v147, v150, v150
	v_add_f32_e32 v146, v146, v147
	v_mul_f32_e32 v147, v155, v155
	v_mul_f32_e32 v148, v157, v157
	v_fmac_f32_e32 v147, v154, v154
	v_fmac_f32_e32 v148, v156, v156
	v_add_f32_e32 v147, v147, v148
	v_and_b32_e32 v148, 64, v214
	v_add_f32_e32 v146, v146, v147
	v_xor_b32_e32 v147, 16, v214
	v_add_u32_e32 v148, 64, v148
	v_cmp_lt_i32_e32 vcc, v147, v148
	v_add_f32_e32 v146, v162, v146
	s_nop 0
	v_cndmask_b32_e32 v147, v214, v147, vcc
	v_lshlrev_b32_e32 v218, 2, v147
	ds_bpermute_b32 v147, v218, v146
	s_waitcnt lgkmcnt(0)
	v_add_f32_e32 v146, v146, v147
	v_xor_b32_e32 v147, 32, v214
	v_cmp_lt_i32_e32 vcc, v147, v148
	s_nop 1
	v_cndmask_b32_e32 v147, v214, v147, vcc
	v_lshlrev_b32_e32 v219, 2, v147
	ds_bpermute_b32 v147, v219, v146
	s_and_saveexec_b64 s[42:43], s[38:39]
	s_cbranch_execz .LBB0_200
	s_waitcnt lgkmcnt(0)
	v_add_f32_e32 v146, v146, v147
	v_fma_f32 v146, v146, s91, 0.5
	v_trunc_f32_e32 v146, v146
	v_mul_f32_e32 v147, 0x2f800000, v146
	v_floor_f32_e32 v147, v147
	v_fmac_f32_e32 v146, 0xcf800000, v147
	v_cvt_u32_f32_e32 v146, v146
	v_cvt_u32_f32_e32 v147, v147
	v_lshl_add_u64 v[148:149], v[194:195], 3, s[52:53]
	global_atomic_add_x2 v[148:149], v[146:147], off

.LBB0_311:
	s_setprio 0
	s_waitcnt vmcnt(0)
	v_readlane_b32 s92, v254, 39
	v_readlane_b32 s94, v254, 41
	s_cmpk_gt_u32 s49, 0xff
	v_readlane_b32 s93, v254, 40
	v_readlane_b32 s95, v254, 42
	s_cbranch_scc1 .LBB0_313
	s_barrier

.LBB0_321:
	v_readlane_b32 s1, v252, 32
	s_add_u32 s1, s1, s27
	v_readlane_b32 s8, v252, 33
	s_addc_u32 s10, s8, s10
	v_writelane_b32 v254, s36, 58
	s_lshl_b64 s[30:31], s[36:37], 22
	s_sub_u32 s27, 0, s30
	v_writelane_b32 v254, s37, 59
	s_subb_u32 s33, 0, s31
	s_add_u32 s96, s1, s27
	v_readlane_b32 s8, v254, 52
	s_addc_u32 s97, s10, s33
	s_lshl_b32 s30, s8, 6
	s_and_b32 s1, s25, 3
	s_add_i32 m0, s83, 0x18000
	v_lshl_add_u64 v[6:7], v[6:7], 0, s[18:19]
	s_ashr_i32 s31, s30, 31
	s_lshl_b32 s25, s11, 13
	s_lshl_b32 s36, s1, 12
	s_waitcnt vmcnt(4)
	s_barrier
	global_load_lds_dwordx4 v[6:7], off
	v_lshl_add_u64 v[4:5], v[4:5], 0, s[18:19]
	s_add_i32 m0, s83, 0x1a000
	s_add_i32 s87, s83, 0x8000
	s_add_i32 s79, s83, 0xa000
	global_load_lds_dwordx4 v[4:5], off
	v_lshl_add_u64 v[2:3], v[2:3], 0, s[18:19]
	s_mov_b32 m0, s87
	s_add_u32 s34, s72, 0x40080
	global_load_lds_dwordx4 v[2:3], off
	v_lshl_add_u64 v[0:1], v[0:1], 0, s[18:19]
	s_mov_b32 m0, s79
	s_addc_u32 s35, s73, 0
	global_load_lds_dwordx4 v[0:1], off
	s_add_i32 m0, s83, 0x1c000
	v_lshl_add_u64 v[0:1], s[34:35], 0, v[148:149]
	global_load_lds_dwordx4 v[0:1], off
	v_lshl_add_u64 v[0:1], s[34:35], 0, v[146:147]
	s_add_i32 m0, s83, 0x1e000
	v_readlane_b32 s9, v254, 53
	global_load_lds_dwordx4 v[0:1], off
	v_lshrrev_b32_e32 v0, 1, v9
	v_and_b32_e32 v0, 24, v0
	v_and_b32_e32 v1, 15, v9
	v_lshlrev_b32_e32 v2, 1, v0
	v_lshl_or_b32 v151, s11, 6, v1
	v_lshl_or_b32 v1, v1, 6, v2
	v_lshlrev_b32_e32 v2, 2, v9
	v_and_b32_e32 v2, 32, v2
	v_bitop3_b32 v3, v1, s25, v2 bitop3:0xde
	v_bitop3_b32 v216, v1, s36, v2 bitop3:0xde
	v_lshlrev_b32_e32 v1, 14, v12
	v_and_b32_e32 v1, 0xffff8000, v1
	v_lshl_or_b32 v150, s1, 6, v0
	v_writelane_b32 v254, s22, 60
	s_add_u32 s1, s22, s27
	v_lshl_add_u32 v1, v13, 11, v1
	v_and_b32_e32 v2, 1, v12
	v_writelane_b32 v254, s1, 52
	v_lshl_or_b32 v1, v2, 6, v1
	v_readlane_b32 s1, v254, 54
	v_lshl_add_u32 v152, v14, 1, v1
	v_lshlrev_b32_e32 v1, 14, v8
	s_addc_u32 s1, s1, s33
	v_and_b32_e32 v1, 0xffff8000, v1
	s_waitcnt vmcnt(6)
	v_writelane_b32 v254, s1, 61
	v_lshl_add_u32 v1, v10, 11, v1
	v_and_b32_e32 v2, 1, v8
	s_lshl_b64 s[8:9], s[30:31], 2
	v_lshl_or_b32 v1, v2, 6, v1
	v_writelane_b32 v254, s8, 62
	s_sext_i32_i8 s10, s38
	v_mov_b32_e32 v153, v145
	v_lshl_add_u32 v154, v11, 1, v1
	v_mov_b32_e32 v155, v145
	s_mov_b32 s22, 0
	v_add_u32_e32 v217, 0, v3
	v_writelane_b32 v254, s9, 63
	v_lshlrev_b32_e32 v218, 2, v0
	s_barrier
	v_readfirstlane_b32 s101, v208
	s_nop 3
	s_lshr_b32 s101, s101, 8
	s_cmp_eq_u32 s101, 0
	s_cbranch_scc1 .Lprio_a1_done
	s_setprio 1
.Lprio_a1_done:
	s_branch .LBB0_323
.LBB0_322:
	s_and_b64 vcc, exec, s[76:77]
	s_mov_b32 s10, s8
	s_mov_b32 s0, s92
	s_mov_b64 s[72:73], s[28:29]
	s_mov_b64 s[52:53], s[94:95]
	global_store_dwordx4 v[206:207], v[128:131], off offset:64
	s_cbranch_vccnz .LBB0_331

.LBB0_325:
	s_ashr_i32 s93, s92, 31
	s_lshl_b64 s[30:31], s[92:93], 19
	s_add_u32 s94, s54, s30
	v_cmp_lt_i64_e32 vcc, s[50:51], v[186:187]
	s_addc_u32 s95, s55, s31
	s_and_b64 s[30:31], vcc, exec
	s_cselect_b32 s1, s95, s53
	s_cselect_b32 s11, s94, s52
	s_ashr_i32 s9, s8, 31
	s_lshl_b64 s[30:31], s[8:9], 19
	s_add_u32 s28, s80, s30
	s_addc_u32 s29, s78, s31
	s_and_b64 s[30:31], vcc, exec
	s_cselect_b32 s25, s29, s73
	s_cselect_b32 s30, s28, s72
	s_add_u32 s52, s52, 0x40080
	s_addc_u32 s53, s53, 0
	s_add_u32 s31, s72, 0x100
	s_addc_u32 s33, s73, 0
	s_mov_b32 s34, -2
	s_add_u32 s27, s52, 0xfffc0080
	s_addc_u32 s35, s53, -1
	s_add_i32 s36, 0, 0x10000
	v_add_u32_e32 v140, s36, v216
	ds_read_b128 v[128:131], v140
	ds_read_b128 v[132:135], v140 offset:1024
	ds_read_b128 v[136:139], v140 offset:2048
	ds_read_b128 v[140:143], v140 offset:3072
	s_cmp_eq_u32 s34, 12
	s_cselect_b32 s75, s1, s35
	s_cselect_b32 s74, s11, s27
	s_cselect_b32 s73, s25, s33
	s_cselect_b32 s72, s30, s31
	v_lshl_add_u64 v[168:169], s[52:53], 0, v[152:153]
	s_add_i32 m0, s83, 0xc000
	ds_read_b128 v[156:159], v217
	ds_read_b128 v[160:163], v217 offset:1024
	ds_read_b128 v[164:167], v217 offset:2048
	ds_read_b128 v[188:191], v217 offset:3072
	ds_read_b128 v[192:195], v217 offset:4096
	ds_read_b128 v[196:199], v217 offset:5120
	ds_read_b128 v[200:203], v217 offset:6144
	ds_read_b128 v[204:207], v217 offset:7168
	global_load_lds_dwordx4 v[168:169], off
	v_lshl_add_u64 v[168:169], s[52:53], 0, v[154:155]
	s_add_i32 m0, s83, 0xe000
	s_nop 0
	global_load_lds_dwordx4 v[168:169], off
	s_waitcnt lgkmcnt(8)
	s_barrier
	s_waitcnt lgkmcnt(0)
	v_mfma_f32_16x16x32_bf16 v[124:127], v[128:131], v[156:159], 0
	v_mfma_f32_16x16x32_bf16 v[120:123], v[136:139], v[156:159], 0
	v_mfma_f32_16x16x32_bf16 v[108:111], v[128:131], v[164:167], 0
	v_mfma_f32_16x16x32_bf16 v[104:107], v[136:139], v[164:167], 0
	v_mfma_f32_16x16x32_bf16 v[92:95], v[128:131], v[192:195], 0
	v_mfma_f32_16x16x32_bf16 v[88:91], v[136:139], v[192:195], 0
	v_mfma_f32_16x16x32_bf16 v[76:79], v[128:131], v[200:203], 0
	v_mfma_f32_16x16x32_bf16 v[72:75], v[136:139], v[200:203], 0
	v_mfma_f32_16x16x32_bf16 v[124:127], v[132:135], v[160:163], v[124:127]
	v_mfma_f32_16x16x32_bf16 v[120:123], v[140:143], v[160:163], v[120:123]
	v_mfma_f32_16x16x32_bf16 v[108:111], v[132:135], v[188:191], v[108:111]
	v_mfma_f32_16x16x32_bf16 v[104:107], v[140:143], v[188:191], v[104:107]
	v_mfma_f32_16x16x32_bf16 v[92:95], v[132:135], v[196:199], v[92:95]
	v_mfma_f32_16x16x32_bf16 v[88:91], v[140:143], v[196:199], v[88:91]
	v_mfma_f32_16x16x32_bf16 v[76:79], v[132:135], v[204:207], v[76:79]
	v_mfma_f32_16x16x32_bf16 v[72:75], v[140:143], v[204:207], v[72:75]
	s_barrier
	s_add_i32 s27, 0, 0x14000
	s_add_i32 s35, s36, s81
	v_add_u32_e32 v144, s27, v216
	v_lshl_add_u64 v[168:169], s[72:73], 0, v[148:149]
	s_mov_b32 m0, s35
	ds_read_b128 v[220:223], v144
	ds_read_b128 v[228:231], v144 offset:1024
	ds_read_b128 v[232:235], v144 offset:2048
	ds_read_b128 v[236:239], v144 offset:3072
	global_load_lds_dwordx4 v[168:169], off
	v_lshl_add_u64 v[176:177], s[72:73], 0, v[146:147]
	s_add_i32 m0, s35, 0x2000
	s_nop 0
	global_load_lds_dwordx4 v[176:177], off
	s_barrier
	s_waitcnt lgkmcnt(0)
	v_mfma_f32_16x16x32_bf16 v[116:119], v[220:223], v[156:159], 0
	v_mfma_f32_16x16x32_bf16 v[112:115], v[232:235], v[156:159], 0
	v_mfma_f32_16x16x32_bf16 v[100:103], v[220:223], v[164:167], 0
	v_mfma_f32_16x16x32_bf16 v[96:99], v[232:235], v[164:167], 0
	v_mfma_f32_16x16x32_bf16 v[84:87], v[220:223], v[192:195], 0
	v_mfma_f32_16x16x32_bf16 v[80:83], v[232:235], v[192:195], 0
	v_mfma_f32_16x16x32_bf16 v[68:71], v[220:223], v[200:203], 0
	v_mfma_f32_16x16x32_bf16 v[64:67], v[232:235], v[200:203], 0
	v_mfma_f32_16x16x32_bf16 v[116:119], v[228:231], v[160:163], v[116:119]
	v_mfma_f32_16x16x32_bf16 v[112:115], v[236:239], v[160:163], v[112:115]
	v_mfma_f32_16x16x32_bf16 v[100:103], v[228:231], v[188:191], v[100:103]
	v_mfma_f32_16x16x32_bf16 v[96:99], v[236:239], v[188:191], v[96:99]
	v_mfma_f32_16x16x32_bf16 v[84:87], v[228:231], v[196:199], v[84:87]
	v_mfma_f32_16x16x32_bf16 v[80:83], v[236:239], v[196:199], v[80:83]
	v_mfma_f32_16x16x32_bf16 v[68:71], v[228:231], v[204:207], v[68:71]
	v_mfma_f32_16x16x32_bf16 v[64:67], v[236:239], v[204:207], v[64:67]
	s_barrier
	s_mov_b32 m0, s83
	v_lshl_add_u64 v[224:225], s[74:75], 0, v[148:149]
	ds_read_b128 v[156:159], v217 offset:16384
	ds_read_b128 v[160:163], v217 offset:17408
	ds_read_b128 v[164:167], v217 offset:18432
	ds_read_b128 v[188:191], v217 offset:19456
	ds_read_b128 v[192:195], v217 offset:20480
	ds_read_b128 v[196:199], v217 offset:21504
	ds_read_b128 v[200:203], v217 offset:22528
	ds_read_b128 v[204:207], v217 offset:23552
	global_load_lds_dwordx4 v[224:225], off
	v_lshl_add_u64 v[240:241], s[74:75], 0, v[146:147]
	s_mov_b32 m0, s84
	s_nop 0
	global_load_lds_dwordx4 v[240:241], off
	s_barrier
	s_waitcnt lgkmcnt(0)
	v_mfma_f32_16x16x32_bf16 v[60:63], v[128:131], v[156:159], 0
	v_mfma_f32_16x16x32_bf16 v[56:59], v[136:139], v[156:159], 0
	v_mfma_f32_16x16x32_bf16 v[44:47], v[128:131], v[164:167], 0
	v_mfma_f32_16x16x32_bf16 v[40:43], v[136:139], v[164:167], 0
	v_mfma_f32_16x16x32_bf16 v[28:31], v[128:131], v[192:195], 0
	v_mfma_f32_16x16x32_bf16 v[24:27], v[136:139], v[192:195], 0
	v_mfma_f32_16x16x32_bf16 v[12:15], v[128:131], v[200:203], 0
	v_mfma_f32_16x16x32_bf16 v[8:11], v[136:139], v[200:203], 0
	v_mfma_f32_16x16x32_bf16 v[60:63], v[132:135], v[160:163], v[60:63]
	v_mfma_f32_16x16x32_bf16 v[56:59], v[140:143], v[160:163], v[56:59]
	v_mfma_f32_16x16x32_bf16 v[44:47], v[132:135], v[188:191], v[44:47]
	v_mfma_f32_16x16x32_bf16 v[40:43], v[140:143], v[188:191], v[40:43]
	v_mfma_f32_16x16x32_bf16 v[28:31], v[132:135], v[196:199], v[28:31]
	v_mfma_f32_16x16x32_bf16 v[24:27], v[140:143], v[196:199], v[24:27]
	v_mfma_f32_16x16x32_bf16 v[12:15], v[132:135], v[204:207], v[12:15]
	v_mfma_f32_16x16x32_bf16 v[8:11], v[140:143], v[204:207], v[8:11]
	s_barrier
	s_add_u32 s36, s72, 0x40000
	s_addc_u32 s37, s73, 0
	s_add_i32 s27, s27, s81
	v_lshl_add_u64 v[128:129], s[36:37], 0, v[148:149]
	s_mov_b32 m0, s27
	s_nop 0
	global_load_lds_dwordx4 v[128:129], off
	v_lshl_add_u64 v[128:129], s[36:37], 0, v[146:147]
	s_add_i32 m0, s27, 0x2000
	s_nop 0
	global_load_lds_dwordx4 v[128:129], off
	s_waitcnt vmcnt(6)
	s_barrier
	v_mfma_f32_16x16x32_bf16 v[52:55], v[220:223], v[156:159], 0
	v_mfma_f32_16x16x32_bf16 v[48:51], v[232:235], v[156:159], 0
	v_mfma_f32_16x16x32_bf16 v[36:39], v[220:223], v[164:167], 0
	v_mfma_f32_16x16x32_bf16 v[32:35], v[232:235], v[164:167], 0
	v_mfma_f32_16x16x32_bf16 v[20:23], v[220:223], v[192:195], 0
	v_mfma_f32_16x16x32_bf16 v[16:19], v[232:235], v[192:195], 0
	v_mfma_f32_16x16x32_bf16 v[4:7], v[220:223], v[200:203], 0
	v_mfma_f32_16x16x32_bf16 v[0:3], v[232:235], v[200:203], 0
	v_mfma_f32_16x16x32_bf16 v[52:55], v[228:231], v[160:163], v[52:55]
	v_mfma_f32_16x16x32_bf16 v[48:51], v[236:239], v[160:163], v[48:51]
	v_mfma_f32_16x16x32_bf16 v[36:39], v[228:231], v[188:191], v[36:39]
	v_mfma_f32_16x16x32_bf16 v[32:35], v[236:239], v[188:191], v[32:35]
	v_mfma_f32_16x16x32_bf16 v[20:23], v[228:231], v[196:199], v[20:23]
	v_mfma_f32_16x16x32_bf16 v[16:19], v[236:239], v[196:199], v[16:19]
	v_mfma_f32_16x16x32_bf16 v[4:7], v[228:231], v[204:207], v[4:7]
	v_mfma_f32_16x16x32_bf16 v[0:3], v[236:239], v[204:207], v[0:3]
	s_barrier
	s_add_i32 s27, 0, 0x18000
	v_add_u32_e32 v140, s27, v216
	ds_read_b128 v[128:131], v140
	ds_read_b128 v[132:135], v140 offset:1024
	ds_read_b128 v[136:139], v140 offset:2048
	ds_read_b128 v[140:143], v140 offset:3072
	s_add_u32 s36, s74, 0x40000
	s_addc_u32 s37, s75, 0
	s_mov_b32 m0, s85
	v_lshl_add_u64 v[220:221], s[36:37], 0, v[148:149]
	ds_read_b128 v[156:159], v217 offset:32768
	ds_read_b128 v[160:163], v217 offset:33792
	ds_read_b128 v[164:167], v217 offset:34816
	ds_read_b128 v[188:191], v217 offset:35840
	ds_read_b128 v[192:195], v217 offset:36864
	ds_read_b128 v[196:199], v217 offset:37888
	ds_read_b128 v[200:203], v217 offset:38912
	ds_read_b128 v[204:207], v217 offset:39936
	global_load_lds_dwordx4 v[220:221], off
	v_lshl_add_u64 v[220:221], s[36:37], 0, v[146:147]
	s_mov_b32 m0, s86
	s_nop 0
	global_load_lds_dwordx4 v[220:221], off
	s_waitcnt lgkmcnt(8)
	s_barrier
	s_waitcnt lgkmcnt(0)
	v_mfma_f32_16x16x32_bf16 v[124:127], v[128:131], v[156:159], v[124:127]
	v_mfma_f32_16x16x32_bf16 v[120:123], v[136:139], v[156:159], v[120:123]
	v_mfma_f32_16x16x32_bf16 v[108:111], v[128:131], v[164:167], v[108:111]
	v_mfma_f32_16x16x32_bf16 v[104:107], v[136:139], v[164:167], v[104:107]
	v_mfma_f32_16x16x32_bf16 v[92:95], v[128:131], v[192:195], v[92:95]
	v_mfma_f32_16x16x32_bf16 v[88:91], v[136:139], v[192:195], v[88:91]
	v_mfma_f32_16x16x32_bf16 v[76:79], v[128:131], v[200:203], v[76:79]
	v_mfma_f32_16x16x32_bf16 v[72:75], v[136:139], v[200:203], v[72:75]
	v_mfma_f32_16x16x32_bf16 v[124:127], v[132:135], v[160:163], v[124:127]
	v_mfma_f32_16x16x32_bf16 v[120:123], v[140:143], v[160:163], v[120:123]
	v_mfma_f32_16x16x32_bf16 v[108:111], v[132:135], v[188:191], v[108:111]
	v_mfma_f32_16x16x32_bf16 v[104:107], v[140:143], v[188:191], v[104:107]
	v_mfma_f32_16x16x32_bf16 v[92:95], v[132:135], v[196:199], v[92:95]
	v_mfma_f32_16x16x32_bf16 v[88:91], v[140:143], v[196:199], v[88:91]
	v_mfma_f32_16x16x32_bf16 v[76:79], v[132:135], v[204:207], v[76:79]
	v_mfma_f32_16x16x32_bf16 v[72:75], v[140:143], v[204:207], v[72:75]
	s_barrier
	s_add_i32 s35, 0, 0x1c000
	s_add_i32 s27, s27, s81
	v_add_u32_e32 v144, s35, v216
	v_lshl_add_u64 v[168:169], v[168:169], 0, s[18:19]
	s_mov_b32 m0, s27
	ds_read_b128 v[220:223], v144
	ds_read_b128 v[228:231], v144 offset:1024
	ds_read_b128 v[232:235], v144 offset:2048
	ds_read_b128 v[236:239], v144 offset:3072
	global_load_lds_dwordx4 v[168:169], off
	v_lshl_add_u64 v[168:169], v[176:177], 0, s[18:19]
	s_add_i32 m0, s27, 0x2000
	s_nop 0
	global_load_lds_dwordx4 v[168:169], off
	s_barrier
	s_waitcnt lgkmcnt(0)
	v_mfma_f32_16x16x32_bf16 v[116:119], v[220:223], v[156:159], v[116:119]
	v_mfma_f32_16x16x32_bf16 v[112:115], v[232:235], v[156:159], v[112:115]
	v_mfma_f32_16x16x32_bf16 v[100:103], v[220:223], v[164:167], v[100:103]
	v_mfma_f32_16x16x32_bf16 v[96:99], v[232:235], v[164:167], v[96:99]
	v_mfma_f32_16x16x32_bf16 v[84:87], v[220:223], v[192:195], v[84:87]
	v_mfma_f32_16x16x32_bf16 v[80:83], v[232:235], v[192:195], v[80:83]
	v_mfma_f32_16x16x32_bf16 v[68:71], v[220:223], v[200:203], v[68:71]
	v_mfma_f32_16x16x32_bf16 v[64:67], v[232:235], v[200:203], v[64:67]
	v_mfma_f32_16x16x32_bf16 v[116:119], v[228:231], v[160:163], v[116:119]
	v_mfma_f32_16x16x32_bf16 v[112:115], v[236:239], v[160:163], v[112:115]
	v_mfma_f32_16x16x32_bf16 v[100:103], v[228:231], v[188:191], v[100:103]
	v_mfma_f32_16x16x32_bf16 v[96:99], v[236:239], v[188:191], v[96:99]
	v_mfma_f32_16x16x32_bf16 v[84:87], v[228:231], v[196:199], v[84:87]
	v_mfma_f32_16x16x32_bf16 v[80:83], v[236:239], v[196:199], v[80:83]
	v_mfma_f32_16x16x32_bf16 v[68:71], v[228:231], v[204:207], v[68:71]
	v_mfma_f32_16x16x32_bf16 v[64:67], v[236:239], v[204:207], v[64:67]
	s_barrier
	s_mov_b32 m0, s87
	v_lshl_add_u64 v[168:169], v[224:225], 0, s[18:19]
	ds_read_b128 v[156:159], v217 offset:49152
	ds_read_b128 v[160:163], v217 offset:50176
	ds_read_b128 v[164:167], v217 offset:51200
	ds_read_b128 v[188:191], v217 offset:52224
	ds_read_b128 v[192:195], v217 offset:53248
	ds_read_b128 v[196:199], v217 offset:54272
	ds_read_b128 v[200:203], v217 offset:55296
	ds_read_b128 v[204:207], v217 offset:56320
	global_load_lds_dwordx4 v[168:169], off
	v_lshl_add_u64 v[168:169], v[240:241], 0, s[18:19]
	s_mov_b32 m0, s79
	s_nop 0
	global_load_lds_dwordx4 v[168:169], off
	s_barrier
	s_waitcnt lgkmcnt(0)
	v_mfma_f32_16x16x32_bf16 v[60:63], v[128:131], v[156:159], v[60:63]
	v_mfma_f32_16x16x32_bf16 v[56:59], v[136:139], v[156:159], v[56:59]
	v_mfma_f32_16x16x32_bf16 v[44:47], v[128:131], v[164:167], v[44:47]
	v_mfma_f32_16x16x32_bf16 v[40:43], v[136:139], v[164:167], v[40:43]
	v_mfma_f32_16x16x32_bf16 v[28:31], v[128:131], v[192:195], v[28:31]
	v_mfma_f32_16x16x32_bf16 v[24:27], v[136:139], v[192:195], v[24:27]
	v_mfma_f32_16x16x32_bf16 v[12:15], v[128:131], v[200:203], v[12:15]
	v_mfma_f32_16x16x32_bf16 v[8:11], v[136:139], v[200:203], v[8:11]
	v_mfma_f32_16x16x32_bf16 v[60:63], v[132:135], v[160:163], v[60:63]
	v_mfma_f32_16x16x32_bf16 v[56:59], v[140:143], v[160:163], v[56:59]
	v_mfma_f32_16x16x32_bf16 v[44:47], v[132:135], v[188:191], v[44:47]
	v_mfma_f32_16x16x32_bf16 v[40:43], v[140:143], v[188:191], v[40:43]
	v_mfma_f32_16x16x32_bf16 v[28:31], v[132:135], v[196:199], v[28:31]
	v_mfma_f32_16x16x32_bf16 v[24:27], v[140:143], v[196:199], v[24:27]
	v_mfma_f32_16x16x32_bf16 v[12:15], v[132:135], v[204:207], v[12:15]
	v_mfma_f32_16x16x32_bf16 v[8:11], v[140:143], v[204:207], v[8:11]
	s_barrier
	s_add_u32 s36, s72, 0x40080
	s_addc_u32 s37, s73, 0
	s_add_i32 s27, s35, s81
	v_lshl_add_u64 v[128:129], s[36:37], 0, v[148:149]
	s_mov_b32 m0, s27
	s_nop 0
	global_load_lds_dwordx4 v[128:129], off
	v_lshl_add_u64 v[128:129], s[36:37], 0, v[146:147]
	s_add_i32 m0, s27, 0x2000
	s_nop 0
	global_load_lds_dwordx4 v[128:129], off
	s_waitcnt vmcnt(6)
	s_barrier
	v_mfma_f32_16x16x32_bf16 v[52:55], v[220:223], v[156:159], v[52:55]
	v_mfma_f32_16x16x32_bf16 v[48:51], v[232:235], v[156:159], v[48:51]
	v_mfma_f32_16x16x32_bf16 v[36:39], v[220:223], v[164:167], v[36:39]
	v_mfma_f32_16x16x32_bf16 v[32:35], v[232:235], v[164:167], v[32:35]
	v_mfma_f32_16x16x32_bf16 v[20:23], v[220:223], v[192:195], v[20:23]
	v_mfma_f32_16x16x32_bf16 v[16:19], v[232:235], v[192:195], v[16:19]
	v_mfma_f32_16x16x32_bf16 v[4:7], v[220:223], v[200:203], v[4:7]
	v_mfma_f32_16x16x32_bf16 v[0:3], v[232:235], v[200:203], v[0:3]
	v_mfma_f32_16x16x32_bf16 v[52:55], v[228:231], v[160:163], v[52:55]
	v_mfma_f32_16x16x32_bf16 v[48:51], v[236:239], v[160:163], v[48:51]
	v_mfma_f32_16x16x32_bf16 v[36:39], v[228:231], v[188:191], v[36:39]
	v_mfma_f32_16x16x32_bf16 v[32:35], v[236:239], v[188:191], v[32:35]
	v_mfma_f32_16x16x32_bf16 v[20:23], v[228:231], v[196:199], v[20:23]
	v_mfma_f32_16x16x32_bf16 v[16:19], v[236:239], v[196:199], v[16:19]
	v_mfma_f32_16x16x32_bf16 v[4:7], v[228:231], v[204:207], v[4:7]
	v_mfma_f32_16x16x32_bf16 v[0:3], v[236:239], v[204:207], v[0:3]
	s_barrier
	s_add_i32 s34, s34, 2
	s_add_u32 s52, s52, 0x100
	s_addc_u32 s53, s53, 0
	s_add_u32 s31, s31, 0x100
	s_addc_u32 s33, s33, 0
	s_cmp_gt_u32 s34, 13
.LBB0_326:
	s_add_u32 s27, s52, 0xfffc0080
	s_addc_u32 s35, s53, -1
	s_add_i32 s36, 0, 0x10000
	v_add_u32_e32 v140, s36, v216
	ds_read_b128 v[128:131], v140
	ds_read_b128 v[132:135], v140 offset:1024
	ds_read_b128 v[136:139], v140 offset:2048
	ds_read_b128 v[140:143], v140 offset:3072
	s_cmp_eq_u32 s34, 12
	s_cselect_b32 s75, s1, s35
	s_cselect_b32 s74, s11, s27
	s_cselect_b32 s73, s25, s33
	s_cselect_b32 s72, s30, s31
	v_lshl_add_u64 v[168:169], s[52:53], 0, v[152:153]
	s_add_i32 m0, s83, 0xc000
	ds_read_b128 v[156:159], v217
	ds_read_b128 v[160:163], v217 offset:1024
	ds_read_b128 v[164:167], v217 offset:2048
	ds_read_b128 v[188:191], v217 offset:3072
	ds_read_b128 v[192:195], v217 offset:4096
	ds_read_b128 v[196:199], v217 offset:5120
	ds_read_b128 v[200:203], v217 offset:6144
	ds_read_b128 v[204:207], v217 offset:7168
	global_load_lds_dwordx4 v[168:169], off
	v_lshl_add_u64 v[168:169], s[52:53], 0, v[154:155]
	s_add_i32 m0, s83, 0xe000
	s_nop 0
	global_load_lds_dwordx4 v[168:169], off
	s_waitcnt lgkmcnt(8)
	s_barrier
	s_waitcnt lgkmcnt(0)
	v_mfma_f32_16x16x32_bf16 v[124:127], v[128:131], v[156:159], v[124:127]
	v_mfma_f32_16x16x32_bf16 v[120:123], v[136:139], v[156:159], v[120:123]
	v_mfma_f32_16x16x32_bf16 v[108:111], v[128:131], v[164:167], v[108:111]
	v_mfma_f32_16x16x32_bf16 v[104:107], v[136:139], v[164:167], v[104:107]
	v_mfma_f32_16x16x32_bf16 v[92:95], v[128:131], v[192:195], v[92:95]
	v_mfma_f32_16x16x32_bf16 v[88:91], v[136:139], v[192:195], v[88:91]
	v_mfma_f32_16x16x32_bf16 v[76:79], v[128:131], v[200:203], v[76:79]
	v_mfma_f32_16x16x32_bf16 v[72:75], v[136:139], v[200:203], v[72:75]
	v_mfma_f32_16x16x32_bf16 v[124:127], v[132:135], v[160:163], v[124:127]
	v_mfma_f32_16x16x32_bf16 v[120:123], v[140:143], v[160:163], v[120:123]
	v_mfma_f32_16x16x32_bf16 v[108:111], v[132:135], v[188:191], v[108:111]
	v_mfma_f32_16x16x32_bf16 v[104:107], v[140:143], v[188:191], v[104:107]
	v_mfma_f32_16x16x32_bf16 v[92:95], v[132:135], v[196:199], v[92:95]
	v_mfma_f32_16x16x32_bf16 v[88:91], v[140:143], v[196:199], v[88:91]
	v_mfma_f32_16x16x32_bf16 v[76:79], v[132:135], v[204:207], v[76:79]
	v_mfma_f32_16x16x32_bf16 v[72:75], v[140:143], v[204:207], v[72:75]
	s_barrier
	s_add_i32 s27, 0, 0x14000
	s_add_i32 s35, s36, s81
	v_add_u32_e32 v144, s27, v216
	v_lshl_add_u64 v[168:169], s[72:73], 0, v[148:149]
	s_mov_b32 m0, s35
	ds_read_b128 v[220:223], v144
	ds_read_b128 v[228:231], v144 offset:1024
	ds_read_b128 v[232:235], v144 offset:2048
	ds_read_b128 v[236:239], v144 offset:3072
	global_load_lds_dwordx4 v[168:169], off
	v_lshl_add_u64 v[176:177], s[72:73], 0, v[146:147]
	s_add_i32 m0, s35, 0x2000
	s_nop 0
	global_load_lds_dwordx4 v[176:177], off
	s_barrier
	s_waitcnt lgkmcnt(0)
	v_mfma_f32_16x16x32_bf16 v[116:119], v[220:223], v[156:159], v[116:119]
	v_mfma_f32_16x16x32_bf16 v[112:115], v[232:235], v[156:159], v[112:115]
	v_mfma_f32_16x16x32_bf16 v[100:103], v[220:223], v[164:167], v[100:103]
	v_mfma_f32_16x16x32_bf16 v[96:99], v[232:235], v[164:167], v[96:99]
	v_mfma_f32_16x16x32_bf16 v[84:87], v[220:223], v[192:195], v[84:87]
	v_mfma_f32_16x16x32_bf16 v[80:83], v[232:235], v[192:195], v[80:83]
	v_mfma_f32_16x16x32_bf16 v[68:71], v[220:223], v[200:203], v[68:71]
	v_mfma_f32_16x16x32_bf16 v[64:67], v[232:235], v[200:203], v[64:67]
	v_mfma_f32_16x16x32_bf16 v[116:119], v[228:231], v[160:163], v[116:119]
	v_mfma_f32_16x16x32_bf16 v[112:115], v[236:239], v[160:163], v[112:115]
	v_mfma_f32_16x16x32_bf16 v[100:103], v[228:231], v[188:191], v[100:103]
	v_mfma_f32_16x16x32_bf16 v[96:99], v[236:239], v[188:191], v[96:99]
	v_mfma_f32_16x16x32_bf16 v[84:87], v[228:231], v[196:199], v[84:87]
	v_mfma_f32_16x16x32_bf16 v[80:83], v[236:239], v[196:199], v[80:83]
	v_mfma_f32_16x16x32_bf16 v[68:71], v[228:231], v[204:207], v[68:71]
	v_mfma_f32_16x16x32_bf16 v[64:67], v[236:239], v[204:207], v[64:67]
	s_barrier
	s_mov_b32 m0, s83
	v_lshl_add_u64 v[224:225], s[74:75], 0, v[148:149]
	ds_read_b128 v[156:159], v217 offset:16384
	ds_read_b128 v[160:163], v217 offset:17408
	ds_read_b128 v[164:167], v217 offset:18432
	ds_read_b128 v[188:191], v217 offset:19456
	ds_read_b128 v[192:195], v217 offset:20480
	ds_read_b128 v[196:199], v217 offset:21504
	ds_read_b128 v[200:203], v217 offset:22528
	ds_read_b128 v[204:207], v217 offset:23552
	global_load_lds_dwordx4 v[224:225], off
	v_lshl_add_u64 v[240:241], s[74:75], 0, v[146:147]
	s_mov_b32 m0, s84
	s_nop 0
	global_load_lds_dwordx4 v[240:241], off
	s_barrier
	s_waitcnt lgkmcnt(0)
	v_mfma_f32_16x16x32_bf16 v[60:63], v[128:131], v[156:159], v[60:63]
	v_mfma_f32_16x16x32_bf16 v[56:59], v[136:139], v[156:159], v[56:59]
	v_mfma_f32_16x16x32_bf16 v[44:47], v[128:131], v[164:167], v[44:47]
	v_mfma_f32_16x16x32_bf16 v[40:43], v[136:139], v[164:167], v[40:43]
	v_mfma_f32_16x16x32_bf16 v[28:31], v[128:131], v[192:195], v[28:31]
	v_mfma_f32_16x16x32_bf16 v[24:27], v[136:139], v[192:195], v[24:27]
	v_mfma_f32_16x16x32_bf16 v[12:15], v[128:131], v[200:203], v[12:15]
	v_mfma_f32_16x16x32_bf16 v[8:11], v[136:139], v[200:203], v[8:11]
	v_mfma_f32_16x16x32_bf16 v[60:63], v[132:135], v[160:163], v[60:63]
	v_mfma_f32_16x16x32_bf16 v[56:59], v[140:143], v[160:163], v[56:59]
	v_mfma_f32_16x16x32_bf16 v[44:47], v[132:135], v[188:191], v[44:47]
	v_mfma_f32_16x16x32_bf16 v[40:43], v[140:143], v[188:191], v[40:43]
	v_mfma_f32_16x16x32_bf16 v[28:31], v[132:135], v[196:199], v[28:31]
	v_mfma_f32_16x16x32_bf16 v[24:27], v[140:143], v[196:199], v[24:27]
	v_mfma_f32_16x16x32_bf16 v[12:15], v[132:135], v[204:207], v[12:15]
	v_mfma_f32_16x16x32_bf16 v[8:11], v[140:143], v[204:207], v[8:11]
	s_barrier
	s_add_u32 s36, s72, 0x40000
	s_addc_u32 s37, s73, 0
	s_add_i32 s27, s27, s81
	v_lshl_add_u64 v[128:129], s[36:37], 0, v[148:149]
	s_mov_b32 m0, s27
	s_nop 0
	global_load_lds_dwordx4 v[128:129], off
	v_lshl_add_u64 v[128:129], s[36:37], 0, v[146:147]
	s_add_i32 m0, s27, 0x2000
	s_nop 0
	global_load_lds_dwordx4 v[128:129], off
	s_waitcnt vmcnt(6)
	s_barrier
	v_mfma_f32_16x16x32_bf16 v[52:55], v[220:223], v[156:159], v[52:55]
	v_mfma_f32_16x16x32_bf16 v[48:51], v[232:235], v[156:159], v[48:51]
	v_mfma_f32_16x16x32_bf16 v[36:39], v[220:223], v[164:167], v[36:39]
	v_mfma_f32_16x16x32_bf16 v[32:35], v[232:235], v[164:167], v[32:35]
	v_mfma_f32_16x16x32_bf16 v[20:23], v[220:223], v[192:195], v[20:23]
	v_mfma_f32_16x16x32_bf16 v[16:19], v[232:235], v[192:195], v[16:19]
	v_mfma_f32_16x16x32_bf16 v[4:7], v[220:223], v[200:203], v[4:7]
	v_mfma_f32_16x16x32_bf16 v[0:3], v[232:235], v[200:203], v[0:3]
	v_mfma_f32_16x16x32_bf16 v[52:55], v[228:231], v[160:163], v[52:55]
	v_mfma_f32_16x16x32_bf16 v[48:51], v[236:239], v[160:163], v[48:51]
	v_mfma_f32_16x16x32_bf16 v[36:39], v[228:231], v[188:191], v[36:39]
	v_mfma_f32_16x16x32_bf16 v[32:35], v[236:239], v[188:191], v[32:35]
	v_mfma_f32_16x16x32_bf16 v[20:23], v[228:231], v[196:199], v[20:23]
	v_mfma_f32_16x16x32_bf16 v[16:19], v[236:239], v[196:199], v[16:19]
	v_mfma_f32_16x16x32_bf16 v[4:7], v[228:231], v[204:207], v[4:7]
	v_mfma_f32_16x16x32_bf16 v[0:3], v[236:239], v[204:207], v[0:3]
	s_barrier
	s_add_i32 s27, 0, 0x18000
	v_add_u32_e32 v140, s27, v216
	ds_read_b128 v[128:131], v140
	ds_read_b128 v[132:135], v140 offset:1024
	ds_read_b128 v[136:139], v140 offset:2048
	ds_read_b128 v[140:143], v140 offset:3072
	s_add_u32 s36, s74, 0x40000
	s_addc_u32 s37, s75, 0
	s_mov_b32 m0, s85
	v_lshl_add_u64 v[220:221], s[36:37], 0, v[148:149]
	ds_read_b128 v[156:159], v217 offset:32768
	ds_read_b128 v[160:163], v217 offset:33792
	ds_read_b128 v[164:167], v217 offset:34816
	ds_read_b128 v[188:191], v217 offset:35840
	ds_read_b128 v[192:195], v217 offset:36864
	ds_read_b128 v[196:199], v217 offset:37888
	ds_read_b128 v[200:203], v217 offset:38912
	ds_read_b128 v[204:207], v217 offset:39936
	global_load_lds_dwordx4 v[220:221], off
	v_lshl_add_u64 v[220:221], s[36:37], 0, v[146:147]
	s_mov_b32 m0, s86
	s_nop 0
	global_load_lds_dwordx4 v[220:221], off
	s_waitcnt lgkmcnt(8)
	s_barrier
	s_waitcnt lgkmcnt(0)
	v_mfma_f32_16x16x32_bf16 v[124:127], v[128:131], v[156:159], v[124:127]
	v_mfma_f32_16x16x32_bf16 v[120:123], v[136:139], v[156:159], v[120:123]
	v_mfma_f32_16x16x32_bf16 v[108:111], v[128:131], v[164:167], v[108:111]
	v_mfma_f32_16x16x32_bf16 v[104:107], v[136:139], v[164:167], v[104:107]
	v_mfma_f32_16x16x32_bf16 v[92:95], v[128:131], v[192:195], v[92:95]
	v_mfma_f32_16x16x32_bf16 v[88:91], v[136:139], v[192:195], v[88:91]
	v_mfma_f32_16x16x32_bf16 v[76:79], v[128:131], v[200:203], v[76:79]
	v_mfma_f32_16x16x32_bf16 v[72:75], v[136:139], v[200:203], v[72:75]
	v_mfma_f32_16x16x32_bf16 v[124:127], v[132:135], v[160:163], v[124:127]
	v_mfma_f32_16x16x32_bf16 v[120:123], v[140:143], v[160:163], v[120:123]
	v_mfma_f32_16x16x32_bf16 v[108:111], v[132:135], v[188:191], v[108:111]
	v_mfma_f32_16x16x32_bf16 v[104:107], v[140:143], v[188:191], v[104:107]
	v_mfma_f32_16x16x32_bf16 v[92:95], v[132:135], v[196:199], v[92:95]
	v_mfma_f32_16x16x32_bf16 v[88:91], v[140:143], v[196:199], v[88:91]
	v_mfma_f32_16x16x32_bf16 v[76:79], v[132:135], v[204:207], v[76:79]
	v_mfma_f32_16x16x32_bf16 v[72:75], v[140:143], v[204:207], v[72:75]
	s_barrier
	s_add_i32 s35, 0, 0x1c000
	s_add_i32 s27, s27, s81
	v_add_u32_e32 v144, s35, v216
	v_lshl_add_u64 v[168:169], v[168:169], 0, s[18:19]
	s_mov_b32 m0, s27
	ds_read_b128 v[220:223], v144
	ds_read_b128 v[228:231], v144 offset:1024
	ds_read_b128 v[232:235], v144 offset:2048
	ds_read_b128 v[236:239], v144 offset:3072
	global_load_lds_dwordx4 v[168:169], off
	v_lshl_add_u64 v[168:169], v[176:177], 0, s[18:19]
	s_add_i32 m0, s27, 0x2000
	s_nop 0
	global_load_lds_dwordx4 v[168:169], off
	s_barrier
	s_waitcnt lgkmcnt(0)
	v_mfma_f32_16x16x32_bf16 v[116:119], v[220:223], v[156:159], v[116:119]
	v_mfma_f32_16x16x32_bf16 v[112:115], v[232:235], v[156:159], v[112:115]
	v_mfma_f32_16x16x32_bf16 v[100:103], v[220:223], v[164:167], v[100:103]
	v_mfma_f32_16x16x32_bf16 v[96:99], v[232:235], v[164:167], v[96:99]
	v_mfma_f32_16x16x32_bf16 v[84:87], v[220:223], v[192:195], v[84:87]
	v_mfma_f32_16x16x32_bf16 v[80:83], v[232:235], v[192:195], v[80:83]
	v_mfma_f32_16x16x32_bf16 v[68:71], v[220:223], v[200:203], v[68:71]
	v_mfma_f32_16x16x32_bf16 v[64:67], v[232:235], v[200:203], v[64:67]
	v_mfma_f32_16x16x32_bf16 v[116:119], v[228:231], v[160:163], v[116:119]
	v_mfma_f32_16x16x32_bf16 v[112:115], v[236:239], v[160:163], v[112:115]
	v_mfma_f32_16x16x32_bf16 v[100:103], v[228:231], v[188:191], v[100:103]
	v_mfma_f32_16x16x32_bf16 v[96:99], v[236:239], v[188:191], v[96:99]
	v_mfma_f32_16x16x32_bf16 v[84:87], v[228:231], v[196:199], v[84:87]
	v_mfma_f32_16x16x32_bf16 v[80:83], v[236:239], v[196:199], v[80:83]
	v_mfma_f32_16x16x32_bf16 v[68:71], v[228:231], v[204:207], v[68:71]
	v_mfma_f32_16x16x32_bf16 v[64:67], v[236:239], v[204:207], v[64:67]
	s_barrier
	s_mov_b32 m0, s87
	v_lshl_add_u64 v[168:169], v[224:225], 0, s[18:19]
	ds_read_b128 v[156:159], v217 offset:49152
	ds_read_b128 v[160:163], v217 offset:50176
	ds_read_b128 v[164:167], v217 offset:51200
	ds_read_b128 v[188:191], v217 offset:52224
	ds_read_b128 v[192:195], v217 offset:53248
	ds_read_b128 v[196:199], v217 offset:54272
	ds_read_b128 v[200:203], v217 offset:55296
	ds_read_b128 v[204:207], v217 offset:56320
	global_load_lds_dwordx4 v[168:169], off
	v_lshl_add_u64 v[168:169], v[240:241], 0, s[18:19]
	s_mov_b32 m0, s79
	s_nop 0
	global_load_lds_dwordx4 v[168:169], off
	s_barrier
	s_waitcnt lgkmcnt(0)
	v_mfma_f32_16x16x32_bf16 v[60:63], v[128:131], v[156:159], v[60:63]
	v_mfma_f32_16x16x32_bf16 v[56:59], v[136:139], v[156:159], v[56:59]
	v_mfma_f32_16x16x32_bf16 v[44:47], v[128:131], v[164:167], v[44:47]
	v_mfma_f32_16x16x32_bf16 v[40:43], v[136:139], v[164:167], v[40:43]
	v_mfma_f32_16x16x32_bf16 v[28:31], v[128:131], v[192:195], v[28:31]
	v_mfma_f32_16x16x32_bf16 v[24:27], v[136:139], v[192:195], v[24:27]
	v_mfma_f32_16x16x32_bf16 v[12:15], v[128:131], v[200:203], v[12:15]
	v_mfma_f32_16x16x32_bf16 v[8:11], v[136:139], v[200:203], v[8:11]
	v_mfma_f32_16x16x32_bf16 v[60:63], v[132:135], v[160:163], v[60:63]
	v_mfma_f32_16x16x32_bf16 v[56:59], v[140:143], v[160:163], v[56:59]
	v_mfma_f32_16x16x32_bf16 v[44:47], v[132:135], v[188:191], v[44:47]
	v_mfma_f32_16x16x32_bf16 v[40:43], v[140:143], v[188:191], v[40:43]
	v_mfma_f32_16x16x32_bf16 v[28:31], v[132:135], v[196:199], v[28:31]
	v_mfma_f32_16x16x32_bf16 v[24:27], v[140:143], v[196:199], v[24:27]
	v_mfma_f32_16x16x32_bf16 v[12:15], v[132:135], v[204:207], v[12:15]
	v_mfma_f32_16x16x32_bf16 v[8:11], v[140:143], v[204:207], v[8:11]
	s_barrier
	s_add_u32 s36, s72, 0x40080
	s_addc_u32 s37, s73, 0
	s_add_i32 s27, s35, s81
	v_lshl_add_u64 v[128:129], s[36:37], 0, v[148:149]
	s_mov_b32 m0, s27
	s_nop 0
	global_load_lds_dwordx4 v[128:129], off
	v_lshl_add_u64 v[128:129], s[36:37], 0, v[146:147]
	s_add_i32 m0, s27, 0x2000
	s_nop 0
	global_load_lds_dwordx4 v[128:129], off
	s_waitcnt vmcnt(6)
	s_barrier
	v_mfma_f32_16x16x32_bf16 v[52:55], v[220:223], v[156:159], v[52:55]
	v_mfma_f32_16x16x32_bf16 v[48:51], v[232:235], v[156:159], v[48:51]
	v_mfma_f32_16x16x32_bf16 v[36:39], v[220:223], v[164:167], v[36:39]
	v_mfma_f32_16x16x32_bf16 v[32:35], v[232:235], v[164:167], v[32:35]
	v_mfma_f32_16x16x32_bf16 v[20:23], v[220:223], v[192:195], v[20:23]
	v_mfma_f32_16x16x32_bf16 v[16:19], v[232:235], v[192:195], v[16:19]
	v_mfma_f32_16x16x32_bf16 v[4:7], v[220:223], v[200:203], v[4:7]
	v_mfma_f32_16x16x32_bf16 v[0:3], v[232:235], v[200:203], v[0:3]
	v_mfma_f32_16x16x32_bf16 v[52:55], v[228:231], v[160:163], v[52:55]
	v_mfma_f32_16x16x32_bf16 v[48:51], v[236:239], v[160:163], v[48:51]
	v_mfma_f32_16x16x32_bf16 v[36:39], v[228:231], v[188:191], v[36:39]
	v_mfma_f32_16x16x32_bf16 v[32:35], v[236:239], v[188:191], v[32:35]
	v_mfma_f32_16x16x32_bf16 v[20:23], v[228:231], v[196:199], v[20:23]
	v_mfma_f32_16x16x32_bf16 v[16:19], v[236:239], v[196:199], v[16:19]
	v_mfma_f32_16x16x32_bf16 v[4:7], v[228:231], v[204:207], v[4:7]
	v_mfma_f32_16x16x32_bf16 v[0:3], v[236:239], v[204:207], v[0:3]
	s_barrier
	s_add_i32 s34, s34, 2
	s_add_u32 s52, s52, 0x100
	s_addc_u32 s53, s53, 0
	s_add_u32 s31, s31, 0x100
	s_addc_u32 s33, s33, 0
	s_cmp_gt_u32 s34, 13
	s_cbranch_scc0 .LBB0_326
	v_lshl_add_u32 v128, s0, 8, v151
	v_readlane_b32 s0, v252, 36
	v_ashrrev_i32_e32 v129, 31, v128
	v_readlane_b32 s1, v252, 37
	v_or_b32_e32 v132, 16, v128
	v_or_b32_e32 v136, 32, v128
	v_lshl_add_u64 v[130:131], v[128:129], 3, s[0:1]
	v_ashrrev_i32_e32 v133, 31, v132
	v_ashrrev_i32_e32 v137, 31, v136
	v_or_b32_e32 v140, 48, v128
	v_lshl_add_u64 v[134:135], v[132:133], 3, s[0:1]
	v_lshl_add_u64 v[138:139], v[136:137], 3, s[0:1]
	v_ashrrev_i32_e32 v141, 31, v140
	global_load_dwordx2 v[202:203], v[130:131], off
	global_load_dwordx2 v[200:201], v[134:135], off
	global_load_dwordx2 v[192:193], v[138:139], off
	global_load_dwordx2 v[166:167], v[130:131], off offset:1024
	v_add_u32_e32 v164, 0x90, v128
	v_add_u32_e32 v158, 0xa0, v128
	v_add_u32_e32 v156, 0xb0, v128
	v_lshl_add_u64 v[142:143], v[140:141], 3, s[0:1]
	v_ashrrev_i32_e32 v165, 31, v164
	v_ashrrev_i32_e32 v159, 31, v158
	v_ashrrev_i32_e32 v157, 31, v156
	v_lshl_add_u64 v[130:131], v[164:165], 3, s[0:1]
	v_lshl_add_u64 v[134:135], v[158:159], 3, s[0:1]
	v_lshl_add_u64 v[138:139], v[156:157], 3, s[0:1]
	global_load_dwordx2 v[196:197], v[142:143], off
	global_load_dwordx2 v[188:189], v[130:131], off
	global_load_dwordx2 v[162:163], v[134:135], off
	global_load_dwordx2 v[160:161], v[138:139], off
	v_add_u32_e32 v168, 0x80, v128
	s_mov_b64 s[0:1], -1
	s_cmp_gt_u32 s10, 1
	v_lshlrev_b32_e32 v144, 1, v150
	v_ashrrev_i32_e32 v169, 31, v168
	v_lshlrev_b64 v[204:205], 10, v[128:129]
	v_lshlrev_b64 v[198:199], 10, v[132:133]
	v_lshlrev_b64 v[194:195], 10, v[136:137]
	v_lshlrev_b64 v[190:191], 10, v[140:141]
	s_waitcnt vmcnt(0)
	v_ffbh_u32_e32 v222, v203
	v_ffbh_u32_e32 v221, v201
	v_ffbh_u32_e32 v220, v193
	v_ffbh_u32_e32 v219, v197
	s_cbranch_scc0 .LBB0_329
	s_cmp_lt_u32 s10, 4
	s_cselect_b64 vcc, -1, 0
	v_readlane_b32 s56, v254, 23
	s_and_b64 s[0:1], vcc, exec
	v_readlane_b32 s70, v254, 37
	v_readlane_b32 s36, v252, 15
	v_readlane_b32 s71, v254, 38
	v_readlane_b32 s37, v252, 16
	s_cselect_b32 s0, s70, s36
	s_mov_b32 s11, 0x4400000
	v_readlane_b32 s30, v254, 62
	s_cselect_b32 s1, s71, s37
	s_cselect_b32 s11, s11, 0x4800000
	v_readlane_b32 s31, v254, 63
	s_add_u32 s0, s0, s30
	s_addc_u32 s1, s1, s31
	global_load_dwordx4 v[136:139], v218, s[0:1] offset:16
	global_load_dwordx4 v[140:143], v218, s[0:1]
	global_load_dwordx4 v[128:131], v218, s[0:1] offset:144
	global_load_dwordx4 v[132:135], v218, s[0:1] offset:128
	v_and_b32_e32 v177, 64, v214
	v_xor_b32_e32 v176, 16, v214
	v_add_u32_e32 v177, 64, v177
	v_cndmask_b32_e32 v223, 1.0, v215, vcc
	v_cmp_lt_i32_e32 vcc, v176, v177
	v_readlane_b32 s9, v254, 52
	s_add_u32 s11, s9, s11
	v_cndmask_b32_e32 v176, v214, v176, vcc
	v_lshlrev_b32_e32 v225, 2, v176
	v_xor_b32_e32 v176, 32, v214
	v_cmp_lt_i32_e32 vcc, v176, v177
	v_readlane_b32 s9, v254, 61
	s_addc_u32 s25, s9, 0
	v_cndmask_b32_e32 v176, v214, v176, vcc
	v_lshlrev_b32_e32 v224, 2, v176
	v_min_u32_e32 v176, 32, v222
	v_lshlrev_b64 v[228:229], v176, v[202:203]
	v_min_u32_e32 v177, 1, v228
	v_or_b32_e32 v177, v229, v177
	v_cvt_f32_u32_e32 v177, v177
	v_sub_u32_e32 v176, 32, v176
	s_lshl_b32 s0, s10, 9
	s_and_b32 s0, s0, 0x200
	v_ldexp_f32 v176, v177, v176
	v_mul_f32_e32 v176, 0x35800000, v176
	v_fmamk_f32 v176, v176, 0x3a800000, v210
	s_add_u32 s0, s11, s0
	v_rsq_f32_e32 v176, v176
	s_addc_u32 s1, s25, 0
	v_lshl_add_u64 v[206:207], s[0:1], 0, v[144:145]
	v_readlane_b32 s48, v252, 27
	v_mov_b32_e32 v228, v176
	v_pk_mul_f32 v[230:231], v[124:125], v[228:229] op_sel_hi:[1,0]
	v_pk_mul_f32 v[232:233], v[126:127], v[228:229] op_sel_hi:[1,0]
	v_pk_mul_f32 v[236:237], v[230:231], v[230:231]
	v_pk_mul_f32 v[234:235], v[232:233], v[232:233]
	v_pk_mul_f32 v[250:251], v[114:115], v[228:229] op_sel_hi:[1,0]
	v_pk_mov_b32 v[238:239], v[236:237], v[234:235] op_sel:[1,0]
	v_mov_b32_e32 v237, v235
	v_pk_add_f32 v[234:235], v[238:239], v[236:237]
	v_pk_mul_f32 v[236:237], v[120:121], v[228:229] op_sel_hi:[1,0]
	v_pk_mul_f32 v[238:239], v[122:123], v[228:229] op_sel_hi:[1,0]
	v_pk_mul_f32 v[242:243], v[236:237], v[236:237]
	v_pk_mul_f32 v[240:241], v[238:239], v[238:239]
	v_pk_add_f32 v[234:235], v[234:235], v[234:235] op_sel_hi:[0,1]
	v_pk_mov_b32 v[244:245], v[242:243], v[240:241] op_sel:[1,0]
	v_mov_b32_e32 v243, v241
	v_pk_add_f32 v[240:241], v[244:245], v[242:243]
	v_pk_mul_f32 v[244:245], v[116:117], v[228:229] op_sel_hi:[1,0]
	v_pk_mul_f32 v[242:243], v[118:119], v[228:229] op_sel_hi:[1,0]
	v_mul_f32_e32 v234, v244, v244
	v_pk_fma_f32 v[246:247], v[244:245], v[244:245], v[234:235] op_sel_hi:[1,1,0]
	v_mul_f32_e32 v234, v242, v242
	v_pk_add_f32 v[240:241], v[240:241], v[240:241] op_sel_hi:[0,1]
	v_pk_fma_f32 v[248:249], v[242:243], v[242:243], v[234:235] op_sel_hi:[1,1,0]
	v_pk_mul_f32 v[176:177], v[112:113], v[228:229] op_sel_hi:[1,0]
	v_mul_f32_e32 v234, v250, v250
	v_mul_f32_e32 v246, v176, v176
	v_mul_f32_e32 v248, v177, v177
	v_mul_f32_e32 v240, v251, v251
	v_pk_add_f32 v[228:229], v[246:247], v[248:249]
	v_pk_add_f32 v[234:235], v[234:235], v[240:241]
	v_lshl_add_u64 v[240:241], v[206:207], 0, v[204:205]
	v_pk_add_f32 v[228:229], v[228:229], v[234:235]
	v_readlane_b32 s57, v254, 24
	v_add_f32_e32 v228, v228, v229
	ds_bpermute_b32 v229, v225, v228
	v_readlane_b32 s58, v254, 25
	v_readlane_b32 s59, v254, 26
	v_readlane_b32 s60, v254, 27
	v_readlane_b32 s61, v254, 28
	s_waitcnt lgkmcnt(0)
	v_add_f32_e32 v228, v228, v229
	ds_bpermute_b32 v229, v224, v228
	v_readlane_b32 s62, v254, 29
	v_readlane_b32 s63, v254, 30
	v_readlane_b32 s64, v254, 31
	v_readlane_b32 s65, v254, 32
	s_waitcnt lgkmcnt(0)
	v_add_f32_e32 v228, v228, v229
	v_fmamk_f32 v228, v228, 0x3c800000, v210
	v_readlane_b32 s66, v254, 33
	v_rsq_f32_e32 v228, v228
	v_readlane_b32 s67, v254, 34
	v_readlane_b32 s68, v254, 35
	v_readlane_b32 s69, v254, 36
	v_mul_f32_e32 v234, v223, v228
	v_pk_mul_f32 v[228:229], v[230:231], v[234:235] op_sel_hi:[1,0]
	v_pk_mul_f32 v[230:231], v[232:233], v[234:235] op_sel_hi:[1,0]
	s_waitcnt vmcnt(2)
	v_pk_mul_f32 v[228:229], v[140:141], v[228:229]
	v_pk_mul_f32 v[230:231], v[142:143], v[230:231]
	v_pk_mul_f32 v[232:233], v[236:237], v[234:235] op_sel_hi:[1,0]
	v_pk_mul_f32 v[236:237], v[238:239], v[234:235] op_sel_hi:[1,0]
	v_cvt_pk_bf16_f32 v228, v228, v229
	v_cvt_pk_bf16_f32 v229, v230, v231
	v_pk_mul_f32 v[232:233], v[136:137], v[232:233]
	v_pk_mul_f32 v[236:237], v[138:139], v[236:237]
	v_cvt_pk_bf16_f32 v230, v232, v233
	v_pk_mul_f32 v[176:177], v[176:177], v[234:235] op_sel_hi:[1,0]
	v_cvt_pk_bf16_f32 v231, v236, v237
	global_store_dwordx4 v[240:241], v[228:231], off
	v_pk_mul_f32 v[232:233], v[250:251], v[234:235] op_sel_hi:[1,0]
	s_waitcnt vmcnt(2)
	v_pk_mul_f32 v[176:177], v[128:129], v[176:177]
	v_pk_mul_f32 v[228:229], v[244:245], v[234:235] op_sel_hi:[1,0]
	v_pk_mul_f32 v[230:231], v[242:243], v[234:235] op_sel_hi:[1,0]
	s_waitcnt vmcnt(1)
	v_pk_mul_f32 v[228:229], v[132:133], v[228:229]
	v_pk_mul_f32 v[230:231], v[134:135], v[230:231]
	v_cvt_pk_bf16_f32 v228, v228, v229
	v_pk_mul_f32 v[232:233], v[130:131], v[232:233]
	v_cvt_pk_bf16_f32 v229, v230, v231
	v_cvt_pk_bf16_f32 v230, v176, v177
	s_nop 1
	v_readlane_b32 s38, v252, 17
	v_cvt_pk_bf16_f32 v231, v232, v233
	s_nop 1
	global_store_dwordx4 v[240:241], v[228:231], off offset:64
	v_readlane_b32 s39, v252, 18
	v_readlane_b32 s40, v252, 19
	v_min_u32_e32 v228, 32, v221
	v_lshlrev_b64 v[176:177], v228, v[200:201]
	v_min_u32_e32 v176, 1, v176
	v_or_b32_e32 v176, v177, v176
	v_cvt_f32_u32_e32 v176, v176
	v_sub_u32_e32 v177, 32, v228
	v_readlane_b32 s41, v252, 20
	v_readlane_b32 s42, v252, 21
	v_ldexp_f32 v176, v176, v177
	v_mul_f32_e32 v176, 0x35800000, v176
	v_fmamk_f32 v176, v176, 0x3a800000, v210
	v_readlane_b32 s43, v252, 22
	v_rsq_f32_e32 v176, v176
	v_readlane_b32 s44, v252, 23
	v_readlane_b32 s45, v252, 24
	v_readlane_b32 s46, v252, 25
	v_pk_mul_f32 v[228:229], v[108:109], v[176:177] op_sel_hi:[1,0]
	v_pk_mul_f32 v[230:231], v[110:111], v[176:177] op_sel_hi:[1,0]
	v_pk_mul_f32 v[234:235], v[228:229], v[228:229]
	v_pk_mul_f32 v[232:233], v[230:231], v[230:231]
	v_pk_mul_f32 v[248:249], v[98:99], v[176:177] op_sel_hi:[1,0]
	v_pk_mov_b32 v[236:237], v[234:235], v[232:233] op_sel:[1,0]
	v_mov_b32_e32 v235, v233
	v_pk_add_f32 v[232:233], v[236:237], v[234:235]
	v_pk_mul_f32 v[234:235], v[104:105], v[176:177] op_sel_hi:[1,0]
	v_pk_mul_f32 v[236:237], v[106:107], v[176:177] op_sel_hi:[1,0]
	v_pk_mul_f32 v[240:241], v[234:235], v[234:235]
	v_pk_mul_f32 v[238:239], v[236:237], v[236:237]
	v_pk_add_f32 v[232:233], v[232:233], v[232:233] op_sel_hi:[0,1]
	v_pk_mov_b32 v[242:243], v[240:241], v[238:239] op_sel:[1,0]
	v_mov_b32_e32 v241, v239
	v_pk_add_f32 v[238:239], v[242:243], v[240:241]
	v_pk_mul_f32 v[242:243], v[100:101], v[176:177] op_sel_hi:[1,0]
	v_pk_mul_f32 v[240:241], v[102:103], v[176:177] op_sel_hi:[1,0]
	v_mul_f32_e32 v232, v242, v242
	v_pk_fma_f32 v[244:245], v[242:243], v[242:243], v[232:233] op_sel_hi:[1,1,0]
	v_mul_f32_e32 v232, v240, v240
	v_pk_add_f32 v[238:239], v[238:239], v[238:239] op_sel_hi:[0,1]
	v_pk_fma_f32 v[246:247], v[240:241], v[240:241], v[232:233] op_sel_hi:[1,1,0]
	v_pk_mul_f32 v[176:177], v[96:97], v[176:177] op_sel_hi:[1,0]
	v_mul_f32_e32 v232, v248, v248
	v_mul_f32_e32 v244, v176, v176
	v_mul_f32_e32 v246, v177, v177
	v_mul_f32_e32 v238, v249, v249
	v_pk_add_f32 v[244:245], v[244:245], v[246:247]
	v_pk_add_f32 v[232:233], v[232:233], v[238:239]
	v_lshl_add_u64 v[238:239], v[206:207], 0, v[198:199]
	v_pk_add_f32 v[232:233], v[244:245], v[232:233]
	v_readlane_b32 s47, v252, 26
	v_add_f32_e32 v232, v232, v233
	ds_bpermute_b32 v233, v225, v232
	v_readlane_b32 s49, v252, 28
	v_readlane_b32 s50, v252, 29
	v_readlane_b32 s51, v252, 30
	v_readlane_b32 s48, v252, 40
	s_waitcnt lgkmcnt(0)
	v_add_f32_e32 v232, v232, v233
	ds_bpermute_b32 v233, v224, v232
	s_mov_b64 s[0:1], 0
	s_waitcnt lgkmcnt(0)
	v_add_f32_e32 v232, v232, v233
	v_fmamk_f32 v232, v232, 0x3c800000, v210
	s_nop 0
	v_rsq_f32_e32 v232, v232
	s_nop 0
	v_mul_f32_e32 v232, v223, v232
	v_pk_mul_f32 v[228:229], v[228:229], v[232:233] op_sel_hi:[1,0]
	v_pk_mul_f32 v[230:231], v[230:231], v[232:233] op_sel_hi:[1,0]
	v_pk_mul_f32 v[228:229], v[140:141], v[228:229]
	v_pk_mul_f32 v[230:231], v[142:143], v[230:231]
	v_pk_mul_f32 v[234:235], v[234:235], v[232:233] op_sel_hi:[1,0]
	v_pk_mul_f32 v[236:237], v[236:237], v[232:233] op_sel_hi:[1,0]
	v_cvt_pk_bf16_f32 v228, v228, v229
	v_cvt_pk_bf16_f32 v229, v230, v231
	v_pk_mul_f32 v[234:235], v[136:137], v[234:235]
	v_pk_mul_f32 v[236:237], v[138:139], v[236:237]
	v_cvt_pk_bf16_f32 v230, v234, v235
	v_pk_mul_f32 v[176:177], v[176:177], v[232:233] op_sel_hi:[1,0]
	v_cvt_pk_bf16_f32 v231, v236, v237
	global_store_dwordx4 v[238:239], v[228:231], off
	v_pk_mul_f32 v[176:177], v[128:129], v[176:177]
	s_nop 0
	v_pk_mul_f32 v[228:229], v[242:243], v[232:233] op_sel_hi:[1,0]
	v_pk_mul_f32 v[230:231], v[240:241], v[232:233] op_sel_hi:[1,0]
	v_pk_mul_f32 v[228:229], v[132:133], v[228:229]
	v_pk_mul_f32 v[230:231], v[134:135], v[230:231]
	v_pk_mul_f32 v[232:233], v[248:249], v[232:233] op_sel_hi:[1,0]
	v_cvt_pk_bf16_f32 v228, v228, v229
	v_cvt_pk_bf16_f32 v229, v230, v231
	v_cvt_pk_bf16_f32 v230, v176, v177
	s_nop 0
	v_pk_mul_f32 v[232:233], v[130:131], v[232:233]
	s_nop 0
	v_cvt_pk_bf16_f32 v231, v232, v233
	global_store_dwordx4 v[238:239], v[228:231], off offset:64
	s_nop 1
	v_min_u32_e32 v228, 32, v220
	v_lshlrev_b64 v[176:177], v228, v[192:193]
	v_min_u32_e32 v176, 1, v176
	v_or_b32_e32 v176, v177, v176
	v_cvt_f32_u32_e32 v176, v176
	v_sub_u32_e32 v177, 32, v228
	v_ldexp_f32 v176, v176, v177
	v_mul_f32_e32 v176, 0x35800000, v176
	v_fmamk_f32 v176, v176, 0x3a800000, v210
	s_nop 0
	v_rsq_f32_e32 v176, v176
	s_nop 0
	v_pk_mul_f32 v[228:229], v[92:93], v[176:177] op_sel_hi:[1,0]
	v_pk_mul_f32 v[230:231], v[94:95], v[176:177] op_sel_hi:[1,0]
	v_pk_mul_f32 v[234:235], v[228:229], v[228:229]
	v_pk_mul_f32 v[232:233], v[230:231], v[230:231]
	v_pk_mul_f32 v[248:249], v[82:83], v[176:177] op_sel_hi:[1,0]
	v_pk_mov_b32 v[236:237], v[234:235], v[232:233] op_sel:[1,0]
	v_mov_b32_e32 v235, v233
	v_pk_add_f32 v[232:233], v[236:237], v[234:235]
	v_pk_mul_f32 v[234:235], v[88:89], v[176:177] op_sel_hi:[1,0]
	v_pk_mul_f32 v[236:237], v[90:91], v[176:177] op_sel_hi:[1,0]
	v_pk_mul_f32 v[240:241], v[234:235], v[234:235]
	v_pk_mul_f32 v[238:239], v[236:237], v[236:237]
	v_pk_add_f32 v[232:233], v[232:233], v[232:233] op_sel_hi:[0,1]
	v_pk_mov_b32 v[242:243], v[240:241], v[238:239] op_sel:[1,0]
	v_mov_b32_e32 v241, v239
	v_pk_add_f32 v[238:239], v[242:243], v[240:241]
	v_pk_mul_f32 v[242:243], v[84:85], v[176:177] op_sel_hi:[1,0]
	v_pk_mul_f32 v[240:241], v[86:87], v[176:177] op_sel_hi:[1,0]
	v_mul_f32_e32 v232, v242, v242
	v_pk_fma_f32 v[244:245], v[242:243], v[242:243], v[232:233] op_sel_hi:[1,1,0]
	v_mul_f32_e32 v232, v240, v240
	v_pk_add_f32 v[238:239], v[238:239], v[238:239] op_sel_hi:[0,1]
	v_pk_fma_f32 v[246:247], v[240:241], v[240:241], v[232:233] op_sel_hi:[1,1,0]
	v_pk_mul_f32 v[176:177], v[80:81], v[176:177] op_sel_hi:[1,0]
	v_mul_f32_e32 v232, v248, v248
	v_mul_f32_e32 v244, v176, v176
	v_mul_f32_e32 v246, v177, v177
	v_mul_f32_e32 v238, v249, v249
	v_pk_add_f32 v[244:245], v[244:245], v[246:247]
	v_pk_add_f32 v[232:233], v[232:233], v[238:239]
	v_lshl_add_u64 v[238:239], v[206:207], 0, v[194:195]
	v_pk_add_f32 v[232:233], v[244:245], v[232:233]
	s_nop 0
	v_add_f32_e32 v232, v232, v233
	ds_bpermute_b32 v233, v225, v232
	s_waitcnt lgkmcnt(0)
	v_add_f32_e32 v232, v232, v233
	ds_bpermute_b32 v233, v224, v232
	s_waitcnt lgkmcnt(0)
	v_add_f32_e32 v232, v232, v233
	v_fmamk_f32 v232, v232, 0x3c800000, v210
	s_nop 0
	v_rsq_f32_e32 v232, v232
	s_nop 0
	v_mul_f32_e32 v232, v223, v232
	v_pk_mul_f32 v[228:229], v[228:229], v[232:233] op_sel_hi:[1,0]
	v_pk_mul_f32 v[230:231], v[230:231], v[232:233] op_sel_hi:[1,0]
	v_pk_mul_f32 v[228:229], v[140:141], v[228:229]
	v_pk_mul_f32 v[230:231], v[142:143], v[230:231]
	v_pk_mul_f32 v[234:235], v[234:235], v[232:233] op_sel_hi:[1,0]
	v_pk_mul_f32 v[236:237], v[236:237], v[232:233] op_sel_hi:[1,0]
	v_cvt_pk_bf16_f32 v228, v228, v229
	v_cvt_pk_bf16_f32 v229, v230, v231
	v_pk_mul_f32 v[234:235], v[136:137], v[234:235]
	v_pk_mul_f32 v[236:237], v[138:139], v[236:237]
	v_cvt_pk_bf16_f32 v230, v234, v235
	v_pk_mul_f32 v[176:177], v[176:177], v[232:233] op_sel_hi:[1,0]
	v_cvt_pk_bf16_f32 v231, v236, v237
	global_store_dwordx4 v[238:239], v[228:231], off
	v_pk_mul_f32 v[176:177], v[128:129], v[176:177]
	s_nop 0
	v_pk_mul_f32 v[228:229], v[242:243], v[232:233] op_sel_hi:[1,0]
	v_pk_mul_f32 v[230:231], v[240:241], v[232:233] op_sel_hi:[1,0]
	v_pk_mul_f32 v[228:229], v[132:133], v[228:229]
	v_pk_mul_f32 v[230:231], v[134:135], v[230:231]
	v_pk_mul_f32 v[232:233], v[248:249], v[232:233] op_sel_hi:[1,0]
	v_cvt_pk_bf16_f32 v228, v228, v229
	v_cvt_pk_bf16_f32 v229, v230, v231
	v_cvt_pk_bf16_f32 v230, v176, v177
	s_nop 0
	v_pk_mul_f32 v[232:233], v[130:131], v[232:233]
	s_nop 0
	v_cvt_pk_bf16_f32 v231, v232, v233
	global_store_dwordx4 v[238:239], v[228:231], off offset:64
	s_nop 1
	v_min_u32_e32 v228, 32, v219
	v_lshlrev_b64 v[176:177], v228, v[196:197]
	v_min_u32_e32 v176, 1, v176
	v_or_b32_e32 v176, v177, v176
	v_cvt_f32_u32_e32 v176, v176
	v_sub_u32_e32 v177, 32, v228
	v_ldexp_f32 v176, v176, v177
	v_mul_f32_e32 v176, 0x35800000, v176
	v_fmamk_f32 v176, v176, 0x3a800000, v210
	s_nop 0
	v_rsq_f32_e32 v176, v176
	s_nop 0
	v_pk_mul_f32 v[228:229], v[76:77], v[176:177] op_sel_hi:[1,0]
	v_pk_mul_f32 v[230:231], v[78:79], v[176:177] op_sel_hi:[1,0]
	v_pk_mul_f32 v[234:235], v[228:229], v[228:229]
	v_pk_mul_f32 v[232:233], v[230:231], v[230:231]
	v_pk_mul_f32 v[248:249], v[66:67], v[176:177] op_sel_hi:[1,0]
	v_pk_mov_b32 v[236:237], v[234:235], v[232:233] op_sel:[1,0]
	v_mov_b32_e32 v235, v233
	v_pk_add_f32 v[232:233], v[236:237], v[234:235]
	v_pk_mul_f32 v[234:235], v[72:73], v[176:177] op_sel_hi:[1,0]
	v_pk_mul_f32 v[236:237], v[74:75], v[176:177] op_sel_hi:[1,0]
	v_pk_mul_f32 v[240:241], v[234:235], v[234:235]
	v_pk_mul_f32 v[238:239], v[236:237], v[236:237]
	v_pk_add_f32 v[232:233], v[232:233], v[232:233] op_sel_hi:[0,1]
	v_pk_mov_b32 v[242:243], v[240:241], v[238:239] op_sel:[1,0]
	v_mov_b32_e32 v241, v239
	v_pk_add_f32 v[238:239], v[242:243], v[240:241]
	v_pk_mul_f32 v[242:243], v[68:69], v[176:177] op_sel_hi:[1,0]
	v_pk_mul_f32 v[240:241], v[70:71], v[176:177] op_sel_hi:[1,0]
	v_mul_f32_e32 v232, v242, v242
	v_pk_fma_f32 v[244:245], v[242:243], v[242:243], v[232:233] op_sel_hi:[1,1,0]
	v_mul_f32_e32 v232, v240, v240
	v_pk_add_f32 v[238:239], v[238:239], v[238:239] op_sel_hi:[0,1]
	v_pk_fma_f32 v[246:247], v[240:241], v[240:241], v[232:233] op_sel_hi:[1,1,0]
	v_pk_mul_f32 v[176:177], v[64:65], v[176:177] op_sel_hi:[1,0]
	v_mul_f32_e32 v232, v248, v248
	v_mul_f32_e32 v244, v176, v176
	v_mul_f32_e32 v246, v177, v177
	v_mul_f32_e32 v238, v249, v249
	v_pk_add_f32 v[244:245], v[244:245], v[246:247]
	v_pk_add_f32 v[232:233], v[232:233], v[238:239]
	v_lshl_add_u64 v[238:239], v[206:207], 0, v[190:191]
	v_pk_add_f32 v[232:233], v[244:245], v[232:233]
	s_nop 0
	v_add_f32_e32 v232, v232, v233
	ds_bpermute_b32 v233, v225, v232
	s_waitcnt lgkmcnt(0)
	v_add_f32_e32 v232, v232, v233
	ds_bpermute_b32 v233, v224, v232
	s_waitcnt lgkmcnt(0)
	v_add_f32_e32 v232, v232, v233
	v_fmamk_f32 v232, v232, 0x3c800000, v210
	s_nop 0
	v_rsq_f32_e32 v232, v232
	s_nop 0
	v_mul_f32_e32 v232, v223, v232
	v_pk_mul_f32 v[228:229], v[228:229], v[232:233] op_sel_hi:[1,0]
	v_pk_mul_f32 v[230:231], v[230:231], v[232:233] op_sel_hi:[1,0]
	v_pk_mul_f32 v[228:229], v[140:141], v[228:229]
	v_pk_mul_f32 v[230:231], v[142:143], v[230:231]
	v_pk_mul_f32 v[234:235], v[234:235], v[232:233] op_sel_hi:[1,0]
	v_pk_mul_f32 v[236:237], v[236:237], v[232:233] op_sel_hi:[1,0]
	v_pk_mul_f32 v[234:235], v[136:137], v[234:235]
	v_pk_mul_f32 v[236:237], v[138:139], v[236:237]
	v_cvt_pk_bf16_f32 v228, v228, v229
	v_cvt_pk_bf16_f32 v229, v230, v231
	v_cvt_pk_bf16_f32 v230, v234, v235
	v_pk_mul_f32 v[176:177], v[176:177], v[232:233] op_sel_hi:[1,0]
	v_cvt_pk_bf16_f32 v231, v236, v237
	global_store_dwordx4 v[238:239], v[228:231], off
	v_pk_mul_f32 v[176:177], v[128:129], v[176:177]
	s_nop 0
	v_pk_mul_f32 v[228:229], v[242:243], v[232:233] op_sel_hi:[1,0]
	v_pk_mul_f32 v[230:231], v[240:241], v[232:233] op_sel_hi:[1,0]
	v_pk_mul_f32 v[228:229], v[132:133], v[228:229]
	v_pk_mul_f32 v[230:231], v[134:135], v[230:231]
	v_pk_mul_f32 v[232:233], v[248:249], v[232:233] op_sel_hi:[1,0]
	v_cvt_pk_bf16_f32 v228, v228, v229
	v_cvt_pk_bf16_f32 v229, v230, v231
	v_cvt_pk_bf16_f32 v230, v176, v177
	v_ffbh_u32_e32 v176, v167
	v_pk_mul_f32 v[232:233], v[130:131], v[232:233]
	s_nop 0
	v_cvt_pk_bf16_f32 v231, v232, v233
	global_store_dwordx4 v[238:239], v[228:231], off offset:64
	s_nop 1
	v_min_u32_e32 v228, 32, v176
	v_lshlrev_b64 v[176:177], v228, v[166:167]
	v_min_u32_e32 v176, 1, v176
	v_or_b32_e32 v176, v177, v176
	v_cvt_f32_u32_e32 v176, v176
	v_sub_u32_e32 v177, 32, v228
	v_ldexp_f32 v176, v176, v177
	v_mul_f32_e32 v176, 0x35800000, v176
	v_fmamk_f32 v176, v176, 0x3a800000, v210
	s_nop 0
	v_rsq_f32_e32 v176, v176
	s_nop 0
	v_pk_mul_f32 v[228:229], v[60:61], v[176:177] op_sel_hi:[1,0]
	v_pk_mul_f32 v[230:231], v[62:63], v[176:177] op_sel_hi:[1,0]
	v_pk_mul_f32 v[234:235], v[228:229], v[228:229]
	v_pk_mul_f32 v[232:233], v[230:231], v[230:231]
	v_pk_mul_f32 v[248:249], v[50:51], v[176:177] op_sel_hi:[1,0]
	v_pk_mov_b32 v[236:237], v[234:235], v[232:233] op_sel:[1,0]
	v_mov_b32_e32 v235, v233
	v_pk_add_f32 v[232:233], v[236:237], v[234:235]
	v_pk_mul_f32 v[234:235], v[56:57], v[176:177] op_sel_hi:[1,0]
	v_pk_mul_f32 v[236:237], v[58:59], v[176:177] op_sel_hi:[1,0]
	v_pk_mul_f32 v[240:241], v[234:235], v[234:235]
	v_pk_mul_f32 v[238:239], v[236:237], v[236:237]
	v_pk_add_f32 v[232:233], v[232:233], v[232:233] op_sel_hi:[0,1]
	v_pk_mov_b32 v[242:243], v[240:241], v[238:239] op_sel:[1,0]
	v_mov_b32_e32 v241, v239
	v_pk_add_f32 v[238:239], v[242:243], v[240:241]
	v_pk_mul_f32 v[242:243], v[52:53], v[176:177] op_sel_hi:[1,0]
	v_pk_mul_f32 v[240:241], v[54:55], v[176:177] op_sel_hi:[1,0]
	v_mul_f32_e32 v232, v242, v242
	v_pk_fma_f32 v[244:245], v[242:243], v[242:243], v[232:233] op_sel_hi:[1,1,0]
	v_mul_f32_e32 v232, v240, v240
	v_pk_add_f32 v[238:239], v[238:239], v[238:239] op_sel_hi:[0,1]
	v_pk_fma_f32 v[246:247], v[240:241], v[240:241], v[232:233] op_sel_hi:[1,1,0]
	v_pk_mul_f32 v[176:177], v[48:49], v[176:177] op_sel_hi:[1,0]
	v_mul_f32_e32 v232, v248, v248
	v_mul_f32_e32 v244, v176, v176
	v_mul_f32_e32 v246, v177, v177
	v_mul_f32_e32 v238, v249, v249
	v_pk_add_f32 v[244:245], v[244:245], v[246:247]
	v_pk_add_f32 v[232:233], v[232:233], v[238:239]
	v_lshlrev_b64 v[238:239], 10, v[168:169]
	v_pk_add_f32 v[232:233], v[244:245], v[232:233]
	v_lshl_add_u64 v[238:239], v[206:207], 0, v[238:239]
	v_add_f32_e32 v232, v232, v233
	ds_bpermute_b32 v233, v225, v232
	s_waitcnt lgkmcnt(0)
	v_add_f32_e32 v232, v232, v233
	ds_bpermute_b32 v233, v224, v232
	s_waitcnt lgkmcnt(0)
	v_add_f32_e32 v232, v232, v233
	v_fmamk_f32 v232, v232, 0x3c800000, v210
	s_nop 0
	v_rsq_f32_e32 v232, v232
	s_nop 0
	v_mul_f32_e32 v232, v223, v232
	v_pk_mul_f32 v[228:229], v[228:229], v[232:233] op_sel_hi:[1,0]
	v_pk_mul_f32 v[230:231], v[230:231], v[232:233] op_sel_hi:[1,0]
	v_pk_mul_f32 v[228:229], v[140:141], v[228:229]
	v_pk_mul_f32 v[230:231], v[142:143], v[230:231]
	v_pk_mul_f32 v[234:235], v[234:235], v[232:233] op_sel_hi:[1,0]
	v_pk_mul_f32 v[236:237], v[236:237], v[232:233] op_sel_hi:[1,0]
	v_pk_mul_f32 v[234:235], v[136:137], v[234:235]
	v_pk_mul_f32 v[236:237], v[138:139], v[236:237]
	v_cvt_pk_bf16_f32 v228, v228, v229
	v_cvt_pk_bf16_f32 v229, v230, v231
	v_cvt_pk_bf16_f32 v230, v234, v235
	v_pk_mul_f32 v[176:177], v[176:177], v[232:233] op_sel_hi:[1,0]
	v_cvt_pk_bf16_f32 v231, v236, v237
	global_store_dwordx4 v[238:239], v[228:231], off
	v_pk_mul_f32 v[176:177], v[128:129], v[176:177]
	s_nop 0
	v_pk_mul_f32 v[228:229], v[242:243], v[232:233] op_sel_hi:[1,0]
	v_pk_mul_f32 v[230:231], v[240:241], v[232:233] op_sel_hi:[1,0]
	v_pk_mul_f32 v[228:229], v[132:133], v[228:229]
	v_pk_mul_f32 v[230:231], v[134:135], v[230:231]
	v_pk_mul_f32 v[232:233], v[248:249], v[232:233] op_sel_hi:[1,0]
	v_cvt_pk_bf16_f32 v228, v228, v229
	v_cvt_pk_bf16_f32 v229, v230, v231
	v_cvt_pk_bf16_f32 v230, v176, v177
	v_ffbh_u32_e32 v176, v189
	v_pk_mul_f32 v[232:233], v[130:131], v[232:233]
	s_nop 0
	v_cvt_pk_bf16_f32 v231, v232, v233
	global_store_dwordx4 v[238:239], v[228:231], off offset:64
	s_nop 1
	v_min_u32_e32 v228, 32, v176
	v_lshlrev_b64 v[176:177], v228, v[188:189]
	v_min_u32_e32 v176, 1, v176
	v_or_b32_e32 v176, v177, v176
	v_cvt_f32_u32_e32 v176, v176
	v_sub_u32_e32 v177, 32, v228
	v_ldexp_f32 v176, v176, v177
	v_mul_f32_e32 v176, 0x35800000, v176
	v_fmamk_f32 v176, v176, 0x3a800000, v210
	s_nop 0
	v_rsq_f32_e32 v176, v176
	s_nop 0
	v_pk_mul_f32 v[228:229], v[44:45], v[176:177] op_sel_hi:[1,0]
	v_pk_mul_f32 v[230:231], v[46:47], v[176:177] op_sel_hi:[1,0]
	v_pk_mul_f32 v[234:235], v[228:229], v[228:229]
	v_pk_mul_f32 v[232:233], v[230:231], v[230:231]
	v_pk_mul_f32 v[248:249], v[34:35], v[176:177] op_sel_hi:[1,0]
	v_pk_mov_b32 v[236:237], v[234:235], v[232:233] op_sel:[1,0]
	v_mov_b32_e32 v235, v233
	v_pk_add_f32 v[232:233], v[236:237], v[234:235]
	v_pk_mul_f32 v[234:235], v[40:41], v[176:177] op_sel_hi:[1,0]
	v_pk_mul_f32 v[236:237], v[42:43], v[176:177] op_sel_hi:[1,0]
	v_pk_mul_f32 v[240:241], v[234:235], v[234:235]
	v_pk_mul_f32 v[238:239], v[236:237], v[236:237]
	v_pk_add_f32 v[232:233], v[232:233], v[232:233] op_sel_hi:[0,1]
	v_pk_mov_b32 v[242:243], v[240:241], v[238:239] op_sel:[1,0]
	v_mov_b32_e32 v241, v239
	v_pk_add_f32 v[238:239], v[242:243], v[240:241]
	v_pk_mul_f32 v[242:243], v[36:37], v[176:177] op_sel_hi:[1,0]
	v_pk_mul_f32 v[240:241], v[38:39], v[176:177] op_sel_hi:[1,0]
	v_mul_f32_e32 v232, v242, v242
	v_pk_fma_f32 v[244:245], v[242:243], v[242:243], v[232:233] op_sel_hi:[1,1,0]
	v_mul_f32_e32 v232, v240, v240
	v_pk_add_f32 v[238:239], v[238:239], v[238:239] op_sel_hi:[0,1]
	v_pk_fma_f32 v[246:247], v[240:241], v[240:241], v[232:233] op_sel_hi:[1,1,0]
	v_pk_mul_f32 v[176:177], v[32:33], v[176:177] op_sel_hi:[1,0]
	v_mul_f32_e32 v232, v248, v248
	v_mul_f32_e32 v244, v176, v176
	v_mul_f32_e32 v246, v177, v177
	v_mul_f32_e32 v238, v249, v249
	v_pk_add_f32 v[244:245], v[244:245], v[246:247]
	v_pk_add_f32 v[232:233], v[232:233], v[238:239]
	v_lshlrev_b64 v[238:239], 10, v[164:165]
	v_pk_add_f32 v[232:233], v[244:245], v[232:233]
	v_lshl_add_u64 v[238:239], v[206:207], 0, v[238:239]
	v_add_f32_e32 v232, v232, v233
	ds_bpermute_b32 v233, v225, v232
	s_waitcnt lgkmcnt(0)
	v_add_f32_e32 v232, v232, v233
	ds_bpermute_b32 v233, v224, v232
	s_waitcnt lgkmcnt(0)
	v_add_f32_e32 v232, v232, v233
	v_fmamk_f32 v232, v232, 0x3c800000, v210
	s_nop 0
	v_rsq_f32_e32 v232, v232
	s_nop 0
	v_mul_f32_e32 v232, v223, v232
	v_pk_mul_f32 v[228:229], v[228:229], v[232:233] op_sel_hi:[1,0]
	v_pk_mul_f32 v[230:231], v[230:231], v[232:233] op_sel_hi:[1,0]
	v_pk_mul_f32 v[228:229], v[140:141], v[228:229]
	v_pk_mul_f32 v[230:231], v[142:143], v[230:231]
	v_pk_mul_f32 v[234:235], v[234:235], v[232:233] op_sel_hi:[1,0]
	v_pk_mul_f32 v[236:237], v[236:237], v[232:233] op_sel_hi:[1,0]
	v_pk_mul_f32 v[234:235], v[136:137], v[234:235]
	v_pk_mul_f32 v[236:237], v[138:139], v[236:237]
	v_cvt_pk_bf16_f32 v228, v228, v229
	v_cvt_pk_bf16_f32 v229, v230, v231
	v_cvt_pk_bf16_f32 v230, v234, v235
	v_pk_mul_f32 v[176:177], v[176:177], v[232:233] op_sel_hi:[1,0]
	v_cvt_pk_bf16_f32 v231, v236, v237
	global_store_dwordx4 v[238:239], v[228:231], off
	v_pk_mul_f32 v[176:177], v[128:129], v[176:177]
	s_nop 0
	v_pk_mul_f32 v[228:229], v[242:243], v[232:233] op_sel_hi:[1,0]
	v_pk_mul_f32 v[230:231], v[240:241], v[232:233] op_sel_hi:[1,0]
	v_pk_mul_f32 v[228:229], v[132:133], v[228:229]
	v_pk_mul_f32 v[230:231], v[134:135], v[230:231]
	v_pk_mul_f32 v[232:233], v[248:249], v[232:233] op_sel_hi:[1,0]
	v_cvt_pk_bf16_f32 v228, v228, v229
	v_cvt_pk_bf16_f32 v229, v230, v231
	v_cvt_pk_bf16_f32 v230, v176, v177
	v_ffbh_u32_e32 v176, v163
	v_pk_mul_f32 v[232:233], v[130:131], v[232:233]
	s_nop 0
	v_cvt_pk_bf16_f32 v231, v232, v233
	global_store_dwordx4 v[238:239], v[228:231], off offset:64
	s_nop 1
	v_min_u32_e32 v228, 32, v176
	v_lshlrev_b64 v[176:177], v228, v[162:163]
	v_min_u32_e32 v176, 1, v176
	v_or_b32_e32 v176, v177, v176
	v_cvt_f32_u32_e32 v176, v176
	v_sub_u32_e32 v177, 32, v228
	v_ldexp_f32 v176, v176, v177
	v_mul_f32_e32 v176, 0x35800000, v176
	v_fmamk_f32 v176, v176, 0x3a800000, v210
	s_nop 0
	v_rsq_f32_e32 v176, v176
	s_nop 0
	v_pk_mul_f32 v[228:229], v[28:29], v[176:177] op_sel_hi:[1,0]
	v_pk_mul_f32 v[230:231], v[30:31], v[176:177] op_sel_hi:[1,0]
	v_pk_mul_f32 v[234:235], v[228:229], v[228:229]
	v_pk_mul_f32 v[232:233], v[230:231], v[230:231]
	v_pk_mul_f32 v[248:249], v[18:19], v[176:177] op_sel_hi:[1,0]
	v_pk_mov_b32 v[236:237], v[234:235], v[232:233] op_sel:[1,0]
	v_mov_b32_e32 v235, v233
	v_pk_add_f32 v[232:233], v[236:237], v[234:235]
	v_pk_mul_f32 v[234:235], v[24:25], v[176:177] op_sel_hi:[1,0]
	v_pk_mul_f32 v[236:237], v[26:27], v[176:177] op_sel_hi:[1,0]
	v_pk_mul_f32 v[240:241], v[234:235], v[234:235]
	v_pk_mul_f32 v[238:239], v[236:237], v[236:237]
	v_pk_add_f32 v[232:233], v[232:233], v[232:233] op_sel_hi:[0,1]
	v_pk_mov_b32 v[242:243], v[240:241], v[238:239] op_sel:[1,0]
	v_mov_b32_e32 v241, v239
	v_pk_add_f32 v[238:239], v[242:243], v[240:241]
	v_pk_mul_f32 v[242:243], v[20:21], v[176:177] op_sel_hi:[1,0]
	v_pk_mul_f32 v[240:241], v[22:23], v[176:177] op_sel_hi:[1,0]
	v_mul_f32_e32 v232, v242, v242
	v_pk_fma_f32 v[244:245], v[242:243], v[242:243], v[232:233] op_sel_hi:[1,1,0]
	v_mul_f32_e32 v232, v240, v240
	v_pk_add_f32 v[238:239], v[238:239], v[238:239] op_sel_hi:[0,1]
	v_pk_fma_f32 v[246:247], v[240:241], v[240:241], v[232:233] op_sel_hi:[1,1,0]
	v_pk_mul_f32 v[176:177], v[16:17], v[176:177] op_sel_hi:[1,0]
	v_mul_f32_e32 v232, v248, v248
	v_mul_f32_e32 v244, v176, v176
	v_mul_f32_e32 v246, v177, v177
	v_mul_f32_e32 v238, v249, v249
	v_pk_add_f32 v[244:245], v[244:245], v[246:247]
	v_pk_add_f32 v[232:233], v[232:233], v[238:239]
	v_lshlrev_b64 v[238:239], 10, v[158:159]
	v_pk_add_f32 v[232:233], v[244:245], v[232:233]
	v_lshl_add_u64 v[238:239], v[206:207], 0, v[238:239]
	v_add_f32_e32 v232, v232, v233
	ds_bpermute_b32 v233, v225, v232
	s_waitcnt lgkmcnt(0)
	v_add_f32_e32 v232, v232, v233
	ds_bpermute_b32 v233, v224, v232
	s_waitcnt lgkmcnt(0)
	v_add_f32_e32 v232, v232, v233
	v_fmamk_f32 v232, v232, 0x3c800000, v210
	s_nop 0
	v_rsq_f32_e32 v232, v232
	s_nop 0
	v_mul_f32_e32 v232, v223, v232
	v_pk_mul_f32 v[228:229], v[228:229], v[232:233] op_sel_hi:[1,0]
	v_pk_mul_f32 v[230:231], v[230:231], v[232:233] op_sel_hi:[1,0]
	v_pk_mul_f32 v[228:229], v[140:141], v[228:229]
	v_pk_mul_f32 v[230:231], v[142:143], v[230:231]
	v_pk_mul_f32 v[234:235], v[234:235], v[232:233] op_sel_hi:[1,0]
	v_pk_mul_f32 v[236:237], v[236:237], v[232:233] op_sel_hi:[1,0]
	v_pk_mul_f32 v[234:235], v[136:137], v[234:235]
	v_pk_mul_f32 v[236:237], v[138:139], v[236:237]
	v_cvt_pk_bf16_f32 v228, v228, v229
	v_cvt_pk_bf16_f32 v229, v230, v231
	v_cvt_pk_bf16_f32 v230, v234, v235
	v_pk_mul_f32 v[176:177], v[176:177], v[232:233] op_sel_hi:[1,0]
	v_cvt_pk_bf16_f32 v231, v236, v237
	global_store_dwordx4 v[238:239], v[228:231], off
	v_pk_mul_f32 v[176:177], v[128:129], v[176:177]
	s_nop 0
	v_pk_mul_f32 v[228:229], v[242:243], v[232:233] op_sel_hi:[1,0]
	v_pk_mul_f32 v[230:231], v[240:241], v[232:233] op_sel_hi:[1,0]
	v_pk_mul_f32 v[228:229], v[132:133], v[228:229]
	v_pk_mul_f32 v[230:231], v[134:135], v[230:231]
	v_pk_mul_f32 v[232:233], v[248:249], v[232:233] op_sel_hi:[1,0]
	v_cvt_pk_bf16_f32 v228, v228, v229
	v_cvt_pk_bf16_f32 v229, v230, v231
	v_cvt_pk_bf16_f32 v230, v176, v177
	v_ffbh_u32_e32 v176, v161
	v_pk_mul_f32 v[232:233], v[130:131], v[232:233]
	s_nop 0
	v_cvt_pk_bf16_f32 v231, v232, v233
	global_store_dwordx4 v[238:239], v[228:231], off offset:64
	s_nop 1
	v_min_u32_e32 v228, 32, v176
	v_lshlrev_b64 v[176:177], v228, v[160:161]
	v_min_u32_e32 v176, 1, v176
	v_or_b32_e32 v176, v177, v176
	v_cvt_f32_u32_e32 v176, v176
	v_sub_u32_e32 v177, 32, v228
	v_ldexp_f32 v176, v176, v177
	v_mul_f32_e32 v176, 0x35800000, v176
	v_fmamk_f32 v176, v176, 0x3a800000, v210
	s_nop 0
	v_rsq_f32_e32 v176, v176
	s_nop 0
	v_pk_mul_f32 v[228:229], v[12:13], v[176:177] op_sel_hi:[1,0]
	v_pk_mul_f32 v[230:231], v[14:15], v[176:177] op_sel_hi:[1,0]
	v_pk_mul_f32 v[234:235], v[228:229], v[228:229]
	v_pk_mul_f32 v[232:233], v[230:231], v[230:231]
	v_pk_mul_f32 v[248:249], v[2:3], v[176:177] op_sel_hi:[1,0]
	v_pk_mov_b32 v[236:237], v[234:235], v[232:233] op_sel:[1,0]
	v_mov_b32_e32 v235, v233
	v_pk_add_f32 v[232:233], v[236:237], v[234:235]
	v_pk_mul_f32 v[234:235], v[8:9], v[176:177] op_sel_hi:[1,0]
	v_pk_mul_f32 v[236:237], v[10:11], v[176:177] op_sel_hi:[1,0]
	v_pk_mul_f32 v[240:241], v[234:235], v[234:235]
	v_pk_mul_f32 v[238:239], v[236:237], v[236:237]
	v_pk_add_f32 v[232:233], v[232:233], v[232:233] op_sel_hi:[0,1]
	v_pk_mov_b32 v[242:243], v[240:241], v[238:239] op_sel:[1,0]
	v_mov_b32_e32 v241, v239
	v_pk_add_f32 v[238:239], v[242:243], v[240:241]
	v_pk_mul_f32 v[242:243], v[4:5], v[176:177] op_sel_hi:[1,0]
	v_pk_mul_f32 v[240:241], v[6:7], v[176:177] op_sel_hi:[1,0]
	v_mul_f32_e32 v232, v242, v242
	v_pk_fma_f32 v[244:245], v[242:243], v[242:243], v[232:233] op_sel_hi:[1,1,0]
	v_mul_f32_e32 v232, v240, v240
	v_pk_add_f32 v[238:239], v[238:239], v[238:239] op_sel_hi:[0,1]
	v_pk_fma_f32 v[246:247], v[240:241], v[240:241], v[232:233] op_sel_hi:[1,1,0]
	v_pk_mul_f32 v[176:177], v[0:1], v[176:177] op_sel_hi:[1,0]
	v_mul_f32_e32 v232, v248, v248
	v_mul_f32_e32 v244, v176, v176
	v_mul_f32_e32 v246, v177, v177
	v_mul_f32_e32 v238, v249, v249
	v_pk_add_f32 v[244:245], v[244:245], v[246:247]
	v_pk_add_f32 v[232:233], v[232:233], v[238:239]
	s_nop 0
	v_pk_add_f32 v[232:233], v[244:245], v[232:233]
	s_nop 0
	v_add_f32_e32 v232, v232, v233
	ds_bpermute_b32 v225, v225, v232
	s_waitcnt lgkmcnt(0)
	v_add_f32_e32 v225, v232, v225
	ds_bpermute_b32 v224, v224, v225
	v_lshlrev_b64 v[232:233], 10, v[156:157]
	v_lshl_add_u64 v[206:207], v[206:207], 0, v[232:233]
	s_waitcnt lgkmcnt(0)
	v_add_f32_e32 v224, v225, v224
	v_fmamk_f32 v224, v224, 0x3c800000, v210
	s_nop 0
	v_rsq_f32_e32 v224, v224
	s_nop 0
	v_mul_f32_e32 v224, v223, v224
	v_pk_mul_f32 v[228:229], v[228:229], v[224:225] op_sel_hi:[1,0]
	v_pk_mul_f32 v[230:231], v[230:231], v[224:225] op_sel_hi:[1,0]
	v_pk_mul_f32 v[140:141], v[140:141], v[228:229]
	v_pk_mul_f32 v[142:143], v[142:143], v[230:231]
	v_pk_mul_f32 v[228:229], v[234:235], v[224:225] op_sel_hi:[1,0]
	v_pk_mul_f32 v[230:231], v[236:237], v[224:225] op_sel_hi:[1,0]
	s_nop 0
	v_pk_mul_f32 v[230:231], v[138:139], v[230:231]
	v_pk_mul_f32 v[138:139], v[136:137], v[228:229]
	v_cvt_pk_bf16_f32 v136, v140, v141
	v_cvt_pk_bf16_f32 v137, v142, v143
	s_nop 0
	v_cvt_pk_bf16_f32 v138, v138, v139
	v_cvt_pk_bf16_f32 v139, v230, v231
	global_store_dwordx4 v[206:207], v[136:139], off
	s_nop 1
	v_pk_mul_f32 v[136:137], v[242:243], v[224:225] op_sel_hi:[1,0]
	v_pk_mul_f32 v[138:139], v[240:241], v[224:225] op_sel_hi:[1,0]
	v_pk_mul_f32 v[132:133], v[132:133], v[136:137]
	v_pk_mul_f32 v[134:135], v[134:135], v[138:139]
	v_pk_mul_f32 v[136:137], v[176:177], v[224:225] op_sel_hi:[1,0]
	v_pk_mul_f32 v[138:139], v[248:249], v[224:225] op_sel_hi:[1,0]
	s_nop 0
	v_pk_mul_f32 v[138:139], v[130:131], v[138:139]
	v_pk_mul_f32 v[130:131], v[128:129], v[136:137]
	v_cvt_pk_bf16_f32 v128, v132, v133
	v_cvt_pk_bf16_f32 v129, v134, v135
	s_nop 0
	v_cvt_pk_bf16_f32 v130, v130, v131
	v_cvt_pk_bf16_f32 v131, v138, v139
	s_nop 1

.LBB0_331:
	s_setprio 0
	s_waitcnt vmcnt(0)
	v_readlane_b32 s58, v254, 55
	v_readlane_b32 s0, v254, 57
	v_readlane_b32 s59, v254, 56
	v_readlane_b32 s96, v254, 44
	s_cmpk_gt_u32 s0, 0xff
	s_mov_b32 s49, s59
	v_readlane_b32 s9, v254, 43
	v_readlane_b32 s97, v254, 45
	s_cbranch_scc1 .LBB0_333
	s_barrier

.LBB0_341:
	s_lshl_b64 s[30:31], s[36:37], 13
	s_sub_u32 s30, 0, s30
	s_subb_u32 s31, 0, s31
	s_add_u32 s30, s22, s30
	v_readlane_b32 s22, v254, 54
	s_addc_u32 s31, s22, s31
	s_add_u32 s42, s30, 0x4c00000
	s_addc_u32 s43, s31, 0
	v_bfe_u32 v16, v8, 4, 2
	s_add_u32 s44, s30, 0x5000000
	v_and_b32_e32 v15, 15, v8
	v_lshlrev_b32_e32 v17, 4, v16
	v_lshlrev_b32_e32 v18, 2, v8
	s_addc_u32 s45, s31, 0
	v_lshl_or_b32 v190, s25, 6, v15
	v_lshl_or_b32 v17, v15, 6, v17
	s_lshl_b32 s25, s25, 13
	v_and_b32_e32 v18, 32, v18
	v_bitop3_b32 v19, v17, s25, v18 bitop3:0xde
	s_lshl_b32 s25, s27, 5
	s_and_b32 s79, s25, 0x60
	s_add_i32 m0, s77, 0x18000
	v_lshl_add_u64 v[6:7], v[6:7], 0, s[18:19]
	s_lshl_b32 s25, s79, 7
	s_waitcnt vmcnt(4)
	s_barrier
	global_load_lds_dwordx4 v[6:7], off
	v_lshl_add_u64 v[4:5], v[4:5], 0, s[18:19]
	s_add_i32 m0, s77, 0x1a000
	s_add_i32 s80, s77, 0x8000
	s_add_i32 s83, s77, 0xa000
	global_load_lds_dwordx4 v[4:5], off
	v_lshl_add_u64 v[2:3], v[2:3], 0, s[18:19]
	s_mov_b32 m0, s80
	s_add_u32 s30, s50, 0x40080
	global_load_lds_dwordx4 v[2:3], off
	v_lshl_add_u64 v[0:1], v[0:1], 0, s[18:19]
	s_mov_b32 m0, s83
	s_addc_u32 s31, s51, 0
	global_load_lds_dwordx4 v[0:1], off
	s_add_i32 m0, s77, 0x1c000
	v_lshl_add_u64 v[0:1], s[30:31], 0, v[148:149]
	global_load_lds_dwordx4 v[0:1], off
	v_lshl_add_u64 v[0:1], s[30:31], 0, v[152:153]
	s_add_i32 m0, s77, 0x1e000
	v_and_b32_e32 v3, 1, v9
	global_load_lds_dwordx4 v[0:1], off
	v_lshrrev_b32_e32 v1, 2, v8
	v_and_b32_e32 v2, 4, v1
	v_lshlrev_b32_e32 v1, 14, v9
	v_and_b32_e32 v1, 0xffff8000, v1
	v_lshl_add_u32 v1, v10, 11, v1
	v_lshl_or_b32 v1, v3, 6, v1
	v_lshl_add_u32 v156, v11, 1, v1
	v_lshlrev_b32_e32 v1, 14, v12
	v_and_b32_e32 v1, 0xffff8000, v1
	v_lshlrev_b32_e32 v191, 3, v16
	s_waitcnt vmcnt(6)
	v_readlane_b32 s30, v252, 36
	v_lshl_add_u32 v1, v13, 11, v1
	v_and_b32_e32 v3, 1, v12
	v_and_b32_e32 v0, 16, v191
	v_lshlrev_b32_e32 v144, 6, v16
	v_readlane_b32 s31, v252, 37
	v_lshl_or_b32 v1, v3, 6, v1
	s_sext_i32_i16 s11, s38
	v_bitop3_b32 v192, v17, s25, v18 bitop3:0xde
	v_add_u32_e32 v193, 0xfffffe00, v190
	s_mov_b32 s84, 0
	v_cmp_eq_u32_e64 s[38:39], 0, v15
	v_lshl_add_u64 v[154:155], s[30:31], 0, v[144:145]
	v_mov_b32_e32 v157, v145
	v_lshl_add_u32 v158, v14, 1, v1
	v_mov_b32_e32 v159, v145
	v_add_u32_e32 v194, 0, v19
	v_lshlrev_b32_e32 v144, 1, v0
	v_lshlrev_b32_e32 v160, 1, v2
	s_barrier
	v_readfirstlane_b32 s101, v208
	s_nop 3
	s_lshr_b32 s101, s101, 8
	s_cmp_eq_u32 s101, 0
	s_cbranch_scc1 .Lprio_a2_done
	s_setprio 1
.Lprio_a2_done:
	s_branch .LBB0_344
.LBB0_342:
	s_or_b64 exec, exec, s[0:1]

.LBB0_350:
	s_lshl_b32 s25, s84, 1
	s_add_i32 s25, s85, s25
	s_and_b32 s85, s25, 3
	s_lshl_b32 s25, s85, 19
	s_add_u32 s92, s74, s25
	v_cmp_lt_i64_e32 vcc, s[52:53], v[180:181]
	s_addc_u32 s93, s75, 0
	s_and_b64 s[30:31], vcc, exec
	s_cselect_b32 s25, s93, s1
	s_cselect_b32 s30, s92, s0
	s_ashr_i32 s47, s46, 31
	s_lshl_b64 s[34:35], s[46:47], 19
	s_add_u32 s94, s54, s34
	s_addc_u32 s95, s55, s35
	s_and_b64 s[34:35], vcc, exec
	s_cselect_b32 s31, s95, s51
	s_cselect_b32 s33, s94, s50
	s_add_u32 s0, s0, 0x40080
	s_addc_u32 s1, s1, 0
	s_add_u32 s34, s50, 0x100
	s_addc_u32 s35, s51, 0
	s_mov_b32 s36, -2
	s_add_u32 s27, s0, 0xfffc0080
	s_addc_u32 s37, s1, -1
	s_add_i32 s47, 0, 0x10000
	v_add_u32_e32 v140, s47, v192
	ds_read_b128 v[128:131], v140
	ds_read_b128 v[132:135], v140 offset:1024
	ds_read_b128 v[136:139], v140 offset:2048
	ds_read_b128 v[140:143], v140 offset:3072
	s_cmp_eq_u32 s36, 12
	s_cselect_b32 s53, s25, s37
	s_cselect_b32 s52, s30, s27
	s_cselect_b32 s51, s31, s35
	s_cselect_b32 s50, s33, s34
	v_lshl_add_u64 v[176:177], s[0:1], 0, v[156:157]
	s_add_i32 m0, s77, 0xc000
	ds_read_b128 v[162:165], v194
	ds_read_b128 v[166:169], v194 offset:1024
	ds_read_b128 v[196:199], v194 offset:2048
	ds_read_b128 v[200:203], v194 offset:3072
	ds_read_b128 v[204:207], v194 offset:4096
	ds_read_b128 v[216:219], v194 offset:5120
	ds_read_b128 v[220:223], v194 offset:6144
	ds_read_b128 v[228:231], v194 offset:7168
	global_load_lds_dwordx4 v[176:177], off
	v_lshl_add_u64 v[176:177], s[0:1], 0, v[158:159]
	s_add_i32 m0, s77, 0xe000
	s_nop 0
	global_load_lds_dwordx4 v[176:177], off
	s_waitcnt lgkmcnt(8)
	s_barrier
	s_waitcnt lgkmcnt(0)
	v_mfma_f32_16x16x32_bf16 v[124:127], v[128:131], v[162:165], 0
	v_mfma_f32_16x16x32_bf16 v[120:123], v[136:139], v[162:165], 0
	v_mfma_f32_16x16x32_bf16 v[116:119], v[128:131], v[196:199], 0
	v_mfma_f32_16x16x32_bf16 v[112:115], v[136:139], v[196:199], 0
	v_mfma_f32_16x16x32_bf16 v[108:111], v[128:131], v[204:207], 0
	v_mfma_f32_16x16x32_bf16 v[104:107], v[136:139], v[204:207], 0
	v_mfma_f32_16x16x32_bf16 v[100:103], v[128:131], v[220:223], 0
	v_mfma_f32_16x16x32_bf16 v[96:99], v[136:139], v[220:223], 0
	v_mfma_f32_16x16x32_bf16 v[124:127], v[132:135], v[166:169], v[124:127]
	v_mfma_f32_16x16x32_bf16 v[120:123], v[140:143], v[166:169], v[120:123]
	v_mfma_f32_16x16x32_bf16 v[116:119], v[132:135], v[200:203], v[116:119]
	v_mfma_f32_16x16x32_bf16 v[112:115], v[140:143], v[200:203], v[112:115]
	v_mfma_f32_16x16x32_bf16 v[108:111], v[132:135], v[216:219], v[108:111]
	v_mfma_f32_16x16x32_bf16 v[104:107], v[140:143], v[216:219], v[104:107]
	v_mfma_f32_16x16x32_bf16 v[100:103], v[132:135], v[228:231], v[100:103]
	v_mfma_f32_16x16x32_bf16 v[96:99], v[140:143], v[228:231], v[96:99]
	s_barrier
	s_add_i32 s27, 0, 0x14000
	s_add_i32 s37, s47, s76
	v_add_u32_e32 v161, s27, v192
	v_lshl_add_u64 v[176:177], s[50:51], 0, v[148:149]
	s_mov_b32 m0, s37
	ds_read_b128 v[232:235], v161
	ds_read_b128 v[236:239], v161 offset:1024
	ds_read_b128 v[240:243], v161 offset:2048
	ds_read_b128 v[244:247], v161 offset:3072
	global_load_lds_dwordx4 v[176:177], off
	v_lshl_add_u64 v[188:189], s[50:51], 0, v[152:153]
	s_add_i32 m0, s37, 0x2000
	s_nop 0
	global_load_lds_dwordx4 v[188:189], off
	s_barrier
	s_waitcnt lgkmcnt(0)
	v_mfma_f32_16x16x32_bf16 v[92:95], v[232:235], v[162:165], 0
	v_mfma_f32_16x16x32_bf16 v[88:91], v[240:243], v[162:165], 0
	v_mfma_f32_16x16x32_bf16 v[84:87], v[232:235], v[196:199], 0
	v_mfma_f32_16x16x32_bf16 v[80:83], v[240:243], v[196:199], 0
	v_mfma_f32_16x16x32_bf16 v[76:79], v[232:235], v[204:207], 0
	v_mfma_f32_16x16x32_bf16 v[72:75], v[240:243], v[204:207], 0
	v_mfma_f32_16x16x32_bf16 v[68:71], v[232:235], v[220:223], 0
	v_mfma_f32_16x16x32_bf16 v[64:67], v[240:243], v[220:223], 0
	v_mfma_f32_16x16x32_bf16 v[92:95], v[236:239], v[166:169], v[92:95]
	v_mfma_f32_16x16x32_bf16 v[88:91], v[244:247], v[166:169], v[88:91]
	v_mfma_f32_16x16x32_bf16 v[84:87], v[236:239], v[200:203], v[84:87]
	v_mfma_f32_16x16x32_bf16 v[80:83], v[244:247], v[200:203], v[80:83]
	v_mfma_f32_16x16x32_bf16 v[76:79], v[236:239], v[216:219], v[76:79]
	v_mfma_f32_16x16x32_bf16 v[72:75], v[244:247], v[216:219], v[72:75]
	v_mfma_f32_16x16x32_bf16 v[68:71], v[236:239], v[228:231], v[68:71]
	v_mfma_f32_16x16x32_bf16 v[64:67], v[244:247], v[228:231], v[64:67]
	s_barrier
	s_mov_b32 m0, s77
	v_lshl_add_u64 v[224:225], s[52:53], 0, v[146:147]
	ds_read_b128 v[162:165], v194 offset:16384
	ds_read_b128 v[166:169], v194 offset:17408
	ds_read_b128 v[196:199], v194 offset:18432
	ds_read_b128 v[200:203], v194 offset:19456
	ds_read_b128 v[204:207], v194 offset:20480
	ds_read_b128 v[216:219], v194 offset:21504
	ds_read_b128 v[220:223], v194 offset:22528
	ds_read_b128 v[228:231], v194 offset:23552
	global_load_lds_dwordx4 v[224:225], off
	v_lshl_add_u64 v[248:249], s[52:53], 0, v[150:151]
	s_mov_b32 m0, s78
	s_nop 0
	global_load_lds_dwordx4 v[248:249], off
	s_barrier
	s_waitcnt lgkmcnt(0)
	v_mfma_f32_16x16x32_bf16 v[60:63], v[128:131], v[162:165], 0
	v_mfma_f32_16x16x32_bf16 v[56:59], v[136:139], v[162:165], 0
	v_mfma_f32_16x16x32_bf16 v[52:55], v[128:131], v[196:199], 0
	v_mfma_f32_16x16x32_bf16 v[48:51], v[136:139], v[196:199], 0
	v_mfma_f32_16x16x32_bf16 v[44:47], v[128:131], v[204:207], 0
	v_mfma_f32_16x16x32_bf16 v[40:43], v[136:139], v[204:207], 0
	v_mfma_f32_16x16x32_bf16 v[36:39], v[128:131], v[220:223], 0
	v_mfma_f32_16x16x32_bf16 v[32:35], v[136:139], v[220:223], 0
	v_mfma_f32_16x16x32_bf16 v[60:63], v[132:135], v[166:169], v[60:63]
	v_mfma_f32_16x16x32_bf16 v[56:59], v[140:143], v[166:169], v[56:59]
	v_mfma_f32_16x16x32_bf16 v[52:55], v[132:135], v[200:203], v[52:55]
	v_mfma_f32_16x16x32_bf16 v[48:51], v[140:143], v[200:203], v[48:51]
	v_mfma_f32_16x16x32_bf16 v[44:47], v[132:135], v[216:219], v[44:47]
	v_mfma_f32_16x16x32_bf16 v[40:43], v[140:143], v[216:219], v[40:43]
	v_mfma_f32_16x16x32_bf16 v[36:39], v[132:135], v[228:231], v[36:39]
	v_mfma_f32_16x16x32_bf16 v[32:35], v[140:143], v[228:231], v[32:35]
	s_barrier
	s_add_u32 s56, s50, 0x40000
	s_addc_u32 s57, s51, 0
	s_add_i32 s27, s27, s76
	v_lshl_add_u64 v[128:129], s[56:57], 0, v[148:149]
	s_mov_b32 m0, s27
	s_nop 0
	global_load_lds_dwordx4 v[128:129], off
	v_lshl_add_u64 v[128:129], s[56:57], 0, v[152:153]
	s_add_i32 m0, s27, 0x2000
	s_nop 0
	global_load_lds_dwordx4 v[128:129], off
	s_waitcnt vmcnt(6)
	s_barrier
	v_mfma_f32_16x16x32_bf16 v[28:31], v[232:235], v[162:165], 0
	v_mfma_f32_16x16x32_bf16 v[24:27], v[240:243], v[162:165], 0
	v_mfma_f32_16x16x32_bf16 v[20:23], v[232:235], v[196:199], 0
	v_mfma_f32_16x16x32_bf16 v[16:19], v[240:243], v[196:199], 0
	v_mfma_f32_16x16x32_bf16 v[12:15], v[232:235], v[204:207], 0
	v_mfma_f32_16x16x32_bf16 v[8:11], v[240:243], v[204:207], 0
	v_mfma_f32_16x16x32_bf16 v[4:7], v[232:235], v[220:223], 0
	v_mfma_f32_16x16x32_bf16 v[0:3], v[240:243], v[220:223], 0
	v_mfma_f32_16x16x32_bf16 v[28:31], v[236:239], v[166:169], v[28:31]
	v_mfma_f32_16x16x32_bf16 v[24:27], v[244:247], v[166:169], v[24:27]
	v_mfma_f32_16x16x32_bf16 v[20:23], v[236:239], v[200:203], v[20:23]
	v_mfma_f32_16x16x32_bf16 v[16:19], v[244:247], v[200:203], v[16:19]
	v_mfma_f32_16x16x32_bf16 v[12:15], v[236:239], v[216:219], v[12:15]
	v_mfma_f32_16x16x32_bf16 v[8:11], v[244:247], v[216:219], v[8:11]
	v_mfma_f32_16x16x32_bf16 v[4:7], v[236:239], v[228:231], v[4:7]
	v_mfma_f32_16x16x32_bf16 v[0:3], v[244:247], v[228:231], v[0:3]
	s_barrier
	s_add_i32 s27, 0, 0x18000
	v_add_u32_e32 v140, s27, v192
	ds_read_b128 v[128:131], v140
	ds_read_b128 v[132:135], v140 offset:1024
	ds_read_b128 v[136:139], v140 offset:2048
	ds_read_b128 v[140:143], v140 offset:3072
	s_add_u32 s52, s52, 0x40000
	s_addc_u32 s53, s53, 0
	s_mov_b32 m0, s81
	v_lshl_add_u64 v[232:233], s[52:53], 0, v[146:147]
	ds_read_b128 v[162:165], v194 offset:32768
	ds_read_b128 v[166:169], v194 offset:33792
	ds_read_b128 v[196:199], v194 offset:34816
	ds_read_b128 v[200:203], v194 offset:35840
	ds_read_b128 v[204:207], v194 offset:36864
	ds_read_b128 v[216:219], v194 offset:37888
	ds_read_b128 v[220:223], v194 offset:38912
	ds_read_b128 v[228:231], v194 offset:39936
	global_load_lds_dwordx4 v[232:233], off
	v_lshl_add_u64 v[232:233], s[52:53], 0, v[150:151]
	s_mov_b32 m0, s82
	s_nop 0
	global_load_lds_dwordx4 v[232:233], off
	s_waitcnt lgkmcnt(8)
	s_barrier
	s_waitcnt lgkmcnt(0)
	v_mfma_f32_16x16x32_bf16 v[124:127], v[128:131], v[162:165], v[124:127]
	v_mfma_f32_16x16x32_bf16 v[120:123], v[136:139], v[162:165], v[120:123]
	v_mfma_f32_16x16x32_bf16 v[116:119], v[128:131], v[196:199], v[116:119]
	v_mfma_f32_16x16x32_bf16 v[112:115], v[136:139], v[196:199], v[112:115]
	v_mfma_f32_16x16x32_bf16 v[108:111], v[128:131], v[204:207], v[108:111]
	v_mfma_f32_16x16x32_bf16 v[104:107], v[136:139], v[204:207], v[104:107]
	v_mfma_f32_16x16x32_bf16 v[100:103], v[128:131], v[220:223], v[100:103]
	v_mfma_f32_16x16x32_bf16 v[96:99], v[136:139], v[220:223], v[96:99]
	v_mfma_f32_16x16x32_bf16 v[124:127], v[132:135], v[166:169], v[124:127]
	v_mfma_f32_16x16x32_bf16 v[120:123], v[140:143], v[166:169], v[120:123]
	v_mfma_f32_16x16x32_bf16 v[116:119], v[132:135], v[200:203], v[116:119]
	v_mfma_f32_16x16x32_bf16 v[112:115], v[140:143], v[200:203], v[112:115]
	v_mfma_f32_16x16x32_bf16 v[108:111], v[132:135], v[216:219], v[108:111]
	v_mfma_f32_16x16x32_bf16 v[104:107], v[140:143], v[216:219], v[104:107]
	v_mfma_f32_16x16x32_bf16 v[100:103], v[132:135], v[228:231], v[100:103]
	v_mfma_f32_16x16x32_bf16 v[96:99], v[140:143], v[228:231], v[96:99]
	s_barrier
	s_add_i32 s37, 0, 0x1c000
	s_add_i32 s27, s27, s76
	v_add_u32_e32 v161, s37, v192
	v_lshl_add_u64 v[176:177], v[176:177], 0, s[18:19]
	s_mov_b32 m0, s27
	ds_read_b128 v[232:235], v161
	ds_read_b128 v[236:239], v161 offset:1024
	ds_read_b128 v[240:243], v161 offset:2048
	ds_read_b128 v[244:247], v161 offset:3072
	global_load_lds_dwordx4 v[176:177], off
	v_lshl_add_u64 v[176:177], v[188:189], 0, s[18:19]
	s_add_i32 m0, s27, 0x2000
	s_nop 0
	global_load_lds_dwordx4 v[176:177], off
	s_barrier
	s_waitcnt lgkmcnt(0)
	v_mfma_f32_16x16x32_bf16 v[92:95], v[232:235], v[162:165], v[92:95]
	v_mfma_f32_16x16x32_bf16 v[88:91], v[240:243], v[162:165], v[88:91]
	v_mfma_f32_16x16x32_bf16 v[84:87], v[232:235], v[196:199], v[84:87]
	v_mfma_f32_16x16x32_bf16 v[80:83], v[240:243], v[196:199], v[80:83]
	v_mfma_f32_16x16x32_bf16 v[76:79], v[232:235], v[204:207], v[76:79]
	v_mfma_f32_16x16x32_bf16 v[72:75], v[240:243], v[204:207], v[72:75]
	v_mfma_f32_16x16x32_bf16 v[68:71], v[232:235], v[220:223], v[68:71]
	v_mfma_f32_16x16x32_bf16 v[64:67], v[240:243], v[220:223], v[64:67]
	v_mfma_f32_16x16x32_bf16 v[92:95], v[236:239], v[166:169], v[92:95]
	v_mfma_f32_16x16x32_bf16 v[88:91], v[244:247], v[166:169], v[88:91]
	v_mfma_f32_16x16x32_bf16 v[84:87], v[236:239], v[200:203], v[84:87]
	v_mfma_f32_16x16x32_bf16 v[80:83], v[244:247], v[200:203], v[80:83]
	v_mfma_f32_16x16x32_bf16 v[76:79], v[236:239], v[216:219], v[76:79]
	v_mfma_f32_16x16x32_bf16 v[72:75], v[244:247], v[216:219], v[72:75]
	v_mfma_f32_16x16x32_bf16 v[68:71], v[236:239], v[228:231], v[68:71]
	v_mfma_f32_16x16x32_bf16 v[64:67], v[244:247], v[228:231], v[64:67]
	s_barrier
	s_mov_b32 m0, s80
	v_lshl_add_u64 v[176:177], v[224:225], 0, s[18:19]
	ds_read_b128 v[162:165], v194 offset:49152
	ds_read_b128 v[166:169], v194 offset:50176
	ds_read_b128 v[196:199], v194 offset:51200
	ds_read_b128 v[200:203], v194 offset:52224
	ds_read_b128 v[204:207], v194 offset:53248
	ds_read_b128 v[216:219], v194 offset:54272
	ds_read_b128 v[220:223], v194 offset:55296
	ds_read_b128 v[228:231], v194 offset:56320
	global_load_lds_dwordx4 v[176:177], off
	v_lshl_add_u64 v[176:177], v[248:249], 0, s[18:19]
	s_mov_b32 m0, s83
	s_nop 0
	global_load_lds_dwordx4 v[176:177], off
	s_barrier
	s_waitcnt lgkmcnt(0)
	v_mfma_f32_16x16x32_bf16 v[60:63], v[128:131], v[162:165], v[60:63]
	v_mfma_f32_16x16x32_bf16 v[56:59], v[136:139], v[162:165], v[56:59]
	v_mfma_f32_16x16x32_bf16 v[52:55], v[128:131], v[196:199], v[52:55]
	v_mfma_f32_16x16x32_bf16 v[48:51], v[136:139], v[196:199], v[48:51]
	v_mfma_f32_16x16x32_bf16 v[44:47], v[128:131], v[204:207], v[44:47]
	v_mfma_f32_16x16x32_bf16 v[40:43], v[136:139], v[204:207], v[40:43]
	v_mfma_f32_16x16x32_bf16 v[36:39], v[128:131], v[220:223], v[36:39]
	v_mfma_f32_16x16x32_bf16 v[32:35], v[136:139], v[220:223], v[32:35]
	v_mfma_f32_16x16x32_bf16 v[60:63], v[132:135], v[166:169], v[60:63]
	v_mfma_f32_16x16x32_bf16 v[56:59], v[140:143], v[166:169], v[56:59]
	v_mfma_f32_16x16x32_bf16 v[52:55], v[132:135], v[200:203], v[52:55]
	v_mfma_f32_16x16x32_bf16 v[48:51], v[140:143], v[200:203], v[48:51]
	v_mfma_f32_16x16x32_bf16 v[44:47], v[132:135], v[216:219], v[44:47]
	v_mfma_f32_16x16x32_bf16 v[40:43], v[140:143], v[216:219], v[40:43]
	v_mfma_f32_16x16x32_bf16 v[36:39], v[132:135], v[228:231], v[36:39]
	v_mfma_f32_16x16x32_bf16 v[32:35], v[140:143], v[228:231], v[32:35]
	s_barrier
	s_add_u32 s50, s50, 0x40080
	s_addc_u32 s51, s51, 0
	s_add_i32 s27, s37, s76
	v_lshl_add_u64 v[128:129], s[50:51], 0, v[148:149]
	s_mov_b32 m0, s27
	s_nop 0
	global_load_lds_dwordx4 v[128:129], off
	v_lshl_add_u64 v[128:129], s[50:51], 0, v[152:153]
	s_add_i32 m0, s27, 0x2000
	s_nop 0
	global_load_lds_dwordx4 v[128:129], off
	s_waitcnt vmcnt(6)
	s_barrier
	v_mfma_f32_16x16x32_bf16 v[28:31], v[232:235], v[162:165], v[28:31]
	v_mfma_f32_16x16x32_bf16 v[24:27], v[240:243], v[162:165], v[24:27]
	v_mfma_f32_16x16x32_bf16 v[20:23], v[232:235], v[196:199], v[20:23]
	v_mfma_f32_16x16x32_bf16 v[16:19], v[240:243], v[196:199], v[16:19]
	v_mfma_f32_16x16x32_bf16 v[12:15], v[232:235], v[204:207], v[12:15]
	v_mfma_f32_16x16x32_bf16 v[8:11], v[240:243], v[204:207], v[8:11]
	v_mfma_f32_16x16x32_bf16 v[4:7], v[232:235], v[220:223], v[4:7]
	v_mfma_f32_16x16x32_bf16 v[0:3], v[240:243], v[220:223], v[0:3]
	v_mfma_f32_16x16x32_bf16 v[28:31], v[236:239], v[166:169], v[28:31]
	v_mfma_f32_16x16x32_bf16 v[24:27], v[244:247], v[166:169], v[24:27]
	v_mfma_f32_16x16x32_bf16 v[20:23], v[236:239], v[200:203], v[20:23]
	v_mfma_f32_16x16x32_bf16 v[16:19], v[244:247], v[200:203], v[16:19]
	v_mfma_f32_16x16x32_bf16 v[12:15], v[236:239], v[216:219], v[12:15]
	v_mfma_f32_16x16x32_bf16 v[8:11], v[244:247], v[216:219], v[8:11]
	v_mfma_f32_16x16x32_bf16 v[4:7], v[236:239], v[228:231], v[4:7]
	v_mfma_f32_16x16x32_bf16 v[0:3], v[244:247], v[228:231], v[0:3]
	s_barrier
	s_add_i32 s36, s36, 2
	s_add_u32 s0, s0, 0x100
	s_addc_u32 s1, s1, 0
	s_add_u32 s34, s34, 0x100
	s_addc_u32 s35, s35, 0
	s_cmp_gt_u32 s36, 13
.LBB0_351:
	s_add_u32 s27, s0, 0xfffc0080
	s_addc_u32 s37, s1, -1
	s_add_i32 s47, 0, 0x10000
	v_add_u32_e32 v140, s47, v192
	ds_read_b128 v[128:131], v140
	ds_read_b128 v[132:135], v140 offset:1024
	ds_read_b128 v[136:139], v140 offset:2048
	ds_read_b128 v[140:143], v140 offset:3072
	s_cmp_eq_u32 s36, 12
	s_cselect_b32 s53, s25, s37
	s_cselect_b32 s52, s30, s27
	s_cselect_b32 s51, s31, s35
	s_cselect_b32 s50, s33, s34
	v_lshl_add_u64 v[176:177], s[0:1], 0, v[156:157]
	s_add_i32 m0, s77, 0xc000
	ds_read_b128 v[162:165], v194
	ds_read_b128 v[166:169], v194 offset:1024
	ds_read_b128 v[196:199], v194 offset:2048
	ds_read_b128 v[200:203], v194 offset:3072
	ds_read_b128 v[204:207], v194 offset:4096
	ds_read_b128 v[216:219], v194 offset:5120
	ds_read_b128 v[220:223], v194 offset:6144
	ds_read_b128 v[228:231], v194 offset:7168
	global_load_lds_dwordx4 v[176:177], off
	v_lshl_add_u64 v[176:177], s[0:1], 0, v[158:159]
	s_add_i32 m0, s77, 0xe000
	s_nop 0
	global_load_lds_dwordx4 v[176:177], off
	s_waitcnt lgkmcnt(8)
	s_barrier
	s_waitcnt lgkmcnt(0)
	v_mfma_f32_16x16x32_bf16 v[124:127], v[128:131], v[162:165], v[124:127]
	v_mfma_f32_16x16x32_bf16 v[120:123], v[136:139], v[162:165], v[120:123]
	v_mfma_f32_16x16x32_bf16 v[116:119], v[128:131], v[196:199], v[116:119]
	v_mfma_f32_16x16x32_bf16 v[112:115], v[136:139], v[196:199], v[112:115]
	v_mfma_f32_16x16x32_bf16 v[108:111], v[128:131], v[204:207], v[108:111]
	v_mfma_f32_16x16x32_bf16 v[104:107], v[136:139], v[204:207], v[104:107]
	v_mfma_f32_16x16x32_bf16 v[100:103], v[128:131], v[220:223], v[100:103]
	v_mfma_f32_16x16x32_bf16 v[96:99], v[136:139], v[220:223], v[96:99]
	v_mfma_f32_16x16x32_bf16 v[124:127], v[132:135], v[166:169], v[124:127]
	v_mfma_f32_16x16x32_bf16 v[120:123], v[140:143], v[166:169], v[120:123]
	v_mfma_f32_16x16x32_bf16 v[116:119], v[132:135], v[200:203], v[116:119]
	v_mfma_f32_16x16x32_bf16 v[112:115], v[140:143], v[200:203], v[112:115]
	v_mfma_f32_16x16x32_bf16 v[108:111], v[132:135], v[216:219], v[108:111]
	v_mfma_f32_16x16x32_bf16 v[104:107], v[140:143], v[216:219], v[104:107]
	v_mfma_f32_16x16x32_bf16 v[100:103], v[132:135], v[228:231], v[100:103]
	v_mfma_f32_16x16x32_bf16 v[96:99], v[140:143], v[228:231], v[96:99]
	s_barrier
	s_add_i32 s27, 0, 0x14000
	s_add_i32 s37, s47, s76
	v_add_u32_e32 v161, s27, v192
	v_lshl_add_u64 v[176:177], s[50:51], 0, v[148:149]
	s_mov_b32 m0, s37
	ds_read_b128 v[232:235], v161
	ds_read_b128 v[236:239], v161 offset:1024
	ds_read_b128 v[240:243], v161 offset:2048
	ds_read_b128 v[244:247], v161 offset:3072
	global_load_lds_dwordx4 v[176:177], off
	v_lshl_add_u64 v[188:189], s[50:51], 0, v[152:153]
	s_add_i32 m0, s37, 0x2000
	s_nop 0
	global_load_lds_dwordx4 v[188:189], off
	s_barrier
	s_waitcnt lgkmcnt(0)
	v_mfma_f32_16x16x32_bf16 v[92:95], v[232:235], v[162:165], v[92:95]
	v_mfma_f32_16x16x32_bf16 v[88:91], v[240:243], v[162:165], v[88:91]
	v_mfma_f32_16x16x32_bf16 v[84:87], v[232:235], v[196:199], v[84:87]
	v_mfma_f32_16x16x32_bf16 v[80:83], v[240:243], v[196:199], v[80:83]
	v_mfma_f32_16x16x32_bf16 v[76:79], v[232:235], v[204:207], v[76:79]
	v_mfma_f32_16x16x32_bf16 v[72:75], v[240:243], v[204:207], v[72:75]
	v_mfma_f32_16x16x32_bf16 v[68:71], v[232:235], v[220:223], v[68:71]
	v_mfma_f32_16x16x32_bf16 v[64:67], v[240:243], v[220:223], v[64:67]
	v_mfma_f32_16x16x32_bf16 v[92:95], v[236:239], v[166:169], v[92:95]
	v_mfma_f32_16x16x32_bf16 v[88:91], v[244:247], v[166:169], v[88:91]
	v_mfma_f32_16x16x32_bf16 v[84:87], v[236:239], v[200:203], v[84:87]
	v_mfma_f32_16x16x32_bf16 v[80:83], v[244:247], v[200:203], v[80:83]
	v_mfma_f32_16x16x32_bf16 v[76:79], v[236:239], v[216:219], v[76:79]
	v_mfma_f32_16x16x32_bf16 v[72:75], v[244:247], v[216:219], v[72:75]
	v_mfma_f32_16x16x32_bf16 v[68:71], v[236:239], v[228:231], v[68:71]
	v_mfma_f32_16x16x32_bf16 v[64:67], v[244:247], v[228:231], v[64:67]
	s_barrier
	s_mov_b32 m0, s77
	v_lshl_add_u64 v[224:225], s[52:53], 0, v[146:147]
	ds_read_b128 v[162:165], v194 offset:16384
	ds_read_b128 v[166:169], v194 offset:17408
	ds_read_b128 v[196:199], v194 offset:18432
	ds_read_b128 v[200:203], v194 offset:19456
	ds_read_b128 v[204:207], v194 offset:20480
	ds_read_b128 v[216:219], v194 offset:21504
	ds_read_b128 v[220:223], v194 offset:22528
	ds_read_b128 v[228:231], v194 offset:23552
	global_load_lds_dwordx4 v[224:225], off
	v_lshl_add_u64 v[248:249], s[52:53], 0, v[150:151]
	s_mov_b32 m0, s78
	s_nop 0
	global_load_lds_dwordx4 v[248:249], off
	s_barrier
	s_waitcnt lgkmcnt(0)
	v_mfma_f32_16x16x32_bf16 v[60:63], v[128:131], v[162:165], v[60:63]
	v_mfma_f32_16x16x32_bf16 v[56:59], v[136:139], v[162:165], v[56:59]
	v_mfma_f32_16x16x32_bf16 v[52:55], v[128:131], v[196:199], v[52:55]
	v_mfma_f32_16x16x32_bf16 v[48:51], v[136:139], v[196:199], v[48:51]
	v_mfma_f32_16x16x32_bf16 v[44:47], v[128:131], v[204:207], v[44:47]
	v_mfma_f32_16x16x32_bf16 v[40:43], v[136:139], v[204:207], v[40:43]
	v_mfma_f32_16x16x32_bf16 v[36:39], v[128:131], v[220:223], v[36:39]
	v_mfma_f32_16x16x32_bf16 v[32:35], v[136:139], v[220:223], v[32:35]
	v_mfma_f32_16x16x32_bf16 v[60:63], v[132:135], v[166:169], v[60:63]
	v_mfma_f32_16x16x32_bf16 v[56:59], v[140:143], v[166:169], v[56:59]
	v_mfma_f32_16x16x32_bf16 v[52:55], v[132:135], v[200:203], v[52:55]
	v_mfma_f32_16x16x32_bf16 v[48:51], v[140:143], v[200:203], v[48:51]
	v_mfma_f32_16x16x32_bf16 v[44:47], v[132:135], v[216:219], v[44:47]
	v_mfma_f32_16x16x32_bf16 v[40:43], v[140:143], v[216:219], v[40:43]
	v_mfma_f32_16x16x32_bf16 v[36:39], v[132:135], v[228:231], v[36:39]
	v_mfma_f32_16x16x32_bf16 v[32:35], v[140:143], v[228:231], v[32:35]
	s_barrier
	s_add_u32 s56, s50, 0x40000
	s_addc_u32 s57, s51, 0
	s_add_i32 s27, s27, s76
	v_lshl_add_u64 v[128:129], s[56:57], 0, v[148:149]
	s_mov_b32 m0, s27
	s_nop 0
	global_load_lds_dwordx4 v[128:129], off
	v_lshl_add_u64 v[128:129], s[56:57], 0, v[152:153]
	s_add_i32 m0, s27, 0x2000
	s_nop 0
	global_load_lds_dwordx4 v[128:129], off
	s_waitcnt vmcnt(6)
	s_barrier
	v_mfma_f32_16x16x32_bf16 v[28:31], v[232:235], v[162:165], v[28:31]
	v_mfma_f32_16x16x32_bf16 v[24:27], v[240:243], v[162:165], v[24:27]
	v_mfma_f32_16x16x32_bf16 v[20:23], v[232:235], v[196:199], v[20:23]
	v_mfma_f32_16x16x32_bf16 v[16:19], v[240:243], v[196:199], v[16:19]
	v_mfma_f32_16x16x32_bf16 v[12:15], v[232:235], v[204:207], v[12:15]
	v_mfma_f32_16x16x32_bf16 v[8:11], v[240:243], v[204:207], v[8:11]
	v_mfma_f32_16x16x32_bf16 v[4:7], v[232:235], v[220:223], v[4:7]
	v_mfma_f32_16x16x32_bf16 v[0:3], v[240:243], v[220:223], v[0:3]
	v_mfma_f32_16x16x32_bf16 v[28:31], v[236:239], v[166:169], v[28:31]
	v_mfma_f32_16x16x32_bf16 v[24:27], v[244:247], v[166:169], v[24:27]
	v_mfma_f32_16x16x32_bf16 v[20:23], v[236:239], v[200:203], v[20:23]
	v_mfma_f32_16x16x32_bf16 v[16:19], v[244:247], v[200:203], v[16:19]
	v_mfma_f32_16x16x32_bf16 v[12:15], v[236:239], v[216:219], v[12:15]
	v_mfma_f32_16x16x32_bf16 v[8:11], v[244:247], v[216:219], v[8:11]
	v_mfma_f32_16x16x32_bf16 v[4:7], v[236:239], v[228:231], v[4:7]
	v_mfma_f32_16x16x32_bf16 v[0:3], v[244:247], v[228:231], v[0:3]
	s_barrier
	s_add_i32 s27, 0, 0x18000
	v_add_u32_e32 v140, s27, v192
	ds_read_b128 v[128:131], v140
	ds_read_b128 v[132:135], v140 offset:1024
	ds_read_b128 v[136:139], v140 offset:2048
	ds_read_b128 v[140:143], v140 offset:3072
	s_add_u32 s52, s52, 0x40000
	s_addc_u32 s53, s53, 0
	s_mov_b32 m0, s81
	v_lshl_add_u64 v[232:233], s[52:53], 0, v[146:147]
	ds_read_b128 v[162:165], v194 offset:32768
	ds_read_b128 v[166:169], v194 offset:33792
	ds_read_b128 v[196:199], v194 offset:34816
	ds_read_b128 v[200:203], v194 offset:35840
	ds_read_b128 v[204:207], v194 offset:36864
	ds_read_b128 v[216:219], v194 offset:37888
	ds_read_b128 v[220:223], v194 offset:38912
	ds_read_b128 v[228:231], v194 offset:39936
	global_load_lds_dwordx4 v[232:233], off
	v_lshl_add_u64 v[232:233], s[52:53], 0, v[150:151]
	s_mov_b32 m0, s82
	s_nop 0
	global_load_lds_dwordx4 v[232:233], off
	s_waitcnt lgkmcnt(8)
	s_barrier
	s_waitcnt lgkmcnt(0)
	v_mfma_f32_16x16x32_bf16 v[124:127], v[128:131], v[162:165], v[124:127]
	v_mfma_f32_16x16x32_bf16 v[120:123], v[136:139], v[162:165], v[120:123]
	v_mfma_f32_16x16x32_bf16 v[116:119], v[128:131], v[196:199], v[116:119]
	v_mfma_f32_16x16x32_bf16 v[112:115], v[136:139], v[196:199], v[112:115]
	v_mfma_f32_16x16x32_bf16 v[108:111], v[128:131], v[204:207], v[108:111]
	v_mfma_f32_16x16x32_bf16 v[104:107], v[136:139], v[204:207], v[104:107]
	v_mfma_f32_16x16x32_bf16 v[100:103], v[128:131], v[220:223], v[100:103]
	v_mfma_f32_16x16x32_bf16 v[96:99], v[136:139], v[220:223], v[96:99]
	v_mfma_f32_16x16x32_bf16 v[124:127], v[132:135], v[166:169], v[124:127]
	v_mfma_f32_16x16x32_bf16 v[120:123], v[140:143], v[166:169], v[120:123]
	v_mfma_f32_16x16x32_bf16 v[116:119], v[132:135], v[200:203], v[116:119]
	v_mfma_f32_16x16x32_bf16 v[112:115], v[140:143], v[200:203], v[112:115]
	v_mfma_f32_16x16x32_bf16 v[108:111], v[132:135], v[216:219], v[108:111]
	v_mfma_f32_16x16x32_bf16 v[104:107], v[140:143], v[216:219], v[104:107]
	v_mfma_f32_16x16x32_bf16 v[100:103], v[132:135], v[228:231], v[100:103]
	v_mfma_f32_16x16x32_bf16 v[96:99], v[140:143], v[228:231], v[96:99]
	s_barrier
	s_add_i32 s37, 0, 0x1c000
	s_add_i32 s27, s27, s76
	v_add_u32_e32 v161, s37, v192
	v_lshl_add_u64 v[176:177], v[176:177], 0, s[18:19]
	s_mov_b32 m0, s27
	ds_read_b128 v[232:235], v161
	ds_read_b128 v[236:239], v161 offset:1024
	ds_read_b128 v[240:243], v161 offset:2048
	ds_read_b128 v[244:247], v161 offset:3072
	global_load_lds_dwordx4 v[176:177], off
	v_lshl_add_u64 v[176:177], v[188:189], 0, s[18:19]
	s_add_i32 m0, s27, 0x2000
	s_nop 0
	global_load_lds_dwordx4 v[176:177], off
	s_barrier
	s_waitcnt lgkmcnt(0)
	v_mfma_f32_16x16x32_bf16 v[92:95], v[232:235], v[162:165], v[92:95]
	v_mfma_f32_16x16x32_bf16 v[88:91], v[240:243], v[162:165], v[88:91]
	v_mfma_f32_16x16x32_bf16 v[84:87], v[232:235], v[196:199], v[84:87]
	v_mfma_f32_16x16x32_bf16 v[80:83], v[240:243], v[196:199], v[80:83]
	v_mfma_f32_16x16x32_bf16 v[76:79], v[232:235], v[204:207], v[76:79]
	v_mfma_f32_16x16x32_bf16 v[72:75], v[240:243], v[204:207], v[72:75]
	v_mfma_f32_16x16x32_bf16 v[68:71], v[232:235], v[220:223], v[68:71]
	v_mfma_f32_16x16x32_bf16 v[64:67], v[240:243], v[220:223], v[64:67]
	v_mfma_f32_16x16x32_bf16 v[92:95], v[236:239], v[166:169], v[92:95]
	v_mfma_f32_16x16x32_bf16 v[88:91], v[244:247], v[166:169], v[88:91]
	v_mfma_f32_16x16x32_bf16 v[84:87], v[236:239], v[200:203], v[84:87]
	v_mfma_f32_16x16x32_bf16 v[80:83], v[244:247], v[200:203], v[80:83]
	v_mfma_f32_16x16x32_bf16 v[76:79], v[236:239], v[216:219], v[76:79]
	v_mfma_f32_16x16x32_bf16 v[72:75], v[244:247], v[216:219], v[72:75]
	v_mfma_f32_16x16x32_bf16 v[68:71], v[236:239], v[228:231], v[68:71]
	v_mfma_f32_16x16x32_bf16 v[64:67], v[244:247], v[228:231], v[64:67]
	s_barrier
	s_mov_b32 m0, s80
	v_lshl_add_u64 v[176:177], v[224:225], 0, s[18:19]
	ds_read_b128 v[162:165], v194 offset:49152
	ds_read_b128 v[166:169], v194 offset:50176
	ds_read_b128 v[196:199], v194 offset:51200
	ds_read_b128 v[200:203], v194 offset:52224
	ds_read_b128 v[204:207], v194 offset:53248
	ds_read_b128 v[216:219], v194 offset:54272
	ds_read_b128 v[220:223], v194 offset:55296
	ds_read_b128 v[228:231], v194 offset:56320
	global_load_lds_dwordx4 v[176:177], off
	v_lshl_add_u64 v[176:177], v[248:249], 0, s[18:19]
	s_mov_b32 m0, s83
	s_nop 0
	global_load_lds_dwordx4 v[176:177], off
	s_barrier
	s_waitcnt lgkmcnt(0)
	v_mfma_f32_16x16x32_bf16 v[60:63], v[128:131], v[162:165], v[60:63]
	v_mfma_f32_16x16x32_bf16 v[56:59], v[136:139], v[162:165], v[56:59]
	v_mfma_f32_16x16x32_bf16 v[52:55], v[128:131], v[196:199], v[52:55]
	v_mfma_f32_16x16x32_bf16 v[48:51], v[136:139], v[196:199], v[48:51]
	v_mfma_f32_16x16x32_bf16 v[44:47], v[128:131], v[204:207], v[44:47]
	v_mfma_f32_16x16x32_bf16 v[40:43], v[136:139], v[204:207], v[40:43]
	v_mfma_f32_16x16x32_bf16 v[36:39], v[128:131], v[220:223], v[36:39]
	v_mfma_f32_16x16x32_bf16 v[32:35], v[136:139], v[220:223], v[32:35]
	v_mfma_f32_16x16x32_bf16 v[60:63], v[132:135], v[166:169], v[60:63]
	v_mfma_f32_16x16x32_bf16 v[56:59], v[140:143], v[166:169], v[56:59]
	v_mfma_f32_16x16x32_bf16 v[52:55], v[132:135], v[200:203], v[52:55]
	v_mfma_f32_16x16x32_bf16 v[48:51], v[140:143], v[200:203], v[48:51]
	v_mfma_f32_16x16x32_bf16 v[44:47], v[132:135], v[216:219], v[44:47]
	v_mfma_f32_16x16x32_bf16 v[40:43], v[140:143], v[216:219], v[40:43]
	v_mfma_f32_16x16x32_bf16 v[36:39], v[132:135], v[228:231], v[36:39]
	v_mfma_f32_16x16x32_bf16 v[32:35], v[140:143], v[228:231], v[32:35]
	s_barrier
	s_add_u32 s50, s50, 0x40080
	s_addc_u32 s51, s51, 0
	s_add_i32 s27, s37, s76
	v_lshl_add_u64 v[128:129], s[50:51], 0, v[148:149]
	s_mov_b32 m0, s27
	s_nop 0
	global_load_lds_dwordx4 v[128:129], off
	v_lshl_add_u64 v[128:129], s[50:51], 0, v[152:153]
	s_add_i32 m0, s27, 0x2000
	s_nop 0
	global_load_lds_dwordx4 v[128:129], off
	s_waitcnt vmcnt(6)
	s_barrier
	v_mfma_f32_16x16x32_bf16 v[28:31], v[232:235], v[162:165], v[28:31]
	v_mfma_f32_16x16x32_bf16 v[24:27], v[240:243], v[162:165], v[24:27]
	v_mfma_f32_16x16x32_bf16 v[20:23], v[232:235], v[196:199], v[20:23]
	v_mfma_f32_16x16x32_bf16 v[16:19], v[240:243], v[196:199], v[16:19]
	v_mfma_f32_16x16x32_bf16 v[12:15], v[232:235], v[204:207], v[12:15]
	v_mfma_f32_16x16x32_bf16 v[8:11], v[240:243], v[204:207], v[8:11]
	v_mfma_f32_16x16x32_bf16 v[4:7], v[232:235], v[220:223], v[4:7]
	v_mfma_f32_16x16x32_bf16 v[0:3], v[240:243], v[220:223], v[0:3]
	v_mfma_f32_16x16x32_bf16 v[28:31], v[236:239], v[166:169], v[28:31]
	v_mfma_f32_16x16x32_bf16 v[24:27], v[244:247], v[166:169], v[24:27]
	v_mfma_f32_16x16x32_bf16 v[20:23], v[236:239], v[200:203], v[20:23]
	v_mfma_f32_16x16x32_bf16 v[16:19], v[244:247], v[200:203], v[16:19]
	v_mfma_f32_16x16x32_bf16 v[12:15], v[236:239], v[216:219], v[12:15]
	v_mfma_f32_16x16x32_bf16 v[8:11], v[244:247], v[216:219], v[8:11]
	v_mfma_f32_16x16x32_bf16 v[4:7], v[236:239], v[228:231], v[4:7]
	v_mfma_f32_16x16x32_bf16 v[0:3], v[244:247], v[228:231], v[0:3]
	s_barrier
	s_add_i32 s36, s36, 2
	s_add_u32 s0, s0, 0x100
	s_addc_u32 s1, s1, 0
	s_add_u32 s34, s34, 0x100
	s_addc_u32 s35, s35, 0
	s_cmp_gt_u32 s36, 13
	s_cbranch_scc0 .LBB0_351
	s_lshl_b32 s0, s11, 8
	s_or_b32 s50, s0, s79
	s_ashr_i32 s51, s50, 31
	v_lshl_add_u64 v[140:141], s[50:51], 3, v[154:155]
	global_load_dwordx4 v[128:131], v[140:141], off offset:48
	global_load_dwordx4 v[132:135], v[140:141], off offset:32
	global_load_dwordx4 v[136:139], v[140:141], off offset:16
	global_load_dwordx4 v[162:165], v[140:141], off
	s_mov_b32 s34, 0x35800000
	s_mov_b32 s0, 0x358637bd
	v_mov_b64_e32 v[168:169], s[0:1]
	s_mov_b32 s30, 0x45800000
	s_cmp_lt_u32 s10, 2
	s_waitcnt vmcnt(0)
	v_ffbh_u32_e32 v142, v165
	v_min_u32_e32 v161, 32, v142
	v_lshlrev_b64 v[142:143], v161, v[164:165]
	v_min_u32_e32 v142, 1, v142
	v_or_b32_e32 v142, v143, v142
	v_cvt_f32_u32_e32 v142, v142
	v_sub_u32_e32 v143, 32, v161
	v_ldexp_f32 v143, v142, v143
	v_ffbh_u32_e32 v142, v163
	v_min_u32_e32 v142, 32, v142
	v_lshlrev_b64 v[162:163], v142, v[162:163]
	v_min_u32_e32 v161, 1, v162
	v_or_b32_e32 v161, v163, v161
	v_cvt_f32_u32_e32 v161, v161
	v_sub_u32_e32 v142, 32, v142
	v_ldexp_f32 v142, v161, v142
	v_pk_mul_f32 v[142:143], v[142:143], s[34:35] op_sel_hi:[1,0]
	s_nop 0
	v_pk_fma_f32 v[142:143], v[142:143], s[2:3], v[168:169] op_sel_hi:[1,0,0]
	s_nop 0
	v_mul_f32_e32 v161, 0x4b800000, v142
	v_cmp_gt_f32_e64 s[0:1], s89, v142
	v_cmp_gt_f32_e32 vcc, s89, v143
	s_nop 0
	v_cndmask_b32_e64 v142, v142, v161, s[0:1]
	v_mul_f32_e32 v161, 0x4b800000, v143
	v_cndmask_b32_e32 v143, v143, v161, vcc
	v_rsq_f32_e32 v142, v142
	v_rsq_f32_e32 v143, v143
	s_nop 0
	v_pk_mul_f32 v[162:163], v[142:143], s[30:31] op_sel_hi:[1,0]
	s_nop 0
	v_cndmask_b32_e64 v166, v142, v162, s[0:1]
	v_ffbh_u32_e32 v142, v139
	v_min_u32_e32 v142, 32, v142
	v_lshlrev_b64 v[138:139], v142, v[138:139]
	v_min_u32_e32 v138, 1, v138
	v_or_b32_e32 v138, v139, v138
	v_cvt_f32_u32_e32 v138, v138
	v_sub_u32_e32 v139, 32, v142
	v_cndmask_b32_e32 v167, v143, v163, vcc
	v_pk_mul_f32 v[60:61], v[60:61], v[166:167]
	v_ldexp_f32 v139, v138, v139
	v_ffbh_u32_e32 v138, v137
	v_min_u32_e32 v138, 32, v138
	v_lshlrev_b64 v[136:137], v138, v[136:137]
	v_min_u32_e32 v136, 1, v136
	v_or_b32_e32 v136, v137, v136
	v_cvt_f32_u32_e32 v136, v136
	v_sub_u32_e32 v137, 32, v138
	v_pk_mul_f32 v[52:53], v[52:53], v[166:167]
	v_pk_mul_f32 v[44:45], v[44:45], v[166:167]
	v_ldexp_f32 v138, v136, v137
	v_pk_mul_f32 v[136:137], v[138:139], s[34:35] op_sel_hi:[1,0]
	v_pk_mul_f32 v[36:37], v[36:37], v[166:167]
	v_pk_fma_f32 v[136:137], v[136:137], s[2:3], v[168:169] op_sel_hi:[1,0,0]
	s_nop 0
	v_mul_f32_e32 v138, 0x4b800000, v136
	v_cmp_gt_f32_e64 s[0:1], s89, v136
	v_cmp_gt_f32_e32 vcc, s89, v137
	s_nop 0
	v_cndmask_b32_e64 v136, v136, v138, s[0:1]
	v_mul_f32_e32 v138, 0x4b800000, v137
	v_cndmask_b32_e32 v137, v137, v138, vcc
	v_rsq_f32_e32 v136, v136
	v_rsq_f32_e32 v137, v137
	s_nop 0
	v_pk_mul_f32 v[138:139], v[136:137], s[30:31] op_sel_hi:[1,0]
	s_nop 0
	v_cndmask_b32_e64 v162, v136, v138, s[0:1]
	v_ffbh_u32_e32 v136, v135
	v_min_u32_e32 v136, 32, v136
	v_lshlrev_b64 v[134:135], v136, v[134:135]
	v_min_u32_e32 v134, 1, v134
	v_or_b32_e32 v134, v135, v134
	v_cvt_f32_u32_e32 v134, v134
	v_sub_u32_e32 v135, 32, v136
	v_cndmask_b32_e32 v163, v137, v139, vcc
	v_ldexp_f32 v135, v134, v135
	v_ffbh_u32_e32 v134, v133
	v_min_u32_e32 v134, 32, v134
	v_lshlrev_b64 v[132:133], v134, v[132:133]
	v_min_u32_e32 v132, 1, v132
	v_or_b32_e32 v132, v133, v132
	v_cvt_f32_u32_e32 v132, v132
	v_sub_u32_e32 v133, 32, v134
	v_ldexp_f32 v134, v132, v133
	v_pk_mul_f32 v[132:133], v[134:135], s[34:35] op_sel_hi:[1,0]
	s_nop 0
	v_pk_fma_f32 v[132:133], v[132:133], s[2:3], v[168:169] op_sel_hi:[1,0,0]
	s_nop 0
	v_mul_f32_e32 v134, 0x4b800000, v132
	v_cmp_gt_f32_e64 s[0:1], s89, v132
	v_cmp_gt_f32_e32 vcc, s89, v133
	s_nop 0
	v_cndmask_b32_e64 v132, v132, v134, s[0:1]
	v_mul_f32_e32 v134, 0x4b800000, v133
	v_cndmask_b32_e32 v133, v133, v134, vcc
	v_rsq_f32_e32 v132, v132
	v_rsq_f32_e32 v133, v133
	s_nop 0
	v_pk_mul_f32 v[134:135], v[132:133], s[30:31] op_sel_hi:[1,0]
	s_nop 0
	v_cndmask_b32_e64 v188, v132, v134, s[0:1]
	v_ffbh_u32_e32 v132, v131
	v_min_u32_e32 v132, 32, v132
	v_lshlrev_b64 v[130:131], v132, v[130:131]
	v_min_u32_e32 v130, 1, v130
	v_or_b32_e32 v130, v131, v130
	v_cvt_f32_u32_e32 v130, v130
	v_sub_u32_e32 v131, 32, v132
	v_cndmask_b32_e32 v189, v133, v135, vcc
	v_pk_mul_f32 v[56:57], v[56:57], v[188:189]
	v_ldexp_f32 v131, v130, v131
	v_ffbh_u32_e32 v130, v129
	v_min_u32_e32 v130, 32, v130
	v_lshlrev_b64 v[128:129], v130, v[128:129]
	v_min_u32_e32 v128, 1, v128
	v_or_b32_e32 v128, v129, v128
	v_cvt_f32_u32_e32 v128, v128
	v_sub_u32_e32 v129, 32, v130
	v_pk_mul_f32 v[48:49], v[48:49], v[188:189]
	v_pk_mul_f32 v[40:41], v[40:41], v[188:189]
	v_ldexp_f32 v130, v128, v129
	v_pk_mul_f32 v[128:129], v[130:131], s[34:35] op_sel_hi:[1,0]
	v_pk_mul_f32 v[32:33], v[32:33], v[188:189]
	v_pk_fma_f32 v[128:129], v[128:129], s[2:3], v[168:169] op_sel_hi:[1,0,0]
	s_nop 0
	v_mul_f32_e32 v130, 0x4b800000, v128
	v_cmp_gt_f32_e64 s[0:1], s89, v128
	v_cmp_gt_f32_e32 vcc, s89, v129
	s_nop 0
	v_cndmask_b32_e64 v128, v128, v130, s[0:1]
	v_mul_f32_e32 v130, 0x4b800000, v129
	v_cndmask_b32_e32 v129, v129, v130, vcc
	v_rsq_f32_e32 v128, v128
	v_rsq_f32_e32 v129, v129
	s_nop 0
	v_pk_mul_f32 v[130:131], v[128:129], s[30:31] op_sel_hi:[1,0]
	s_nop 0
	v_cndmask_b32_e32 v165, v129, v131, vcc
	v_cndmask_b32_e64 v164, v128, v130, s[0:1]
	global_load_dwordx4 v[128:131], v[140:141], off offset:1072
	global_load_dwordx4 v[132:135], v[140:141], off offset:1056
	global_load_dwordx4 v[136:139], v[140:141], off offset:1040
	s_nop 0
	global_load_dwordx4 v[140:143], v[140:141], off offset:1024
	s_waitcnt vmcnt(0)
	v_ffbh_u32_e32 v161, v143
	v_min_u32_e32 v161, 32, v161
	v_lshlrev_b64 v[142:143], v161, v[142:143]
	v_min_u32_e32 v142, 1, v142
	v_or_b32_e32 v142, v143, v142
	v_cvt_f32_u32_e32 v142, v142
	v_sub_u32_e32 v143, 32, v161
	v_ldexp_f32 v143, v142, v143
	v_ffbh_u32_e32 v142, v141
	v_min_u32_e32 v142, 32, v142
	v_lshlrev_b64 v[140:141], v142, v[140:141]
	v_min_u32_e32 v140, 1, v140
	v_or_b32_e32 v140, v141, v140
	v_cvt_f32_u32_e32 v140, v140
	v_sub_u32_e32 v141, 32, v142
	v_ldexp_f32 v142, v140, v141
	v_pk_mul_f32 v[140:141], v[142:143], s[34:35] op_sel_hi:[1,0]
	s_nop 0
	v_pk_fma_f32 v[140:141], v[140:141], s[2:3], v[168:169] op_sel_hi:[1,0,0]
	s_nop 0
	v_mul_f32_e32 v142, 0x4b800000, v140
	v_cmp_gt_f32_e64 s[0:1], s89, v140
	v_cmp_gt_f32_e32 vcc, s89, v141
	s_nop 0
	v_cndmask_b32_e64 v140, v140, v142, s[0:1]
	v_mul_f32_e32 v142, 0x4b800000, v141
	v_cndmask_b32_e32 v141, v141, v142, vcc
	v_rsq_f32_e32 v140, v140
	v_rsq_f32_e32 v141, v141
	s_nop 0
	v_pk_mul_f32 v[142:143], v[140:141], s[30:31] op_sel_hi:[1,0]
	s_nop 0
	v_cndmask_b32_e64 v142, v140, v142, s[0:1]
	v_ffbh_u32_e32 v140, v139
	v_min_u32_e32 v140, 32, v140
	v_lshlrev_b64 v[138:139], v140, v[138:139]
	v_min_u32_e32 v138, 1, v138
	v_or_b32_e32 v138, v139, v138
	v_cvt_f32_u32_e32 v138, v138
	v_sub_u32_e32 v139, 32, v140
	v_cndmask_b32_e32 v143, v141, v143, vcc
	v_pk_mul_f32 v[140:141], v[124:125], v[166:167]
	v_ldexp_f32 v139, v138, v139
	v_ffbh_u32_e32 v138, v137
	v_min_u32_e32 v138, 32, v138
	v_lshlrev_b64 v[136:137], v138, v[136:137]
	v_min_u32_e32 v136, 1, v136
	v_or_b32_e32 v136, v137, v136
	v_cvt_f32_u32_e32 v136, v136
	v_sub_u32_e32 v137, 32, v138
	v_pk_mul_f32 v[28:29], v[28:29], v[142:143]
	v_pk_mul_f32 v[20:21], v[20:21], v[142:143]
	v_ldexp_f32 v138, v136, v137
	v_pk_mul_f32 v[136:137], v[138:139], s[34:35] op_sel_hi:[1,0]
	v_pk_mul_f32 v[12:13], v[12:13], v[142:143]
	v_pk_fma_f32 v[136:137], v[136:137], s[2:3], v[168:169] op_sel_hi:[1,0,0]
	v_pk_mul_f32 v[4:5], v[4:5], v[142:143]
	v_mul_f32_e32 v138, 0x4b800000, v136
	v_cmp_gt_f32_e64 s[0:1], s89, v136
	v_cmp_gt_f32_e32 vcc, s89, v137
	s_nop 0
	v_cndmask_b32_e64 v136, v136, v138, s[0:1]
	v_mul_f32_e32 v138, 0x4b800000, v137
	v_cndmask_b32_e32 v137, v137, v138, vcc
	v_rsq_f32_e32 v136, v136
	v_rsq_f32_e32 v137, v137
	s_nop 0
	v_pk_mul_f32 v[138:139], v[136:137], s[30:31] op_sel_hi:[1,0]
	s_nop 0
	v_cndmask_b32_e64 v136, v136, v138, s[0:1]
	v_ffbh_u32_e32 v138, v135
	v_min_u32_e32 v138, 32, v138
	v_lshlrev_b64 v[134:135], v138, v[134:135]
	v_min_u32_e32 v134, 1, v134
	v_or_b32_e32 v134, v135, v134
	v_cvt_f32_u32_e32 v134, v134
	v_sub_u32_e32 v135, 32, v138
	v_cndmask_b32_e32 v137, v137, v139, vcc
	v_pk_mul_f32 v[138:139], v[120:121], v[188:189]
	v_ldexp_f32 v135, v134, v135
	v_ffbh_u32_e32 v134, v133
	v_min_u32_e32 v134, 32, v134
	v_lshlrev_b64 v[132:133], v134, v[132:133]
	v_min_u32_e32 v132, 1, v132
	v_or_b32_e32 v132, v133, v132
	v_cvt_f32_u32_e32 v132, v132
	v_sub_u32_e32 v133, 32, v134
	v_pk_mul_f32 v[120:121], v[84:85], v[142:143]
	v_ldexp_f32 v134, v132, v133
	v_pk_mul_f32 v[132:133], v[134:135], s[34:35] op_sel_hi:[1,0]
	s_nop 0
	v_pk_fma_f32 v[132:133], v[132:133], s[2:3], v[168:169] op_sel_hi:[1,0,0]
	s_nop 0
	v_mul_f32_e32 v134, 0x4b800000, v132
	v_cmp_gt_f32_e64 s[0:1], s89, v132
	v_cmp_gt_f32_e32 vcc, s89, v133
	s_nop 0
	v_cndmask_b32_e64 v132, v132, v134, s[0:1]
	v_mul_f32_e32 v134, 0x4b800000, v133
	v_cndmask_b32_e32 v133, v133, v134, vcc
	v_rsq_f32_e32 v132, v132
	v_rsq_f32_e32 v133, v133
	s_nop 0
	v_pk_mul_f32 v[134:135], v[132:133], s[30:31] op_sel_hi:[1,0]
	s_nop 0
	v_cndmask_b32_e64 v176, v132, v134, s[0:1]
	v_ffbh_u32_e32 v132, v131
	v_min_u32_e32 v132, 32, v132
	v_lshlrev_b64 v[130:131], v132, v[130:131]
	v_min_u32_e32 v130, 1, v130
	v_or_b32_e32 v130, v131, v130
	v_cvt_f32_u32_e32 v130, v130
	v_sub_u32_e32 v131, 32, v132
	v_cndmask_b32_e32 v177, v133, v135, vcc
	v_pk_mul_f32 v[124:125], v[88:89], v[176:177]
	v_ldexp_f32 v131, v130, v131
	v_ffbh_u32_e32 v130, v129
	v_min_u32_e32 v130, 32, v130
	v_lshlrev_b64 v[128:129], v130, v[128:129]
	v_min_u32_e32 v128, 1, v128
	v_or_b32_e32 v128, v129, v128
	v_cvt_f32_u32_e32 v128, v128
	v_sub_u32_e32 v129, 32, v130
	v_pk_mul_f32 v[134:135], v[116:117], v[166:167]
	v_pk_mul_f32 v[132:133], v[112:113], v[188:189]
	v_ldexp_f32 v130, v128, v129
	v_pk_mul_f32 v[128:129], v[130:131], s[34:35] op_sel_hi:[1,0]
	v_pk_mul_f32 v[116:117], v[80:81], v[176:177]
	v_pk_fma_f32 v[128:129], v[128:129], s[2:3], v[168:169] op_sel_hi:[1,0,0]
	v_pk_mul_f32 v[88:89], v[104:105], v[188:189]
	v_mul_f32_e32 v130, 0x4b800000, v128
	v_cmp_gt_f32_e64 s[0:1], s89, v128
	v_cmp_gt_f32_e32 vcc, s89, v129
	v_pk_mul_f32 v[112:113], v[76:77], v[142:143]
	v_cndmask_b32_e64 v128, v128, v130, s[0:1]
	v_mul_f32_e32 v130, 0x4b800000, v129
	v_cndmask_b32_e32 v129, v129, v130, vcc
	v_rsq_f32_e32 v128, v128
	v_rsq_f32_e32 v129, v129
	v_pk_mul_f32 v[76:77], v[100:101], v[166:167]
	v_pk_mul_f32 v[104:105], v[68:69], v[142:143]
	v_pk_mul_f32 v[24:25], v[24:25], v[176:177]
	v_pk_mul_f32 v[130:131], v[128:129], s[30:31] op_sel_hi:[1,0]
	v_pk_mul_f32 v[16:17], v[16:17], v[176:177]
	v_cndmask_b32_e32 v129, v129, v131, vcc
	v_cndmask_b32_e64 v128, v128, v130, s[0:1]
	s_mov_b64 s[0:1], -1
	v_pk_mul_f32 v[130:131], v[92:93], v[142:143]
	v_pk_mul_f32 v[92:93], v[108:109], v[166:167]
	v_pk_mul_f32 v[108:109], v[72:73], v[176:177]
	v_pk_mul_f32 v[72:73], v[96:97], v[188:189]
	v_pk_mul_f32 v[96:97], v[64:65], v[176:177]
	v_pk_mul_f32 v[8:9], v[8:9], v[176:177]
	v_pk_mul_f32 v[0:1], v[0:1], v[176:177]
	s_cbranch_scc1 .LBB0_354
	v_lshl_add_u32 v68, s10, 8, v193
	v_ashrrev_i32_e32 v69, 31, v68
	v_pk_mul_f32 v[64:65], v[126:127], v[162:163]
	v_cvt_pk_bf16_f32 v80, v140, v141
	s_lshl_b64 s[0:1], s[50:51], 1
	v_cvt_pk_bf16_f32 v81, v64, v65
	v_lshlrev_b64 v[64:65], 13, v[68:69]
	v_lshl_add_u64 v[64:65], s[44:45], 0, v[64:65]
	v_lshl_add_u64 v[64:65], v[64:65], 0, s[0:1]
	v_lshl_add_u64 v[64:65], v[64:65], 0, v[144:145]
	v_mov_b32_e32 v161, v145
	v_lshl_add_u64 v[64:65], v[64:65], 0, v[160:161]
	global_store_dwordx2 v[64:65], v[80:81], off
	v_pk_mul_f32 v[80:81], v[122:123], v[164:165]
	v_cvt_pk_bf16_f32 v84, v138, v139
	s_nop 0
	v_cvt_pk_bf16_f32 v85, v80, v81
	v_pk_mul_f32 v[80:81], v[94:95], v[136:137]
	global_store_dwordx2 v[64:65], v[84:85], off offset:16
	v_cvt_pk_bf16_f32 v84, v130, v131
	v_cvt_pk_bf16_f32 v85, v80, v81
	v_pk_mul_f32 v[80:81], v[90:91], v[128:129]
	global_store_dwordx2 v[64:65], v[84:85], off offset:256
	v_cvt_pk_bf16_f32 v84, v124, v125
	v_cvt_pk_bf16_f32 v85, v80, v81
	v_or_b32_e32 v80, 16, v68
	v_ashrrev_i32_e32 v81, 31, v80
	v_lshlrev_b64 v[80:81], 13, v[80:81]
	v_lshl_add_u64 v[80:81], s[44:45], 0, v[80:81]
	v_lshl_add_u64 v[80:81], v[80:81], 0, s[0:1]
	v_lshl_add_u64 v[80:81], v[80:81], 0, v[144:145]
	global_store_dwordx2 v[64:65], v[84:85], off offset:272
	v_pk_mul_f32 v[84:85], v[118:119], v[162:163]
	v_cvt_pk_bf16_f32 v100, v134, v135
	v_lshl_add_u64 v[80:81], v[80:81], 0, v[160:161]
	v_cvt_pk_bf16_f32 v101, v84, v85
	global_store_dwordx2 v[80:81], v[100:101], off
	v_pk_mul_f32 v[84:85], v[114:115], v[164:165]
	v_cvt_pk_bf16_f32 v100, v132, v133
	s_nop 0
	v_cvt_pk_bf16_f32 v101, v84, v85
	global_store_dwordx2 v[80:81], v[100:101], off offset:16
	v_pk_mul_f32 v[84:85], v[86:87], v[136:137]
	v_cvt_pk_bf16_f32 v100, v120, v121
	s_nop 0
	v_cvt_pk_bf16_f32 v101, v84, v85
	global_store_dwordx2 v[80:81], v[100:101], off offset:256
	v_pk_mul_f32 v[84:85], v[82:83], v[128:129]
	v_cvt_pk_bf16_f32 v100, v116, v117
	s_nop 0
	v_cvt_pk_bf16_f32 v101, v84, v85
	global_store_dwordx2 v[80:81], v[100:101], off offset:272
	v_or_b32_e32 v80, 32, v68
	v_ashrrev_i32_e32 v81, 31, v80
	v_lshlrev_b64 v[80:81], 13, v[80:81]
	v_lshl_add_u64 v[80:81], s[44:45], 0, v[80:81]
	v_or_b32_e32 v68, 48, v68
	v_lshl_add_u64 v[80:81], v[80:81], 0, s[0:1]
	v_ashrrev_i32_e32 v69, 31, v68
	v_pk_mul_f32 v[84:85], v[110:111], v[162:163]
	v_lshl_add_u64 v[80:81], v[80:81], 0, v[144:145]
	v_lshlrev_b64 v[68:69], 13, v[68:69]
	v_cvt_pk_bf16_f32 v100, v92, v93
	v_cvt_pk_bf16_f32 v101, v84, v85
	v_lshl_add_u64 v[80:81], v[80:81], 0, v[160:161]
	v_pk_mul_f32 v[84:85], v[106:107], v[164:165]
	v_lshl_add_u64 v[68:69], s[44:45], 0, v[68:69]
	global_store_dwordx2 v[80:81], v[100:101], off
	v_cvt_pk_bf16_f32 v100, v88, v89
	v_cvt_pk_bf16_f32 v101, v84, v85
	v_pk_mul_f32 v[84:85], v[78:79], v[136:137]
	v_lshl_add_u64 v[68:69], v[68:69], 0, s[0:1]
	global_store_dwordx2 v[80:81], v[100:101], off offset:16
	v_cvt_pk_bf16_f32 v100, v112, v113
	v_cvt_pk_bf16_f32 v101, v84, v85
	v_pk_mul_f32 v[84:85], v[74:75], v[128:129]
	v_lshl_add_u64 v[68:69], v[68:69], 0, v[144:145]
	global_store_dwordx2 v[80:81], v[100:101], off offset:256
	v_cvt_pk_bf16_f32 v100, v108, v109
	v_cvt_pk_bf16_f32 v101, v84, v85
	global_store_dwordx2 v[80:81], v[100:101], off offset:272
	v_cvt_pk_bf16_f32 v84, v76, v77
	v_lshl_add_u64 v[68:69], v[68:69], 0, v[160:161]
	v_pk_mul_f32 v[80:81], v[102:103], v[162:163]
	s_mov_b64 s[0:1], 0x100000
	v_cvt_pk_bf16_f32 v85, v80, v81
	global_store_dwordx2 v[68:69], v[84:85], off
	v_cvt_pk_bf16_f32 v84, v72, v73
	v_pk_mul_f32 v[80:81], v[98:99], v[164:165]
	s_nop 0
	v_cvt_pk_bf16_f32 v85, v80, v81
	global_store_dwordx2 v[68:69], v[84:85], off offset:16
	v_cvt_pk_bf16_f32 v84, v104, v105
	v_pk_mul_f32 v[80:81], v[70:71], v[136:137]
	s_nop 0
	v_cvt_pk_bf16_f32 v85, v80, v81
	global_store_dwordx2 v[68:69], v[84:85], off offset:256
	v_cvt_pk_bf16_f32 v84, v96, v97
	v_pk_mul_f32 v[80:81], v[66:67], v[128:129]
	s_nop 0
	v_cvt_pk_bf16_f32 v85, v80, v81
	global_store_dwordx2 v[68:69], v[84:85], off offset:272
	v_add_co_u32_e32 v84, vcc, s29, v64
	v_pk_mul_f32 v[68:69], v[62:63], v[162:163]
	s_nop 0
	v_addc_co_u32_e32 v85, vcc, 0, v65, vcc
	v_cvt_pk_bf16_f32 v80, v60, v61
	v_cvt_pk_bf16_f32 v81, v68, v69
	v_lshl_add_u64 v[68:69], v[64:65], 0, s[0:1]
	global_store_dwordx2 v[84:85], v[80:81], off
	v_cvt_pk_bf16_f32 v84, v56, v57
	v_pk_mul_f32 v[80:81], v[58:59], v[164:165]
	s_mov_b64 s[0:1], 0x120000
	v_cvt_pk_bf16_f32 v85, v80, v81
	global_store_dwordx2 v[68:69], v[84:85], off offset:16
	v_cvt_pk_bf16_f32 v84, v28, v29
	v_pk_mul_f32 v[80:81], v[30:31], v[136:137]
	s_nop 0
	v_cvt_pk_bf16_f32 v85, v80, v81
	global_store_dwordx2 v[68:69], v[84:85], off offset:256
	v_cvt_pk_bf16_f32 v84, v24, v25
	v_pk_mul_f32 v[80:81], v[26:27], v[128:129]
	s_nop 0
	v_cvt_pk_bf16_f32 v85, v80, v81
	global_store_dwordx2 v[68:69], v[84:85], off offset:272
	v_add_co_u32_e32 v84, vcc, s49, v64
	v_pk_mul_f32 v[68:69], v[54:55], v[162:163]
	v_cvt_pk_bf16_f32 v80, v52, v53
	s_nop 0
	v_addc_co_u32_e32 v85, vcc, 0, v65, vcc
	v_cvt_pk_bf16_f32 v81, v68, v69
	v_lshl_add_u64 v[68:69], v[64:65], 0, s[0:1]
	global_store_dwordx2 v[84:85], v[80:81], off
	v_pk_mul_f32 v[80:81], v[50:51], v[164:165]
	v_cvt_pk_bf16_f32 v84, v48, v49
	s_mov_b64 s[0:1], 0x140000
	v_cvt_pk_bf16_f32 v85, v80, v81
	global_store_dwordx2 v[68:69], v[84:85], off offset:16
	v_pk_mul_f32 v[80:81], v[22:23], v[136:137]
	v_cvt_pk_bf16_f32 v84, v20, v21
	s_nop 0
	v_cvt_pk_bf16_f32 v85, v80, v81
	global_store_dwordx2 v[68:69], v[84:85], off offset:256
	v_pk_mul_f32 v[80:81], v[18:19], v[128:129]
	v_cvt_pk_bf16_f32 v84, v16, v17
	s_nop 0
	v_cvt_pk_bf16_f32 v85, v80, v81
	global_store_dwordx2 v[68:69], v[84:85], off offset:272
	v_pk_mul_f32 v[68:69], v[46:47], v[162:163]
	v_cvt_pk_bf16_f32 v80, v44, v45
	s_nop 0
	v_cvt_pk_bf16_f32 v81, v68, v69
	v_lshl_add_u64 v[68:69], v[64:65], 0, s[0:1]
	s_mov_b32 s0, 0x140000
	v_add_co_u32_e32 v84, vcc, s0, v64
	s_mov_b64 s[0:1], 0x160000
	s_nop 0
	v_addc_co_u32_e32 v85, vcc, 0, v65, vcc
	global_store_dwordx2 v[84:85], v[80:81], off
	v_pk_mul_f32 v[80:81], v[42:43], v[164:165]
	v_cvt_pk_bf16_f32 v84, v40, v41
	s_nop 0
	v_cvt_pk_bf16_f32 v85, v80, v81
	global_store_dwordx2 v[68:69], v[84:85], off offset:16
	v_pk_mul_f32 v[80:81], v[14:15], v[136:137]
	v_cvt_pk_bf16_f32 v84, v12, v13
	s_nop 0
	v_cvt_pk_bf16_f32 v85, v80, v81
	global_store_dwordx2 v[68:69], v[84:85], off offset:256
	v_pk_mul_f32 v[80:81], v[10:11], v[128:129]
	v_cvt_pk_bf16_f32 v84, v8, v9
	s_nop 0
	v_cvt_pk_bf16_f32 v85, v80, v81
	global_store_dwordx2 v[68:69], v[84:85], off offset:272
	v_pk_mul_f32 v[68:69], v[38:39], v[162:163]
	v_cvt_pk_bf16_f32 v80, v36, v37
	s_nop 0
	v_cvt_pk_bf16_f32 v81, v68, v69
	v_lshl_add_u64 v[68:69], v[64:65], 0, s[0:1]
	s_mov_b32 s0, 0x160000
	v_add_co_u32_e32 v64, vcc, s0, v64
	s_mov_b64 s[0:1], 0
	s_nop 0
	v_addc_co_u32_e32 v65, vcc, 0, v65, vcc
	global_store_dwordx2 v[64:65], v[80:81], off
	v_pk_mul_f32 v[64:65], v[34:35], v[164:165]
	v_cvt_pk_bf16_f32 v80, v32, v33
	s_nop 0
	v_cvt_pk_bf16_f32 v81, v64, v65
	global_store_dwordx2 v[68:69], v[80:81], off offset:16
	v_pk_mul_f32 v[64:65], v[6:7], v[136:137]
	v_cvt_pk_bf16_f32 v80, v4, v5
	s_nop 0
	v_cvt_pk_bf16_f32 v81, v64, v65
	global_store_dwordx2 v[68:69], v[80:81], off offset:256
	v_pk_mul_f32 v[64:65], v[2:3], v[128:129]
	v_cvt_pk_bf16_f32 v80, v0, v1
	s_nop 0
	v_cvt_pk_bf16_f32 v81, v64, v65
	s_nop 1
	global_store_dwordx2 v[68:69], v[80:81], off offset:272

.LBB0_363:
	s_setprio 0
	s_waitcnt vmcnt(0)
	s_cmpk_gt_u32 s72, 0xff
	s_cbranch_scc1 .LBB0_365
	s_barrier
